# GEMM loops: snake order of MFMAs so consecutive MFMAs share one operand
# baseline (speedup 1.0000x reference)
; #define PG8_STAGE(bufoff, gbase, voff) do { _Pragma("unroll") for (int _i = 0; _i < 2; ++_i) \
;         __builtin_amdgcn_global_load_lds((const unsigned*)((const char*)(gbase) + (voff)[_i]), (PG8_LAS unsigned*)(lds + (bufoff) + ldsw + _i * 8192), 16, 0, 0); } while (0)
; #define PG8_LDA(dst, b, h) do { _Pragma("unroll") for (int m = 0; m < 4; ++m) _Pragma("unroll") for (int k = 0; k < 2; ++k) dst[m][k] = *(const PG8_LAS bf16x8*)(lds + PG8_SA(b, h) + aoff + m * 2048 + k * 1024); } while (0)
; #define PG8_LDB(dst, b, h) do { _Pragma("unroll") for (int n = 0; n < 2; ++n) _Pragma("unroll") for (int k = 0; k < 2; ++k) dst[n][k] = *(const PG8_LAS bf16x8*)(lds + PG8_SB(b, h) + boff + n * 2048 + k * 1024); } while (0)
; #define PG8_MMA(ai, bj, At, Bt) do { __builtin_amdgcn_s_setprio(1); _Pragma("unroll") for (int m = 0; m < 4; ++m) _Pragma("unroll") for (int n = 0; n < 2; ++n) _Pragma("unroll") for (int k = 0; k < 2; ++k) \
;         acc[ai][bj][m][n] = __builtin_amdgcn_mfma_f32_16x16x32_bf16(Bt[n][k], At[m][k], acc[ai][bj][m][n], 0, 0, 0); __builtin_amdgcn_s_setprio(0); } while (0)
; #define PG8_WAIT_V(n) asm volatile("s_waitcnt vmcnt(" #n ")" ::: "memory")
; #define PG8_WAIT_L(n) asm volatile("s_waitcnt lgkmcnt(" #n ")" ::: "memory")
; #define PG8_BAR __builtin_amdgcn_s_barrier()
; #define PG8_SCHED __builtin_amdgcn_sched_barrier(0)
; template <class Epi, class Sched, bool ALIGN_EPI = false, bool SP2 = false>
; __device__ __forceinline__ void gemm_phase(PG8_LAS unsigned char* lds, const Gemm g, const Sched& S, const Epi& E) {
;     ...
;             PG8_LDB(B0, 0, 0); PG8_LDB(B1, 0, 1); PG8_SCHED; PG8_LDA(At, 0, 0); PG8_STAGE(PG8_SA(1, 1), a1 + hstep, voffA);
;             PG8_WAIT_V(8); PG8_WAIT_L(0); PG8_BAR; PG8_MMA(0, 0, At, B0); PG8_MMA(0, 1, At, B1); PG8_BAR; PG8_SCHED;
;             PG8_LDA(At, 0, 1); PG8_STAGE(PG8_SB(0, 0), b2, voffB); PG8_STAGE(PG8_SB(0, 1), b2 + hstep, voffB); PG8_STAGE(PG8_SA(0, 0), a2, voffA);
;             PG8_WAIT_V(8); PG8_WAIT_L(0); PG8_BAR; PG8_MMA(1, 0, At, B0); PG8_MMA(1, 1, At, B1); PG8_BAR; PG8_SCHED;
.LBB0_175:
	ds_read_b128 v[140:143], v177
	ds_read_b128 v[144:147], v177 offset:1024
	ds_read_b128 v[148:151], v177 offset:2048
	ds_read_b128 v[152:155], v177 offset:3072
	ds_read_b128 v[156:159], v178
	ds_read_b128 v[160:163], v178 offset:1024
	ds_read_b128 v[164:167], v178 offset:2048
	ds_read_b128 v[168:171], v178 offset:3072
	s_add_u32 s60, s58, 0xfffc0080
	s_addc_u32 s61, s59, -1
	s_cmp_eq_u32 s74, 12
	s_cselect_b32 s63, s3, s61
	s_cselect_b32 s62, s41, s60
	s_cselect_b32 s61, s45, s73
	s_cselect_b32 s60, s71, s72
	v_lshl_add_u64 v[172:173], s[58:59], 0, v[136:137]
	s_add_i32 m0, s28, 0xc000
	ds_read_b128 v[182:185], v179
	ds_read_b128 v[186:189], v179 offset:1024
	ds_read_b128 v[190:193], v179 offset:2048
	ds_read_b128 v[194:197], v179 offset:3072
	ds_read_b128 v[202:205], v179 offset:4096
	ds_read_b128 v[206:209], v179 offset:5120
	ds_read_b128 v[210:213], v179 offset:6144
	ds_read_b128 v[214:217], v179 offset:7168
	global_load_lds_dwordx4 v[172:173], off
	v_lshl_add_u64 v[172:173], s[58:59], 0, v[138:139]
	s_add_i32 m0, s28, 0xe000
	s_nop 0
	global_load_lds_dwordx4 v[172:173], off
	s_waitcnt vmcnt(8)
	s_waitcnt lgkmcnt(0)
	s_barrier
	s_setprio 1
	s_waitcnt lgkmcnt(0)
	v_mfma_f32_16x16x32_bf16 v[124:127], v[140:143], v[182:185], v[124:127]
	v_mfma_f32_16x16x32_bf16 v[120:123], v[148:151], v[182:185], v[120:123]
	v_mfma_f32_16x16x32_bf16 v[104:107], v[148:151], v[190:193], v[104:107]
	v_mfma_f32_16x16x32_bf16 v[108:111], v[140:143], v[190:193], v[108:111]
	v_mfma_f32_16x16x32_bf16 v[92:95], v[140:143], v[202:205], v[92:95]
	v_mfma_f32_16x16x32_bf16 v[88:91], v[148:151], v[202:205], v[88:91]
	v_mfma_f32_16x16x32_bf16 v[72:75], v[148:151], v[210:213], v[72:75]
	v_mfma_f32_16x16x32_bf16 v[76:79], v[140:143], v[210:213], v[76:79]
	v_mfma_f32_16x16x32_bf16 v[124:127], v[144:147], v[186:189], v[124:127]
	v_mfma_f32_16x16x32_bf16 v[120:123], v[152:155], v[186:189], v[120:123]
	v_mfma_f32_16x16x32_bf16 v[104:107], v[152:155], v[194:197], v[104:107]
	v_mfma_f32_16x16x32_bf16 v[108:111], v[144:147], v[194:197], v[108:111]
	v_mfma_f32_16x16x32_bf16 v[92:95], v[144:147], v[206:209], v[92:95]
	v_mfma_f32_16x16x32_bf16 v[88:91], v[152:155], v[206:209], v[88:91]
	v_mfma_f32_16x16x32_bf16 v[72:75], v[152:155], v[214:217], v[72:75]
	v_mfma_f32_16x16x32_bf16 v[76:79], v[144:147], v[214:217], v[76:79]
	s_setprio 0
	s_setprio 1
	v_mfma_f32_16x16x32_bf16 v[116:119], v[156:159], v[182:185], v[116:119]
	v_mfma_f32_16x16x32_bf16 v[112:115], v[164:167], v[182:185], v[112:115]
	v_mfma_f32_16x16x32_bf16 v[96:99], v[164:167], v[190:193], v[96:99]
	v_mfma_f32_16x16x32_bf16 v[100:103], v[156:159], v[190:193], v[100:103]
	v_mfma_f32_16x16x32_bf16 v[84:87], v[156:159], v[202:205], v[84:87]
	v_mfma_f32_16x16x32_bf16 v[80:83], v[164:167], v[202:205], v[80:83]
	v_mfma_f32_16x16x32_bf16 v[64:67], v[164:167], v[210:213], v[64:67]
	v_mfma_f32_16x16x32_bf16 v[68:71], v[156:159], v[210:213], v[68:71]
	v_mfma_f32_16x16x32_bf16 v[116:119], v[160:163], v[186:189], v[116:119]
	v_mfma_f32_16x16x32_bf16 v[112:115], v[168:171], v[186:189], v[112:115]
	v_mfma_f32_16x16x32_bf16 v[96:99], v[168:171], v[194:197], v[96:99]
	v_mfma_f32_16x16x32_bf16 v[100:103], v[160:163], v[194:197], v[100:103]
	v_mfma_f32_16x16x32_bf16 v[84:87], v[160:163], v[206:209], v[84:87]
	v_mfma_f32_16x16x32_bf16 v[80:83], v[168:171], v[206:209], v[80:83]
	v_mfma_f32_16x16x32_bf16 v[64:67], v[168:171], v[214:217], v[64:67]
	v_mfma_f32_16x16x32_bf16 v[68:71], v[160:163], v[214:217], v[68:71]
	s_setprio 0
	s_barrier
	s_add_i32 s75, s67, s21
	v_lshl_add_u64 v[172:173], s[60:61], 0, v[132:133]
	s_mov_b32 m0, s75
	ds_read_b128 v[182:185], v179 offset:16384
	ds_read_b128 v[186:189], v179 offset:17408
	ds_read_b128 v[190:193], v179 offset:18432
	ds_read_b128 v[194:197], v179 offset:19456
	ds_read_b128 v[202:205], v179 offset:20480
	ds_read_b128 v[206:209], v179 offset:21504
	ds_read_b128 v[210:213], v179 offset:22528
	ds_read_b128 v[214:217], v179 offset:23552
	global_load_lds_dwordx4 v[172:173], off
	s_add_i32 m0, s75, 0x2000
	s_add_u32 s76, s60, 0x40000
	v_lshl_add_u64 v[198:199], s[60:61], 0, v[128:129]
	s_addc_u32 s77, s61, 0
	s_add_i32 s75, s68, s21
	global_load_lds_dwordx4 v[198:199], off
	v_lshl_add_u64 v[218:219], s[76:77], 0, v[132:133]
	s_mov_b32 m0, s75
	v_lshl_add_u64 v[220:221], s[62:63], 0, v[130:131]
	global_load_lds_dwordx4 v[218:219], off
	v_lshl_add_u64 v[218:219], s[76:77], 0, v[128:129]
	s_add_i32 m0, s75, 0x2000
	s_nop 0
	global_load_lds_dwordx4 v[218:219], off
	v_lshl_add_u64 v[218:219], s[62:63], 0, v[134:135]
	s_mov_b32 m0, s28
	s_nop 0
	global_load_lds_dwordx4 v[218:219], off
	s_mov_b32 m0, s29
	s_nop 0
	global_load_lds_dwordx4 v[220:221], off
	s_waitcnt vmcnt(8)
	s_waitcnt lgkmcnt(0)
	s_barrier
; #define PG8_STAGE(bufoff, gbase, voff) do { _Pragma("unroll") for (int _i = 0; _i < 2; ++_i) \
;         __builtin_amdgcn_global_load_lds((const unsigned*)((const char*)(gbase) + (voff)[_i]), (PG8_LAS unsigned*)(lds + (bufoff) + ldsw + _i * 8192), 16, 0, 0); } while (0)
; #define PG8_LDA(dst, b, h) do { _Pragma("unroll") for (int m = 0; m < 4; ++m) _Pragma("unroll") for (int k = 0; k < 2; ++k) dst[m][k] = *(const PG8_LAS bf16x8*)(lds + PG8_SA(b, h) + aoff + m * 2048 + k * 1024); } while (0)
; #define PG8_LDB(dst, b, h) do { _Pragma("unroll") for (int n = 0; n < 2; ++n) _Pragma("unroll") for (int k = 0; k < 2; ++k) dst[n][k] = *(const PG8_LAS bf16x8*)(lds + PG8_SB(b, h) + boff + n * 2048 + k * 1024); } while (0)
; #define PG8_MMA(ai, bj, At, Bt) do { __builtin_amdgcn_s_setprio(1); _Pragma("unroll") for (int m = 0; m < 4; ++m) _Pragma("unroll") for (int n = 0; n < 2; ++n) _Pragma("unroll") for (int k = 0; k < 2; ++k) \
;         acc[ai][bj][m][n] = __builtin_amdgcn_mfma_f32_16x16x32_bf16(Bt[n][k], At[m][k], acc[ai][bj][m][n], 0, 0, 0); __builtin_amdgcn_s_setprio(0); } while (0)
; #define PG8_WAIT_V(n) asm volatile("s_waitcnt vmcnt(" #n ")" ::: "memory")
; #define PG8_WAIT_L(n) asm volatile("s_waitcnt lgkmcnt(" #n ")" ::: "memory")
; #define PG8_BAR __builtin_amdgcn_s_barrier()
; #define PG8_SCHED __builtin_amdgcn_sched_barrier(0)
; template <class Epi, class Sched, bool ALIGN_EPI = false, bool SP2 = false>
; __device__ __forceinline__ void gemm_phase(PG8_LAS unsigned char* lds, const Gemm g, const Sched& S, const Epi& E) {
;     ...
;             PG8_WAIT_V(8); PG8_WAIT_L(0); PG8_BAR; PG8_MMA(1, 0, At, B0); PG8_MMA(1, 1, At, B1); PG8_BAR; PG8_SCHED;
;             PG8_LDB(B0, 1, 0); PG8_LDB(B1, 1, 1); PG8_SCHED; PG8_LDA(At, 1, 0); PG8_STAGE(PG8_SA(0, 1), a2 + hstep, voffA);
;             PG8_WAIT_V(8); PG8_WAIT_L(0); PG8_BAR; PG8_MMA(0, 0, At, B0); PG8_MMA(0, 1, At, B1); PG8_BAR; PG8_SCHED;
	s_setprio 1
	s_waitcnt lgkmcnt(0)
	v_mfma_f32_16x16x32_bf16 v[60:63], v[140:143], v[182:185], v[60:63]
	v_mfma_f32_16x16x32_bf16 v[56:59], v[148:151], v[182:185], v[56:59]
	v_mfma_f32_16x16x32_bf16 v[40:43], v[148:151], v[190:193], v[40:43]
	v_mfma_f32_16x16x32_bf16 v[44:47], v[140:143], v[190:193], v[44:47]
	v_mfma_f32_16x16x32_bf16 v[28:31], v[140:143], v[202:205], v[28:31]
	v_mfma_f32_16x16x32_bf16 v[24:27], v[148:151], v[202:205], v[24:27]
	v_mfma_f32_16x16x32_bf16 v[8:11], v[148:151], v[210:213], v[8:11]
	v_mfma_f32_16x16x32_bf16 v[12:15], v[140:143], v[210:213], v[12:15]
	v_mfma_f32_16x16x32_bf16 v[60:63], v[144:147], v[186:189], v[60:63]
	v_mfma_f32_16x16x32_bf16 v[56:59], v[152:155], v[186:189], v[56:59]
	v_mfma_f32_16x16x32_bf16 v[40:43], v[152:155], v[194:197], v[40:43]
	v_mfma_f32_16x16x32_bf16 v[44:47], v[144:147], v[194:197], v[44:47]
	v_mfma_f32_16x16x32_bf16 v[28:31], v[144:147], v[206:209], v[28:31]
	v_mfma_f32_16x16x32_bf16 v[24:27], v[152:155], v[206:209], v[24:27]
	v_mfma_f32_16x16x32_bf16 v[8:11], v[152:155], v[214:217], v[8:11]
	v_mfma_f32_16x16x32_bf16 v[12:15], v[144:147], v[214:217], v[12:15]
	s_setprio 0
	s_setprio 1
	v_mfma_f32_16x16x32_bf16 v[52:55], v[156:159], v[182:185], v[52:55]
	v_mfma_f32_16x16x32_bf16 v[48:51], v[164:167], v[182:185], v[48:51]
	v_mfma_f32_16x16x32_bf16 v[32:35], v[164:167], v[190:193], v[32:35]
	v_mfma_f32_16x16x32_bf16 v[36:39], v[156:159], v[190:193], v[36:39]
	v_mfma_f32_16x16x32_bf16 v[20:23], v[156:159], v[202:205], v[20:23]
	v_mfma_f32_16x16x32_bf16 v[16:19], v[164:167], v[202:205], v[16:19]
	v_mfma_f32_16x16x32_bf16 v[0:3], v[164:167], v[210:213], v[0:3]
	v_mfma_f32_16x16x32_bf16 v[4:7], v[156:159], v[210:213], v[4:7]
	v_mfma_f32_16x16x32_bf16 v[52:55], v[160:163], v[186:189], v[52:55]
	v_mfma_f32_16x16x32_bf16 v[48:51], v[168:171], v[186:189], v[48:51]
	v_mfma_f32_16x16x32_bf16 v[32:35], v[168:171], v[194:197], v[32:35]
	v_mfma_f32_16x16x32_bf16 v[36:39], v[160:163], v[194:197], v[36:39]
	v_mfma_f32_16x16x32_bf16 v[20:23], v[160:163], v[206:209], v[20:23]
	v_mfma_f32_16x16x32_bf16 v[16:19], v[168:171], v[206:209], v[16:19]
	v_mfma_f32_16x16x32_bf16 v[0:3], v[168:171], v[214:217], v[0:3]
	v_mfma_f32_16x16x32_bf16 v[4:7], v[160:163], v[214:217], v[4:7]
	s_setprio 0
	s_barrier
	s_add_i32 s75, 0, 0x18000
	s_add_i32 s76, 0, 0x1c000
	v_add_u32_e32 v152, s75, v175
	v_add_u32_e32 v168, s76, v175
	ds_read_b128 v[140:143], v152
	ds_read_b128 v[144:147], v152 offset:1024
	ds_read_b128 v[148:151], v152 offset:2048
	ds_read_b128 v[152:155], v152 offset:3072
	ds_read_b128 v[156:159], v168
	ds_read_b128 v[160:163], v168 offset:1024
	ds_read_b128 v[164:167], v168 offset:2048
	ds_read_b128 v[168:171], v168 offset:3072
	s_add_u32 s62, s62, 0x40000
	s_addc_u32 s63, s63, 0
	s_mov_b32 m0, s30
	v_lshl_add_u64 v[222:223], s[62:63], 0, v[134:135]
	ds_read_b128 v[182:185], v179 offset:32768
	ds_read_b128 v[186:189], v179 offset:33792
	ds_read_b128 v[190:193], v179 offset:34816
	ds_read_b128 v[194:197], v179 offset:35840
	ds_read_b128 v[202:205], v179 offset:36864
	ds_read_b128 v[206:209], v179 offset:37888
	ds_read_b128 v[210:213], v179 offset:38912
	ds_read_b128 v[214:217], v179 offset:39936
	global_load_lds_dwordx4 v[222:223], off
	v_lshl_add_u64 v[222:223], s[62:63], 0, v[130:131]
	s_mov_b32 m0, s31
	s_nop 0
	global_load_lds_dwordx4 v[222:223], off
	s_waitcnt vmcnt(8)
	s_waitcnt lgkmcnt(0)
	s_barrier
	s_setprio 1
	s_waitcnt lgkmcnt(0)
	v_mfma_f32_16x16x32_bf16 v[124:127], v[140:143], v[182:185], v[124:127]
	v_mfma_f32_16x16x32_bf16 v[120:123], v[148:151], v[182:185], v[120:123]
	v_mfma_f32_16x16x32_bf16 v[104:107], v[148:151], v[190:193], v[104:107]
	v_mfma_f32_16x16x32_bf16 v[108:111], v[140:143], v[190:193], v[108:111]
	v_mfma_f32_16x16x32_bf16 v[92:95], v[140:143], v[202:205], v[92:95]
	v_mfma_f32_16x16x32_bf16 v[88:91], v[148:151], v[202:205], v[88:91]
	v_mfma_f32_16x16x32_bf16 v[72:75], v[148:151], v[210:213], v[72:75]
	v_mfma_f32_16x16x32_bf16 v[76:79], v[140:143], v[210:213], v[76:79]
	v_mfma_f32_16x16x32_bf16 v[124:127], v[144:147], v[186:189], v[124:127]
	v_mfma_f32_16x16x32_bf16 v[120:123], v[152:155], v[186:189], v[120:123]
	v_mfma_f32_16x16x32_bf16 v[104:107], v[152:155], v[194:197], v[104:107]
	v_mfma_f32_16x16x32_bf16 v[108:111], v[144:147], v[194:197], v[108:111]
	v_mfma_f32_16x16x32_bf16 v[92:95], v[144:147], v[206:209], v[92:95]
	v_mfma_f32_16x16x32_bf16 v[88:91], v[152:155], v[206:209], v[88:91]
	v_mfma_f32_16x16x32_bf16 v[72:75], v[152:155], v[214:217], v[72:75]
	v_mfma_f32_16x16x32_bf16 v[76:79], v[144:147], v[214:217], v[76:79]
	s_setprio 0
	s_setprio 1
	v_mfma_f32_16x16x32_bf16 v[116:119], v[156:159], v[182:185], v[116:119]
	v_mfma_f32_16x16x32_bf16 v[112:115], v[164:167], v[182:185], v[112:115]
	v_mfma_f32_16x16x32_bf16 v[96:99], v[164:167], v[190:193], v[96:99]
	v_mfma_f32_16x16x32_bf16 v[100:103], v[156:159], v[190:193], v[100:103]
	v_mfma_f32_16x16x32_bf16 v[84:87], v[156:159], v[202:205], v[84:87]
	v_mfma_f32_16x16x32_bf16 v[80:83], v[164:167], v[202:205], v[80:83]
	v_mfma_f32_16x16x32_bf16 v[64:67], v[164:167], v[210:213], v[64:67]
	v_mfma_f32_16x16x32_bf16 v[68:71], v[156:159], v[210:213], v[68:71]
	v_mfma_f32_16x16x32_bf16 v[116:119], v[160:163], v[186:189], v[116:119]
	v_mfma_f32_16x16x32_bf16 v[112:115], v[168:171], v[186:189], v[112:115]
	v_mfma_f32_16x16x32_bf16 v[96:99], v[168:171], v[194:197], v[96:99]
	v_mfma_f32_16x16x32_bf16 v[100:103], v[160:163], v[194:197], v[100:103]
	v_mfma_f32_16x16x32_bf16 v[84:87], v[160:163], v[206:209], v[84:87]
	v_mfma_f32_16x16x32_bf16 v[80:83], v[168:171], v[206:209], v[80:83]
	v_mfma_f32_16x16x32_bf16 v[64:67], v[168:171], v[214:217], v[64:67]
	v_mfma_f32_16x16x32_bf16 v[68:71], v[160:163], v[214:217], v[68:71]
	s_setprio 0
	s_barrier
; #define PG8_STAGE(bufoff, gbase, voff) do { _Pragma("unroll") for (int _i = 0; _i < 2; ++_i) \
;         __builtin_amdgcn_global_load_lds((const unsigned*)((const char*)(gbase) + (voff)[_i]), (PG8_LAS unsigned*)(lds + (bufoff) + ldsw + _i * 8192), 16, 0, 0); } while (0)
; #define PG8_LDA(dst, b, h) do { _Pragma("unroll") for (int m = 0; m < 4; ++m) _Pragma("unroll") for (int k = 0; k < 2; ++k) dst[m][k] = *(const PG8_LAS bf16x8*)(lds + PG8_SA(b, h) + aoff + m * 2048 + k * 1024); } while (0)
; #define PG8_MMA(ai, bj, At, Bt) do { __builtin_amdgcn_s_setprio(1); _Pragma("unroll") for (int m = 0; m < 4; ++m) _Pragma("unroll") for (int n = 0; n < 2; ++n) _Pragma("unroll") for (int k = 0; k < 2; ++k) \
;         acc[ai][bj][m][n] = __builtin_amdgcn_mfma_f32_16x16x32_bf16(Bt[n][k], At[m][k], acc[ai][bj][m][n], 0, 0, 0); __builtin_amdgcn_s_setprio(0); } while (0)
; #define PG8_WAIT_V(n) asm volatile("s_waitcnt vmcnt(" #n ")" ::: "memory")
; #define PG8_WAIT_L(n) asm volatile("s_waitcnt lgkmcnt(" #n ")" ::: "memory")
; #define PG8_BAR __builtin_amdgcn_s_barrier()
; #define PG8_SCHED __builtin_amdgcn_sched_barrier(0)
; template <class Epi, class Sched, bool ALIGN_EPI = false, bool SP2 = false>
; __device__ __forceinline__ void gemm_phase(PG8_LAS unsigned char* lds, const Gemm g, const Sched& S, const Epi& E) {
;     ...
;         for (int t = 0; t < nt; t += 2) {
;     ...
;             PG8_LDA(At, 1, 1); PG8_STAGE(PG8_SB(1, 0), b3, voffB); PG8_STAGE(PG8_SB(1, 1), b3 + hstep, voffB); PG8_STAGE(PG8_SA(1, 0), a3, voffA);
;             PG8_WAIT_V(8); PG8_WAIT_L(0); PG8_BAR; PG8_MMA(1, 0, At, B0); PG8_MMA(1, 1, At, B1); PG8_BAR; PG8_SCHED;
	s_add_i32 s62, s75, s21
	v_lshl_add_u64 v[172:173], v[172:173], 0, s[36:37]
	s_mov_b32 m0, s62
	ds_read_b128 v[182:185], v179 offset:49152
	ds_read_b128 v[186:189], v179 offset:50176
	ds_read_b128 v[190:193], v179 offset:51200
	ds_read_b128 v[194:197], v179 offset:52224
	ds_read_b128 v[202:205], v179 offset:53248
	ds_read_b128 v[206:209], v179 offset:54272
	ds_read_b128 v[210:213], v179 offset:55296
	ds_read_b128 v[214:217], v179 offset:56320
	global_load_lds_dwordx4 v[172:173], off
	s_add_i32 m0, s62, 0x2000
	s_add_u32 s60, s60, 0x40080
	v_lshl_add_u64 v[172:173], v[198:199], 0, s[36:37]
	s_addc_u32 s61, s61, 0
	s_add_i32 s62, s76, s21
	global_load_lds_dwordx4 v[172:173], off
	v_lshl_add_u64 v[172:173], s[60:61], 0, v[132:133]
	s_mov_b32 m0, s62
	s_nop 0
	global_load_lds_dwordx4 v[172:173], off
	v_lshl_add_u64 v[172:173], s[60:61], 0, v[128:129]
	s_add_i32 m0, s62, 0x2000
	s_nop 0
	global_load_lds_dwordx4 v[172:173], off
	v_lshl_add_u64 v[172:173], v[218:219], 0, s[36:37]
	s_mov_b32 m0, s65
	s_nop 0
	global_load_lds_dwordx4 v[172:173], off
	v_lshl_add_u64 v[172:173], v[220:221], 0, s[36:37]
	s_mov_b32 m0, s66
	s_nop 0
	global_load_lds_dwordx4 v[172:173], off
	s_waitcnt vmcnt(8)
	s_waitcnt lgkmcnt(0)
	s_barrier
	s_setprio 1
	s_waitcnt lgkmcnt(0)
	v_mfma_f32_16x16x32_bf16 v[60:63], v[140:143], v[182:185], v[60:63]
	v_mfma_f32_16x16x32_bf16 v[56:59], v[148:151], v[182:185], v[56:59]
	v_mfma_f32_16x16x32_bf16 v[40:43], v[148:151], v[190:193], v[40:43]
	v_mfma_f32_16x16x32_bf16 v[44:47], v[140:143], v[190:193], v[44:47]
	v_mfma_f32_16x16x32_bf16 v[28:31], v[140:143], v[202:205], v[28:31]
	v_mfma_f32_16x16x32_bf16 v[24:27], v[148:151], v[202:205], v[24:27]
	v_mfma_f32_16x16x32_bf16 v[8:11], v[148:151], v[210:213], v[8:11]
	v_mfma_f32_16x16x32_bf16 v[12:15], v[140:143], v[210:213], v[12:15]
	v_mfma_f32_16x16x32_bf16 v[60:63], v[144:147], v[186:189], v[60:63]
	v_mfma_f32_16x16x32_bf16 v[56:59], v[152:155], v[186:189], v[56:59]
	v_mfma_f32_16x16x32_bf16 v[40:43], v[152:155], v[194:197], v[40:43]
	v_mfma_f32_16x16x32_bf16 v[44:47], v[144:147], v[194:197], v[44:47]
	v_mfma_f32_16x16x32_bf16 v[28:31], v[144:147], v[206:209], v[28:31]
	v_mfma_f32_16x16x32_bf16 v[24:27], v[152:155], v[206:209], v[24:27]
	v_mfma_f32_16x16x32_bf16 v[8:11], v[152:155], v[214:217], v[8:11]
	v_mfma_f32_16x16x32_bf16 v[12:15], v[144:147], v[214:217], v[12:15]
	s_setprio 0
	s_setprio 1
	v_mfma_f32_16x16x32_bf16 v[52:55], v[156:159], v[182:185], v[52:55]
	v_mfma_f32_16x16x32_bf16 v[48:51], v[164:167], v[182:185], v[48:51]
	v_mfma_f32_16x16x32_bf16 v[32:35], v[164:167], v[190:193], v[32:35]
	v_mfma_f32_16x16x32_bf16 v[36:39], v[156:159], v[190:193], v[36:39]
	v_mfma_f32_16x16x32_bf16 v[20:23], v[156:159], v[202:205], v[20:23]
	v_mfma_f32_16x16x32_bf16 v[16:19], v[164:167], v[202:205], v[16:19]
	v_mfma_f32_16x16x32_bf16 v[0:3], v[164:167], v[210:213], v[0:3]
	v_mfma_f32_16x16x32_bf16 v[4:7], v[156:159], v[210:213], v[4:7]
	v_mfma_f32_16x16x32_bf16 v[52:55], v[160:163], v[186:189], v[52:55]
	v_mfma_f32_16x16x32_bf16 v[48:51], v[168:171], v[186:189], v[48:51]
	v_mfma_f32_16x16x32_bf16 v[32:35], v[168:171], v[194:197], v[32:35]
	v_mfma_f32_16x16x32_bf16 v[36:39], v[160:163], v[194:197], v[36:39]
	v_mfma_f32_16x16x32_bf16 v[20:23], v[160:163], v[206:209], v[20:23]
	v_mfma_f32_16x16x32_bf16 v[16:19], v[168:171], v[206:209], v[16:19]
	v_mfma_f32_16x16x32_bf16 v[0:3], v[168:171], v[214:217], v[0:3]
	v_mfma_f32_16x16x32_bf16 v[4:7], v[160:163], v[214:217], v[4:7]
	s_setprio 0
	s_barrier
	s_add_i32 s74, s74, 2
	s_add_u32 s58, s58, 0x100
	s_addc_u32 s59, s59, 0
	s_add_u32 s72, s72, 0x100
	s_addc_u32 s73, s73, 0
	s_cmp_gt_u32 s74, 13
	s_cbranch_scc0 .LBB0_175
	s_and_b64 vcc, exec, s[38:39]
	s_cbranch_vccz .LBB0_178
	s_barrier

; #define PG8_STAGE(bufoff, gbase, voff) do { _Pragma("unroll") for (int _i = 0; _i < 2; ++_i) \
;         __builtin_amdgcn_global_load_lds((const unsigned*)((const char*)(gbase) + (voff)[_i]), (PG8_LAS unsigned*)(lds + (bufoff) + ldsw + _i * 8192), 16, 0, 0); } while (0)
; #define PG8_LDA(dst, b, h) do { _Pragma("unroll") for (int m = 0; m < 4; ++m) _Pragma("unroll") for (int k = 0; k < 2; ++k) dst[m][k] = *(const PG8_LAS bf16x8*)(lds + PG8_SA(b, h) + aoff + m * 2048 + k * 1024); } while (0)
; #define PG8_LDB(dst, b, h) do { _Pragma("unroll") for (int n = 0; n < 2; ++n) _Pragma("unroll") for (int k = 0; k < 2; ++k) dst[n][k] = *(const PG8_LAS bf16x8*)(lds + PG8_SB(b, h) + boff + n * 2048 + k * 1024); } while (0)
; #define PG8_MMA(ai, bj, At, Bt) do { __builtin_amdgcn_s_setprio(1); _Pragma("unroll") for (int m = 0; m < 4; ++m) _Pragma("unroll") for (int n = 0; n < 2; ++n) _Pragma("unroll") for (int k = 0; k < 2; ++k) \
;         acc[ai][bj][m][n] = __builtin_amdgcn_mfma_f32_16x16x32_bf16(Bt[n][k], At[m][k], acc[ai][bj][m][n], 0, 0, 0); __builtin_amdgcn_s_setprio(0); } while (0)
; #define PG8_WAIT_V(n) asm volatile("s_waitcnt vmcnt(" #n ")" ::: "memory")
; #define PG8_WAIT_L(n) asm volatile("s_waitcnt lgkmcnt(" #n ")" ::: "memory")
; #define PG8_BAR __builtin_amdgcn_s_barrier()
; #define PG8_SCHED __builtin_amdgcn_sched_barrier(0)
; template <class Epi, class Sched, bool ALIGN_EPI = false, bool SP2 = false>
; __device__ __forceinline__ void gemm_phase(PG8_LAS unsigned char* lds, const Gemm g, const Sched& S, const Epi& E) {
;     ...
;             PG8_LDB(B0, 0, 0); PG8_LDB(B1, 0, 1); PG8_SCHED; PG8_LDA(At, 0, 0); PG8_STAGE(PG8_SA(1, 1), a1 + hstep, voffA);
;             PG8_WAIT_V(8); PG8_WAIT_L(0); PG8_BAR; PG8_MMA(0, 0, At, B0); PG8_MMA(0, 1, At, B1); PG8_BAR; PG8_SCHED;
;             PG8_LDA(At, 0, 1); PG8_STAGE(PG8_SB(0, 0), b2, voffB); PG8_STAGE(PG8_SB(0, 1), b2 + hstep, voffB); PG8_STAGE(PG8_SA(0, 0), a2, voffA);
;             PG8_WAIT_V(8); PG8_WAIT_L(0); PG8_BAR; PG8_MMA(1, 0, At, B0); PG8_MMA(1, 1, At, B1); PG8_BAR; PG8_SCHED;
.LBB0_245:
	ds_read_b128 v[128:131], v156
	ds_read_b128 v[132:135], v156 offset:1024
	ds_read_b128 v[148:151], v156 offset:2048
	ds_read_b128 v[162:165], v156 offset:3072
	ds_read_b128 v[166:169], v157
	ds_read_b128 v[170:173], v157 offset:1024
	ds_read_b128 v[174:177], v157 offset:2048
	ds_read_b128 v[178:181], v157 offset:3072
	s_add_u32 s58, s56, 0xfff50080
	s_addc_u32 s59, s57, -1
	s_cmp_eq_u32 s85, 40
	s_cselect_b32 s61, s47, s59
	s_cselect_b32 s60, s46, s58
	s_cselect_b32 s59, s51, s84
	s_cselect_b32 s58, s50, s83
	s_mov_b32 m0, s71
	v_lshl_add_u64 v[152:153], s[56:57], 0, v[144:145]
	ds_read_b128 v[182:185], v158
	ds_read_b128 v[186:189], v158 offset:1024
	ds_read_b128 v[190:193], v158 offset:2048
	ds_read_b128 v[194:197], v158 offset:3072
	ds_read_b128 v[202:205], v158 offset:4096
	ds_read_b128 v[206:209], v158 offset:5120
	ds_read_b128 v[210:213], v158 offset:6144
	ds_read_b128 v[214:217], v158 offset:7168
	global_load_lds_dwordx4 v[152:153], off
	v_lshl_add_u64 v[152:153], s[56:57], 0, v[146:147]
	s_mov_b32 m0, s72
	s_nop 0
	global_load_lds_dwordx4 v[152:153], off
	s_waitcnt vmcnt(8)
	s_waitcnt lgkmcnt(0)
	s_barrier
	s_setprio 1
	s_waitcnt lgkmcnt(0)
	v_mfma_f32_16x16x32_bf16 v[124:127], v[128:131], v[182:185], v[124:127]
	v_mfma_f32_16x16x32_bf16 v[120:123], v[148:151], v[182:185], v[120:123]
	v_mfma_f32_16x16x32_bf16 v[104:107], v[148:151], v[190:193], v[104:107]
	v_mfma_f32_16x16x32_bf16 v[108:111], v[128:131], v[190:193], v[108:111]
	v_mfma_f32_16x16x32_bf16 v[92:95], v[128:131], v[202:205], v[92:95]
	v_mfma_f32_16x16x32_bf16 v[88:91], v[148:151], v[202:205], v[88:91]
	v_mfma_f32_16x16x32_bf16 v[72:75], v[148:151], v[210:213], v[72:75]
	v_mfma_f32_16x16x32_bf16 v[76:79], v[128:131], v[210:213], v[76:79]
	v_mfma_f32_16x16x32_bf16 v[124:127], v[132:135], v[186:189], v[124:127]
	v_mfma_f32_16x16x32_bf16 v[120:123], v[162:165], v[186:189], v[120:123]
	v_mfma_f32_16x16x32_bf16 v[104:107], v[162:165], v[194:197], v[104:107]
	v_mfma_f32_16x16x32_bf16 v[108:111], v[132:135], v[194:197], v[108:111]
	v_mfma_f32_16x16x32_bf16 v[92:95], v[132:135], v[206:209], v[92:95]
	v_mfma_f32_16x16x32_bf16 v[88:91], v[162:165], v[206:209], v[88:91]
	v_mfma_f32_16x16x32_bf16 v[72:75], v[162:165], v[214:217], v[72:75]
	v_mfma_f32_16x16x32_bf16 v[76:79], v[132:135], v[214:217], v[76:79]
	s_setprio 0
	s_setprio 1
	v_mfma_f32_16x16x32_bf16 v[116:119], v[166:169], v[182:185], v[116:119]
	v_mfma_f32_16x16x32_bf16 v[112:115], v[174:177], v[182:185], v[112:115]
	v_mfma_f32_16x16x32_bf16 v[96:99], v[174:177], v[190:193], v[96:99]
	v_mfma_f32_16x16x32_bf16 v[100:103], v[166:169], v[190:193], v[100:103]
	v_mfma_f32_16x16x32_bf16 v[84:87], v[166:169], v[202:205], v[84:87]
	v_mfma_f32_16x16x32_bf16 v[80:83], v[174:177], v[202:205], v[80:83]
	v_mfma_f32_16x16x32_bf16 v[64:67], v[174:177], v[210:213], v[64:67]
	v_mfma_f32_16x16x32_bf16 v[68:71], v[166:169], v[210:213], v[68:71]
	v_mfma_f32_16x16x32_bf16 v[116:119], v[170:173], v[186:189], v[116:119]
	v_mfma_f32_16x16x32_bf16 v[112:115], v[178:181], v[186:189], v[112:115]
	v_mfma_f32_16x16x32_bf16 v[96:99], v[178:181], v[194:197], v[96:99]
	v_mfma_f32_16x16x32_bf16 v[100:103], v[170:173], v[194:197], v[100:103]
	v_mfma_f32_16x16x32_bf16 v[84:87], v[170:173], v[206:209], v[84:87]
	v_mfma_f32_16x16x32_bf16 v[80:83], v[178:181], v[206:209], v[80:83]
	v_mfma_f32_16x16x32_bf16 v[64:67], v[178:181], v[214:217], v[64:67]
	v_mfma_f32_16x16x32_bf16 v[68:71], v[170:173], v[214:217], v[68:71]
	s_setprio 0
	s_barrier
	s_mov_b32 m0, s73
	v_lshl_add_u64 v[152:153], s[58:59], 0, v[138:139]
	s_add_u32 s86, s58, 0xb0000
	ds_read_b128 v[182:185], v158 offset:16384
	ds_read_b128 v[186:189], v158 offset:17408
	ds_read_b128 v[190:193], v158 offset:18432
	ds_read_b128 v[194:197], v158 offset:19456
	ds_read_b128 v[202:205], v158 offset:20480
	ds_read_b128 v[206:209], v158 offset:21504
	ds_read_b128 v[210:213], v158 offset:22528
	ds_read_b128 v[214:217], v158 offset:23552
	global_load_lds_dwordx4 v[152:153], off
	v_lshl_add_u64 v[198:199], s[58:59], 0, v[142:143]
	s_mov_b32 m0, s74
	s_addc_u32 s87, s59, 0
	global_load_lds_dwordx4 v[198:199], off
	v_lshl_add_u64 v[218:219], s[86:87], 0, v[138:139]
	s_mov_b32 m0, s75
	v_lshl_add_u64 v[220:221], s[60:61], 0, v[140:141]
	global_load_lds_dwordx4 v[218:219], off
	v_lshl_add_u64 v[218:219], s[86:87], 0, v[142:143]
	s_mov_b32 m0, s76
	s_nop 0
	global_load_lds_dwordx4 v[218:219], off
	v_lshl_add_u64 v[218:219], s[60:61], 0, v[136:137]
	s_mov_b32 m0, s28
	s_nop 0
	global_load_lds_dwordx4 v[218:219], off
	s_mov_b32 m0, s29
	s_nop 0
	global_load_lds_dwordx4 v[220:221], off
	s_waitcnt vmcnt(8)
	s_waitcnt lgkmcnt(0)
	s_barrier
; #define PG8_STAGE(bufoff, gbase, voff) do { _Pragma("unroll") for (int _i = 0; _i < 2; ++_i) \
;         __builtin_amdgcn_global_load_lds((const unsigned*)((const char*)(gbase) + (voff)[_i]), (PG8_LAS unsigned*)(lds + (bufoff) + ldsw + _i * 8192), 16, 0, 0); } while (0)
; #define PG8_LDA(dst, b, h) do { _Pragma("unroll") for (int m = 0; m < 4; ++m) _Pragma("unroll") for (int k = 0; k < 2; ++k) dst[m][k] = *(const PG8_LAS bf16x8*)(lds + PG8_SA(b, h) + aoff + m * 2048 + k * 1024); } while (0)
; #define PG8_LDB(dst, b, h) do { _Pragma("unroll") for (int n = 0; n < 2; ++n) _Pragma("unroll") for (int k = 0; k < 2; ++k) dst[n][k] = *(const PG8_LAS bf16x8*)(lds + PG8_SB(b, h) + boff + n * 2048 + k * 1024); } while (0)
; #define PG8_MMA(ai, bj, At, Bt) do { __builtin_amdgcn_s_setprio(1); _Pragma("unroll") for (int m = 0; m < 4; ++m) _Pragma("unroll") for (int n = 0; n < 2; ++n) _Pragma("unroll") for (int k = 0; k < 2; ++k) \
;         acc[ai][bj][m][n] = __builtin_amdgcn_mfma_f32_16x16x32_bf16(Bt[n][k], At[m][k], acc[ai][bj][m][n], 0, 0, 0); __builtin_amdgcn_s_setprio(0); } while (0)
; #define PG8_WAIT_V(n) asm volatile("s_waitcnt vmcnt(" #n ")" ::: "memory")
; #define PG8_WAIT_L(n) asm volatile("s_waitcnt lgkmcnt(" #n ")" ::: "memory")
; #define PG8_BAR __builtin_amdgcn_s_barrier()
; #define PG8_SCHED __builtin_amdgcn_sched_barrier(0)
; template <class Epi, class Sched, bool ALIGN_EPI = false, bool SP2 = false>
; __device__ __forceinline__ void gemm_phase(PG8_LAS unsigned char* lds, const Gemm g, const Sched& S, const Epi& E) {
;     ...
;             PG8_WAIT_V(8); PG8_WAIT_L(0); PG8_BAR; PG8_MMA(1, 0, At, B0); PG8_MMA(1, 1, At, B1); PG8_BAR; PG8_SCHED;
;             PG8_LDB(B0, 1, 0); PG8_LDB(B1, 1, 1); PG8_SCHED; PG8_LDA(At, 1, 0); PG8_STAGE(PG8_SA(0, 1), a2 + hstep, voffA);
;             PG8_WAIT_V(8); PG8_WAIT_L(0); PG8_BAR; PG8_MMA(0, 0, At, B0); PG8_MMA(0, 1, At, B1); PG8_BAR; PG8_SCHED;
	s_setprio 1
	s_waitcnt lgkmcnt(0)
	v_mfma_f32_16x16x32_bf16 v[60:63], v[128:131], v[182:185], v[60:63]
	v_mfma_f32_16x16x32_bf16 v[56:59], v[148:151], v[182:185], v[56:59]
	v_mfma_f32_16x16x32_bf16 v[40:43], v[148:151], v[190:193], v[40:43]
	v_mfma_f32_16x16x32_bf16 v[44:47], v[128:131], v[190:193], v[44:47]
	v_mfma_f32_16x16x32_bf16 v[32:35], v[128:131], v[202:205], v[32:35]
	v_mfma_f32_16x16x32_bf16 v[24:27], v[148:151], v[202:205], v[24:27]
	v_mfma_f32_16x16x32_bf16 v[8:11], v[148:151], v[210:213], v[8:11]
	v_mfma_f32_16x16x32_bf16 v[16:19], v[128:131], v[210:213], v[16:19]
	v_mfma_f32_16x16x32_bf16 v[60:63], v[132:135], v[186:189], v[60:63]
	v_mfma_f32_16x16x32_bf16 v[56:59], v[162:165], v[186:189], v[56:59]
	v_mfma_f32_16x16x32_bf16 v[40:43], v[162:165], v[194:197], v[40:43]
	v_mfma_f32_16x16x32_bf16 v[44:47], v[132:135], v[194:197], v[44:47]
	v_mfma_f32_16x16x32_bf16 v[32:35], v[132:135], v[206:209], v[32:35]
	v_mfma_f32_16x16x32_bf16 v[24:27], v[162:165], v[206:209], v[24:27]
	v_mfma_f32_16x16x32_bf16 v[8:11], v[162:165], v[214:217], v[8:11]
	v_mfma_f32_16x16x32_bf16 v[16:19], v[132:135], v[214:217], v[16:19]
	s_setprio 0
	s_setprio 1
	v_mfma_f32_16x16x32_bf16 v[52:55], v[166:169], v[182:185], v[52:55]
	v_mfma_f32_16x16x32_bf16 v[48:51], v[174:177], v[182:185], v[48:51]
	v_mfma_f32_16x16x32_bf16 v[28:31], v[174:177], v[190:193], v[28:31]
	v_mfma_f32_16x16x32_bf16 v[36:39], v[166:169], v[190:193], v[36:39]
	v_mfma_f32_16x16x32_bf16 v[20:23], v[166:169], v[202:205], v[20:23]
	v_mfma_f32_16x16x32_bf16 v[12:15], v[174:177], v[202:205], v[12:15]
	v_mfma_f32_16x16x32_bf16 v[0:3], v[174:177], v[210:213], v[0:3]
	v_mfma_f32_16x16x32_bf16 v[4:7], v[166:169], v[210:213], v[4:7]
	v_mfma_f32_16x16x32_bf16 v[52:55], v[170:173], v[186:189], v[52:55]
	v_mfma_f32_16x16x32_bf16 v[48:51], v[178:181], v[186:189], v[48:51]
	v_mfma_f32_16x16x32_bf16 v[28:31], v[178:181], v[194:197], v[28:31]
	v_mfma_f32_16x16x32_bf16 v[36:39], v[170:173], v[194:197], v[36:39]
	v_mfma_f32_16x16x32_bf16 v[20:23], v[170:173], v[206:209], v[20:23]
	v_mfma_f32_16x16x32_bf16 v[12:15], v[178:181], v[206:209], v[12:15]
	v_mfma_f32_16x16x32_bf16 v[0:3], v[178:181], v[214:217], v[0:3]
	v_mfma_f32_16x16x32_bf16 v[4:7], v[170:173], v[214:217], v[4:7]
	s_setprio 0
	s_barrier
	ds_read_b128 v[128:131], v160
	ds_read_b128 v[132:135], v160 offset:1024
	ds_read_b128 v[148:151], v160 offset:2048
	ds_read_b128 v[162:165], v160 offset:3072
	ds_read_b128 v[166:169], v161
	ds_read_b128 v[170:173], v161 offset:1024
	ds_read_b128 v[174:177], v161 offset:2048
	ds_read_b128 v[178:181], v161 offset:3072
	s_add_u32 s60, s60, 0xb0000
	s_addc_u32 s61, s61, 0
	s_mov_b32 m0, s30
	v_lshl_add_u64 v[222:223], s[60:61], 0, v[136:137]
	ds_read_b128 v[182:185], v158 offset:32768
	ds_read_b128 v[186:189], v158 offset:33792
	ds_read_b128 v[190:193], v158 offset:34816
	ds_read_b128 v[194:197], v158 offset:35840
	ds_read_b128 v[202:205], v158 offset:36864
	ds_read_b128 v[206:209], v158 offset:37888
	ds_read_b128 v[210:213], v158 offset:38912
	ds_read_b128 v[214:217], v158 offset:39936
	global_load_lds_dwordx4 v[222:223], off
	v_lshl_add_u64 v[222:223], s[60:61], 0, v[140:141]
	s_mov_b32 m0, s31
	s_nop 0
	global_load_lds_dwordx4 v[222:223], off
	s_waitcnt vmcnt(8)
	s_waitcnt lgkmcnt(0)
	s_barrier
	s_setprio 1
	s_waitcnt lgkmcnt(0)
	v_mfma_f32_16x16x32_bf16 v[124:127], v[128:131], v[182:185], v[124:127]
	v_mfma_f32_16x16x32_bf16 v[120:123], v[148:151], v[182:185], v[120:123]
	v_mfma_f32_16x16x32_bf16 v[104:107], v[148:151], v[190:193], v[104:107]
	v_mfma_f32_16x16x32_bf16 v[108:111], v[128:131], v[190:193], v[108:111]
	v_mfma_f32_16x16x32_bf16 v[92:95], v[128:131], v[202:205], v[92:95]
	v_mfma_f32_16x16x32_bf16 v[88:91], v[148:151], v[202:205], v[88:91]
	v_mfma_f32_16x16x32_bf16 v[72:75], v[148:151], v[210:213], v[72:75]
	v_mfma_f32_16x16x32_bf16 v[76:79], v[128:131], v[210:213], v[76:79]
	v_mfma_f32_16x16x32_bf16 v[124:127], v[132:135], v[186:189], v[124:127]
	v_mfma_f32_16x16x32_bf16 v[120:123], v[162:165], v[186:189], v[120:123]
	v_mfma_f32_16x16x32_bf16 v[104:107], v[162:165], v[194:197], v[104:107]
	v_mfma_f32_16x16x32_bf16 v[108:111], v[132:135], v[194:197], v[108:111]
	v_mfma_f32_16x16x32_bf16 v[92:95], v[132:135], v[206:209], v[92:95]
	v_mfma_f32_16x16x32_bf16 v[88:91], v[162:165], v[206:209], v[88:91]
	v_mfma_f32_16x16x32_bf16 v[72:75], v[162:165], v[214:217], v[72:75]
	v_mfma_f32_16x16x32_bf16 v[76:79], v[132:135], v[214:217], v[76:79]
	s_setprio 0
	s_setprio 1
	v_mfma_f32_16x16x32_bf16 v[116:119], v[166:169], v[182:185], v[116:119]
	v_mfma_f32_16x16x32_bf16 v[112:115], v[174:177], v[182:185], v[112:115]
	v_mfma_f32_16x16x32_bf16 v[96:99], v[174:177], v[190:193], v[96:99]
	v_mfma_f32_16x16x32_bf16 v[100:103], v[166:169], v[190:193], v[100:103]
	v_mfma_f32_16x16x32_bf16 v[84:87], v[166:169], v[202:205], v[84:87]
	v_mfma_f32_16x16x32_bf16 v[80:83], v[174:177], v[202:205], v[80:83]
	v_mfma_f32_16x16x32_bf16 v[64:67], v[174:177], v[210:213], v[64:67]
	v_mfma_f32_16x16x32_bf16 v[68:71], v[166:169], v[210:213], v[68:71]
	v_mfma_f32_16x16x32_bf16 v[116:119], v[170:173], v[186:189], v[116:119]
	v_mfma_f32_16x16x32_bf16 v[112:115], v[178:181], v[186:189], v[112:115]
	v_mfma_f32_16x16x32_bf16 v[96:99], v[178:181], v[194:197], v[96:99]
	v_mfma_f32_16x16x32_bf16 v[100:103], v[170:173], v[194:197], v[100:103]
	v_mfma_f32_16x16x32_bf16 v[84:87], v[170:173], v[206:209], v[84:87]
	v_mfma_f32_16x16x32_bf16 v[80:83], v[178:181], v[206:209], v[80:83]
	v_mfma_f32_16x16x32_bf16 v[64:67], v[178:181], v[214:217], v[64:67]
	v_mfma_f32_16x16x32_bf16 v[68:71], v[170:173], v[214:217], v[68:71]
	s_setprio 0
	s_barrier
; #define PG8_STAGE(bufoff, gbase, voff) do { _Pragma("unroll") for (int _i = 0; _i < 2; ++_i) \
;         __builtin_amdgcn_global_load_lds((const unsigned*)((const char*)(gbase) + (voff)[_i]), (PG8_LAS unsigned*)(lds + (bufoff) + ldsw + _i * 8192), 16, 0, 0); } while (0)
; #define PG8_LDA(dst, b, h) do { _Pragma("unroll") for (int m = 0; m < 4; ++m) _Pragma("unroll") for (int k = 0; k < 2; ++k) dst[m][k] = *(const PG8_LAS bf16x8*)(lds + PG8_SA(b, h) + aoff + m * 2048 + k * 1024); } while (0)
; #define PG8_MMA(ai, bj, At, Bt) do { __builtin_amdgcn_s_setprio(1); _Pragma("unroll") for (int m = 0; m < 4; ++m) _Pragma("unroll") for (int n = 0; n < 2; ++n) _Pragma("unroll") for (int k = 0; k < 2; ++k) \
;         acc[ai][bj][m][n] = __builtin_amdgcn_mfma_f32_16x16x32_bf16(Bt[n][k], At[m][k], acc[ai][bj][m][n], 0, 0, 0); __builtin_amdgcn_s_setprio(0); } while (0)
; #define PG8_WAIT_V(n) asm volatile("s_waitcnt vmcnt(" #n ")" ::: "memory")
; #define PG8_WAIT_L(n) asm volatile("s_waitcnt lgkmcnt(" #n ")" ::: "memory")
; #define PG8_BAR __builtin_amdgcn_s_barrier()
; #define PG8_SCHED __builtin_amdgcn_sched_barrier(0)
; template <class Epi, class Sched, bool ALIGN_EPI = false, bool SP2 = false>
; __device__ __forceinline__ void gemm_phase(PG8_LAS unsigned char* lds, const Gemm g, const Sched& S, const Epi& E) {
;     ...
;             PG8_LDA(At, 1, 1); PG8_STAGE(PG8_SB(1, 0), b3, voffB); PG8_STAGE(PG8_SB(1, 1), b3 + hstep, voffB); PG8_STAGE(PG8_SA(1, 0), a3, voffA);
;             PG8_WAIT_V(8); PG8_WAIT_L(0); PG8_BAR; PG8_MMA(1, 0, At, B0); PG8_MMA(1, 1, At, B1); PG8_BAR; PG8_SCHED;
	s_add_i32 s60, s77, s21
	v_lshl_add_u64 v[152:153], v[152:153], 0, s[40:41]
	s_mov_b32 m0, s60
	ds_read_b128 v[182:185], v158 offset:49152
	ds_read_b128 v[186:189], v158 offset:50176
	ds_read_b128 v[190:193], v158 offset:51200
	ds_read_b128 v[194:197], v158 offset:52224
	ds_read_b128 v[202:205], v158 offset:53248
	ds_read_b128 v[206:209], v158 offset:54272
	ds_read_b128 v[210:213], v158 offset:55296
	ds_read_b128 v[214:217], v158 offset:56320
	global_load_lds_dwordx4 v[152:153], off
	s_add_i32 m0, s60, 0x2000
	s_add_u32 s58, s58, 0xb0080
	v_lshl_add_u64 v[152:153], v[198:199], 0, s[40:41]
	s_addc_u32 s59, s59, 0
	s_add_i32 s60, s78, s21
	global_load_lds_dwordx4 v[152:153], off
	v_lshl_add_u64 v[152:153], s[58:59], 0, v[138:139]
	s_mov_b32 m0, s60
	s_nop 0
	global_load_lds_dwordx4 v[152:153], off
	v_lshl_add_u64 v[152:153], s[58:59], 0, v[142:143]
	s_add_i32 m0, s60, 0x2000
	s_nop 0
	global_load_lds_dwordx4 v[152:153], off
	v_lshl_add_u64 v[152:153], v[218:219], 0, s[40:41]
	s_mov_b32 m0, s64
	s_nop 0
	global_load_lds_dwordx4 v[152:153], off
	v_lshl_add_u64 v[152:153], v[220:221], 0, s[40:41]
	s_mov_b32 m0, s65
	s_nop 0
	global_load_lds_dwordx4 v[152:153], off
	s_waitcnt vmcnt(8)
	s_waitcnt lgkmcnt(0)
	s_barrier
	s_setprio 1
	s_waitcnt lgkmcnt(0)
	v_mfma_f32_16x16x32_bf16 v[60:63], v[128:131], v[182:185], v[60:63]
	v_mfma_f32_16x16x32_bf16 v[56:59], v[148:151], v[182:185], v[56:59]
	v_mfma_f32_16x16x32_bf16 v[40:43], v[148:151], v[190:193], v[40:43]
	v_mfma_f32_16x16x32_bf16 v[44:47], v[128:131], v[190:193], v[44:47]
	v_mfma_f32_16x16x32_bf16 v[32:35], v[128:131], v[202:205], v[32:35]
	v_mfma_f32_16x16x32_bf16 v[24:27], v[148:151], v[202:205], v[24:27]
	v_mfma_f32_16x16x32_bf16 v[8:11], v[148:151], v[210:213], v[8:11]
	v_mfma_f32_16x16x32_bf16 v[16:19], v[128:131], v[210:213], v[16:19]
	v_mfma_f32_16x16x32_bf16 v[60:63], v[132:135], v[186:189], v[60:63]
	v_mfma_f32_16x16x32_bf16 v[56:59], v[162:165], v[186:189], v[56:59]
	v_mfma_f32_16x16x32_bf16 v[40:43], v[162:165], v[194:197], v[40:43]
	v_mfma_f32_16x16x32_bf16 v[44:47], v[132:135], v[194:197], v[44:47]
	v_mfma_f32_16x16x32_bf16 v[32:35], v[132:135], v[206:209], v[32:35]
	v_mfma_f32_16x16x32_bf16 v[24:27], v[162:165], v[206:209], v[24:27]
	v_mfma_f32_16x16x32_bf16 v[8:11], v[162:165], v[214:217], v[8:11]
	v_mfma_f32_16x16x32_bf16 v[16:19], v[132:135], v[214:217], v[16:19]
	s_setprio 0
	s_setprio 1
	v_mfma_f32_16x16x32_bf16 v[52:55], v[166:169], v[182:185], v[52:55]
	v_mfma_f32_16x16x32_bf16 v[48:51], v[174:177], v[182:185], v[48:51]
	v_mfma_f32_16x16x32_bf16 v[28:31], v[174:177], v[190:193], v[28:31]
	v_mfma_f32_16x16x32_bf16 v[36:39], v[166:169], v[190:193], v[36:39]
	v_mfma_f32_16x16x32_bf16 v[20:23], v[166:169], v[202:205], v[20:23]
	v_mfma_f32_16x16x32_bf16 v[12:15], v[174:177], v[202:205], v[12:15]
	v_mfma_f32_16x16x32_bf16 v[0:3], v[174:177], v[210:213], v[0:3]
	v_mfma_f32_16x16x32_bf16 v[4:7], v[166:169], v[210:213], v[4:7]
	v_mfma_f32_16x16x32_bf16 v[52:55], v[170:173], v[186:189], v[52:55]
	v_mfma_f32_16x16x32_bf16 v[48:51], v[178:181], v[186:189], v[48:51]
	v_mfma_f32_16x16x32_bf16 v[28:31], v[178:181], v[194:197], v[28:31]
	v_mfma_f32_16x16x32_bf16 v[36:39], v[170:173], v[194:197], v[36:39]
	v_mfma_f32_16x16x32_bf16 v[20:23], v[170:173], v[206:209], v[20:23]
	v_mfma_f32_16x16x32_bf16 v[12:15], v[178:181], v[206:209], v[12:15]
	v_mfma_f32_16x16x32_bf16 v[0:3], v[178:181], v[214:217], v[0:3]
	v_mfma_f32_16x16x32_bf16 v[4:7], v[170:173], v[214:217], v[4:7]
	s_setprio 0
	s_barrier
	s_add_i32 s85, s85, 2
	s_add_u32 s56, s56, 0x100
	s_addc_u32 s57, s57, 0
	s_add_u32 s83, s83, 0x100
	s_addc_u32 s84, s84, 0
	s_cmp_gt_u32 s85, 41
	s_cbranch_scc0 .LBB0_245
	s_and_b64 vcc, exec, s[44:45]
	s_cbranch_vccz .LBB0_248
	s_barrier

; #define PG8_STAGE(bufoff, gbase, voff) do { _Pragma("unroll") for (int _i = 0; _i < 2; ++_i) \
;         __builtin_amdgcn_global_load_lds((const unsigned*)((const char*)(gbase) + (voff)[_i]), (PG8_LAS unsigned*)(lds + (bufoff) + ldsw + _i * 8192), 16, 0, 0); } while (0)
; #define PG8_LDA(dst, b, h) do { _Pragma("unroll") for (int m = 0; m < 4; ++m) _Pragma("unroll") for (int k = 0; k < 2; ++k) dst[m][k] = *(const PG8_LAS bf16x8*)(lds + PG8_SA(b, h) + aoff + m * 2048 + k * 1024); } while (0)
; #define PG8_LDB(dst, b, h) do { _Pragma("unroll") for (int n = 0; n < 2; ++n) _Pragma("unroll") for (int k = 0; k < 2; ++k) dst[n][k] = *(const PG8_LAS bf16x8*)(lds + PG8_SB(b, h) + boff + n * 2048 + k * 1024); } while (0)
; #define PG8_MMA(ai, bj, At, Bt) do { __builtin_amdgcn_s_setprio(1); _Pragma("unroll") for (int m = 0; m < 4; ++m) _Pragma("unroll") for (int n = 0; n < 2; ++n) _Pragma("unroll") for (int k = 0; k < 2; ++k) \
;         acc[ai][bj][m][n] = __builtin_amdgcn_mfma_f32_16x16x32_bf16(Bt[n][k], At[m][k], acc[ai][bj][m][n], 0, 0, 0); __builtin_amdgcn_s_setprio(0); } while (0)
; #define PG8_WAIT_V(n) asm volatile("s_waitcnt vmcnt(" #n ")" ::: "memory")
; #define PG8_WAIT_L(n) asm volatile("s_waitcnt lgkmcnt(" #n ")" ::: "memory")
; #define PG8_BAR __builtin_amdgcn_s_barrier()
; #define PG8_SCHED __builtin_amdgcn_sched_barrier(0)
; template <class Epi, class Sched, bool ALIGN_EPI = false, bool SP2 = false>
; __device__ __forceinline__ void gemm_phase(PG8_LAS unsigned char* lds, const Gemm g, const Sched& S, const Epi& E) {
;     ...
;             PG8_LDB(B0, 0, 0); PG8_LDB(B1, 0, 1); PG8_SCHED; PG8_LDA(At, 0, 0); PG8_STAGE(PG8_SA(1, 1), a1 + hstep, voffA);
;             PG8_WAIT_V(8); PG8_WAIT_L(0); PG8_BAR; PG8_MMA(0, 0, At, B0); PG8_MMA(0, 1, At, B1); PG8_BAR; PG8_SCHED;
;             PG8_LDA(At, 0, 1); PG8_STAGE(PG8_SB(0, 0), b2, voffB); PG8_STAGE(PG8_SB(0, 1), b2 + hstep, voffB); PG8_STAGE(PG8_SA(0, 0), a2, voffA);
.LBB0_325:
	ds_read_b128 v[140:143], v162
	ds_read_b128 v[144:147], v162 offset:1024
	ds_read_b128 v[148:151], v162 offset:2048
	ds_read_b128 v[152:155], v162 offset:3072
	ds_read_b128 v[168:171], v163
	ds_read_b128 v[172:175], v163 offset:1024
	ds_read_b128 v[176:179], v163 offset:2048
	ds_read_b128 v[180:183], v163 offset:3072
	s_add_u32 s74, s72, 0xfffc0080
	s_addc_u32 s75, s73, -1
	s_cmp_eq_u32 s84, 12
	s_cselect_b32 s77, s5, s75
	s_cselect_b32 s76, s61, s74
	s_cselect_b32 s75, s63, s83
	s_cselect_b32 s74, s71, s82
	v_lshl_add_u64 v[156:157], s[72:73], 0, v[136:137]
	s_add_i32 m0, s28, 0xc000
	ds_read_b128 v[184:187], v164
	ds_read_b128 v[188:191], v164 offset:1024
	ds_read_b128 v[192:195], v164 offset:2048
	ds_read_b128 v[196:199], v164 offset:3072
	ds_read_b128 v[202:205], v164 offset:4096
	ds_read_b128 v[206:209], v164 offset:5120
	ds_read_b128 v[210:213], v164 offset:6144
	ds_read_b128 v[214:217], v164 offset:7168
	global_load_lds_dwordx4 v[156:157], off
	v_lshl_add_u64 v[156:157], s[72:73], 0, v[138:139]
	s_add_i32 m0, s28, 0xe000
	s_nop 0
	global_load_lds_dwordx4 v[156:157], off
	s_waitcnt vmcnt(8)
	s_waitcnt lgkmcnt(0)
	s_barrier
	s_setprio 1
	s_waitcnt lgkmcnt(0)
	v_mfma_f32_16x16x32_bf16 v[124:127], v[140:143], v[184:187], v[124:127]
	v_mfma_f32_16x16x32_bf16 v[120:123], v[148:151], v[184:187], v[120:123]
	v_mfma_f32_16x16x32_bf16 v[104:107], v[148:151], v[192:195], v[104:107]
	v_mfma_f32_16x16x32_bf16 v[108:111], v[140:143], v[192:195], v[108:111]
	v_mfma_f32_16x16x32_bf16 v[92:95], v[140:143], v[202:205], v[92:95]
	v_mfma_f32_16x16x32_bf16 v[88:91], v[148:151], v[202:205], v[88:91]
	v_mfma_f32_16x16x32_bf16 v[72:75], v[148:151], v[210:213], v[72:75]
	v_mfma_f32_16x16x32_bf16 v[76:79], v[140:143], v[210:213], v[76:79]
	v_mfma_f32_16x16x32_bf16 v[124:127], v[144:147], v[188:191], v[124:127]
	v_mfma_f32_16x16x32_bf16 v[120:123], v[152:155], v[188:191], v[120:123]
	v_mfma_f32_16x16x32_bf16 v[104:107], v[152:155], v[196:199], v[104:107]
	v_mfma_f32_16x16x32_bf16 v[108:111], v[144:147], v[196:199], v[108:111]
	v_mfma_f32_16x16x32_bf16 v[92:95], v[144:147], v[206:209], v[92:95]
	v_mfma_f32_16x16x32_bf16 v[88:91], v[152:155], v[206:209], v[88:91]
	v_mfma_f32_16x16x32_bf16 v[72:75], v[152:155], v[214:217], v[72:75]
	v_mfma_f32_16x16x32_bf16 v[76:79], v[144:147], v[214:217], v[76:79]
	s_setprio 0
	s_setprio 1
	v_mfma_f32_16x16x32_bf16 v[116:119], v[168:171], v[184:187], v[116:119]
	v_mfma_f32_16x16x32_bf16 v[112:115], v[176:179], v[184:187], v[112:115]
	v_mfma_f32_16x16x32_bf16 v[96:99], v[176:179], v[192:195], v[96:99]
	v_mfma_f32_16x16x32_bf16 v[100:103], v[168:171], v[192:195], v[100:103]
	v_mfma_f32_16x16x32_bf16 v[84:87], v[168:171], v[202:205], v[84:87]
	v_mfma_f32_16x16x32_bf16 v[80:83], v[176:179], v[202:205], v[80:83]
	v_mfma_f32_16x16x32_bf16 v[64:67], v[176:179], v[210:213], v[64:67]
	v_mfma_f32_16x16x32_bf16 v[68:71], v[168:171], v[210:213], v[68:71]
	v_mfma_f32_16x16x32_bf16 v[116:119], v[172:175], v[188:191], v[116:119]
	v_mfma_f32_16x16x32_bf16 v[112:115], v[180:183], v[188:191], v[112:115]
	v_mfma_f32_16x16x32_bf16 v[96:99], v[180:183], v[196:199], v[96:99]
	v_mfma_f32_16x16x32_bf16 v[100:103], v[172:175], v[196:199], v[100:103]
	v_mfma_f32_16x16x32_bf16 v[84:87], v[172:175], v[206:209], v[84:87]
	v_mfma_f32_16x16x32_bf16 v[80:83], v[180:183], v[206:209], v[80:83]
	v_mfma_f32_16x16x32_bf16 v[64:67], v[180:183], v[214:217], v[64:67]
	v_mfma_f32_16x16x32_bf16 v[68:71], v[172:175], v[214:217], v[68:71]
	s_setprio 0
	s_barrier
	s_add_i32 s85, s79, s21
	v_lshl_add_u64 v[156:157], s[74:75], 0, v[130:131]
	s_mov_b32 m0, s85
	ds_read_b128 v[184:187], v164 offset:16384
	ds_read_b128 v[188:191], v164 offset:17408
	ds_read_b128 v[192:195], v164 offset:18432
	ds_read_b128 v[196:199], v164 offset:19456
	ds_read_b128 v[202:205], v164 offset:20480
	ds_read_b128 v[206:209], v164 offset:21504
	ds_read_b128 v[210:213], v164 offset:22528
	ds_read_b128 v[214:217], v164 offset:23552
	global_load_lds_dwordx4 v[156:157], off
	s_add_i32 m0, s85, 0x2000
	s_add_u32 s86, s74, 0x40000
	v_lshl_add_u64 v[218:219], s[74:75], 0, v[134:135]
	s_addc_u32 s87, s75, 0
	s_add_i32 s85, s80, s21
	global_load_lds_dwordx4 v[218:219], off
	v_lshl_add_u64 v[220:221], s[86:87], 0, v[130:131]
	s_mov_b32 m0, s85
	v_lshl_add_u64 v[222:223], s[76:77], 0, v[132:133]
	global_load_lds_dwordx4 v[220:221], off
	v_lshl_add_u64 v[220:221], s[86:87], 0, v[134:135]
	s_add_i32 m0, s85, 0x2000
	s_nop 0
	global_load_lds_dwordx4 v[220:221], off
	v_lshl_add_u64 v[220:221], s[76:77], 0, v[128:129]
	s_mov_b32 m0, s28
	s_nop 0
	global_load_lds_dwordx4 v[220:221], off
	s_mov_b32 m0, s29
	s_nop 0
	global_load_lds_dwordx4 v[222:223], off
	s_waitcnt vmcnt(8)
	s_waitcnt lgkmcnt(0)
	s_barrier
; #define PG8_STAGE(bufoff, gbase, voff) do { _Pragma("unroll") for (int _i = 0; _i < 2; ++_i) \
;         __builtin_amdgcn_global_load_lds((const unsigned*)((const char*)(gbase) + (voff)[_i]), (PG8_LAS unsigned*)(lds + (bufoff) + ldsw + _i * 8192), 16, 0, 0); } while (0)
; #define PG8_LDA(dst, b, h) do { _Pragma("unroll") for (int m = 0; m < 4; ++m) _Pragma("unroll") for (int k = 0; k < 2; ++k) dst[m][k] = *(const PG8_LAS bf16x8*)(lds + PG8_SA(b, h) + aoff + m * 2048 + k * 1024); } while (0)
; #define PG8_LDB(dst, b, h) do { _Pragma("unroll") for (int n = 0; n < 2; ++n) _Pragma("unroll") for (int k = 0; k < 2; ++k) dst[n][k] = *(const PG8_LAS bf16x8*)(lds + PG8_SB(b, h) + boff + n * 2048 + k * 1024); } while (0)
; #define PG8_MMA(ai, bj, At, Bt) do { __builtin_amdgcn_s_setprio(1); _Pragma("unroll") for (int m = 0; m < 4; ++m) _Pragma("unroll") for (int n = 0; n < 2; ++n) _Pragma("unroll") for (int k = 0; k < 2; ++k) \
;         acc[ai][bj][m][n] = __builtin_amdgcn_mfma_f32_16x16x32_bf16(Bt[n][k], At[m][k], acc[ai][bj][m][n], 0, 0, 0); __builtin_amdgcn_s_setprio(0); } while (0)
; #define PG8_WAIT_V(n) asm volatile("s_waitcnt vmcnt(" #n ")" ::: "memory")
; #define PG8_WAIT_L(n) asm volatile("s_waitcnt lgkmcnt(" #n ")" ::: "memory")
; #define PG8_BAR __builtin_amdgcn_s_barrier()
; #define PG8_SCHED __builtin_amdgcn_sched_barrier(0)
; template <class Epi, class Sched, bool ALIGN_EPI = false, bool SP2 = false>
; __device__ __forceinline__ void gemm_phase(PG8_LAS unsigned char* lds, const Gemm g, const Sched& S, const Epi& E) {
;     ...
;             PG8_WAIT_V(8); PG8_WAIT_L(0); PG8_BAR; PG8_MMA(1, 0, At, B0); PG8_MMA(1, 1, At, B1); PG8_BAR; PG8_SCHED;
;             PG8_LDB(B0, 1, 0); PG8_LDB(B1, 1, 1); PG8_SCHED; PG8_LDA(At, 1, 0); PG8_STAGE(PG8_SA(0, 1), a2 + hstep, voffA);
;             PG8_WAIT_V(8); PG8_WAIT_L(0); PG8_BAR; PG8_MMA(0, 0, At, B0); PG8_MMA(0, 1, At, B1); PG8_BAR; PG8_SCHED;
	s_setprio 1
	s_waitcnt lgkmcnt(0)
	v_mfma_f32_16x16x32_bf16 v[60:63], v[140:143], v[184:187], v[60:63]
	v_mfma_f32_16x16x32_bf16 v[56:59], v[148:151], v[184:187], v[56:59]
	v_mfma_f32_16x16x32_bf16 v[40:43], v[148:151], v[192:195], v[40:43]
	v_mfma_f32_16x16x32_bf16 v[44:47], v[140:143], v[192:195], v[44:47]
	v_mfma_f32_16x16x32_bf16 v[28:31], v[140:143], v[202:205], v[28:31]
	v_mfma_f32_16x16x32_bf16 v[24:27], v[148:151], v[202:205], v[24:27]
	v_mfma_f32_16x16x32_bf16 v[8:11], v[148:151], v[210:213], v[8:11]
	v_mfma_f32_16x16x32_bf16 v[12:15], v[140:143], v[210:213], v[12:15]
	v_mfma_f32_16x16x32_bf16 v[60:63], v[144:147], v[188:191], v[60:63]
	v_mfma_f32_16x16x32_bf16 v[56:59], v[152:155], v[188:191], v[56:59]
	v_mfma_f32_16x16x32_bf16 v[40:43], v[152:155], v[196:199], v[40:43]
	v_mfma_f32_16x16x32_bf16 v[44:47], v[144:147], v[196:199], v[44:47]
	v_mfma_f32_16x16x32_bf16 v[28:31], v[144:147], v[206:209], v[28:31]
	v_mfma_f32_16x16x32_bf16 v[24:27], v[152:155], v[206:209], v[24:27]
	v_mfma_f32_16x16x32_bf16 v[8:11], v[152:155], v[214:217], v[8:11]
	v_mfma_f32_16x16x32_bf16 v[12:15], v[144:147], v[214:217], v[12:15]
	s_setprio 0
	s_setprio 1
	v_mfma_f32_16x16x32_bf16 v[52:55], v[168:171], v[184:187], v[52:55]
	v_mfma_f32_16x16x32_bf16 v[48:51], v[176:179], v[184:187], v[48:51]
	v_mfma_f32_16x16x32_bf16 v[32:35], v[176:179], v[192:195], v[32:35]
	v_mfma_f32_16x16x32_bf16 v[36:39], v[168:171], v[192:195], v[36:39]
	v_mfma_f32_16x16x32_bf16 v[20:23], v[168:171], v[202:205], v[20:23]
	v_mfma_f32_16x16x32_bf16 v[16:19], v[176:179], v[202:205], v[16:19]
	v_mfma_f32_16x16x32_bf16 v[0:3], v[176:179], v[210:213], v[0:3]
	v_mfma_f32_16x16x32_bf16 v[4:7], v[168:171], v[210:213], v[4:7]
	v_mfma_f32_16x16x32_bf16 v[52:55], v[172:175], v[188:191], v[52:55]
	v_mfma_f32_16x16x32_bf16 v[48:51], v[180:183], v[188:191], v[48:51]
	v_mfma_f32_16x16x32_bf16 v[32:35], v[180:183], v[196:199], v[32:35]
	v_mfma_f32_16x16x32_bf16 v[36:39], v[172:175], v[196:199], v[36:39]
	v_mfma_f32_16x16x32_bf16 v[20:23], v[172:175], v[206:209], v[20:23]
	v_mfma_f32_16x16x32_bf16 v[16:19], v[180:183], v[206:209], v[16:19]
	v_mfma_f32_16x16x32_bf16 v[0:3], v[180:183], v[214:217], v[0:3]
	v_mfma_f32_16x16x32_bf16 v[4:7], v[172:175], v[214:217], v[4:7]
	s_setprio 0
	s_barrier
	s_add_i32 s85, 0, 0x18000
	s_add_i32 s86, 0, 0x1c000
	v_add_u32_e32 v152, s85, v160
	v_add_u32_e32 v167, s86, v160
	ds_read_b128 v[140:143], v152
	ds_read_b128 v[144:147], v152 offset:1024
	ds_read_b128 v[148:151], v152 offset:2048
	ds_read_b128 v[152:155], v152 offset:3072
	ds_read_b128 v[168:171], v167
	ds_read_b128 v[172:175], v167 offset:1024
	ds_read_b128 v[176:179], v167 offset:2048
	ds_read_b128 v[180:183], v167 offset:3072
	s_add_u32 s76, s76, 0x40000
	s_addc_u32 s77, s77, 0
	s_mov_b32 m0, s30
	v_lshl_add_u64 v[224:225], s[76:77], 0, v[128:129]
	ds_read_b128 v[184:187], v164 offset:32768
	ds_read_b128 v[188:191], v164 offset:33792
	ds_read_b128 v[192:195], v164 offset:34816
	ds_read_b128 v[196:199], v164 offset:35840
	ds_read_b128 v[202:205], v164 offset:36864
	ds_read_b128 v[206:209], v164 offset:37888
	ds_read_b128 v[210:213], v164 offset:38912
	ds_read_b128 v[214:217], v164 offset:39936
	global_load_lds_dwordx4 v[224:225], off
	v_lshl_add_u64 v[224:225], s[76:77], 0, v[132:133]
	s_mov_b32 m0, s31
	s_nop 0
	global_load_lds_dwordx4 v[224:225], off
	s_waitcnt vmcnt(8)
	s_waitcnt lgkmcnt(0)
	s_barrier
	s_setprio 1
	s_waitcnt lgkmcnt(0)
	v_mfma_f32_16x16x32_bf16 v[124:127], v[140:143], v[184:187], v[124:127]
	v_mfma_f32_16x16x32_bf16 v[120:123], v[148:151], v[184:187], v[120:123]
	v_mfma_f32_16x16x32_bf16 v[104:107], v[148:151], v[192:195], v[104:107]
	v_mfma_f32_16x16x32_bf16 v[108:111], v[140:143], v[192:195], v[108:111]
	v_mfma_f32_16x16x32_bf16 v[92:95], v[140:143], v[202:205], v[92:95]
	v_mfma_f32_16x16x32_bf16 v[88:91], v[148:151], v[202:205], v[88:91]
	v_mfma_f32_16x16x32_bf16 v[72:75], v[148:151], v[210:213], v[72:75]
	v_mfma_f32_16x16x32_bf16 v[76:79], v[140:143], v[210:213], v[76:79]
	v_mfma_f32_16x16x32_bf16 v[124:127], v[144:147], v[188:191], v[124:127]
	v_mfma_f32_16x16x32_bf16 v[120:123], v[152:155], v[188:191], v[120:123]
	v_mfma_f32_16x16x32_bf16 v[104:107], v[152:155], v[196:199], v[104:107]
	v_mfma_f32_16x16x32_bf16 v[108:111], v[144:147], v[196:199], v[108:111]
	v_mfma_f32_16x16x32_bf16 v[92:95], v[144:147], v[206:209], v[92:95]
	v_mfma_f32_16x16x32_bf16 v[88:91], v[152:155], v[206:209], v[88:91]
	v_mfma_f32_16x16x32_bf16 v[72:75], v[152:155], v[214:217], v[72:75]
	v_mfma_f32_16x16x32_bf16 v[76:79], v[144:147], v[214:217], v[76:79]
	s_setprio 0
	s_setprio 1
	v_mfma_f32_16x16x32_bf16 v[116:119], v[168:171], v[184:187], v[116:119]
	v_mfma_f32_16x16x32_bf16 v[112:115], v[176:179], v[184:187], v[112:115]
	v_mfma_f32_16x16x32_bf16 v[96:99], v[176:179], v[192:195], v[96:99]
	v_mfma_f32_16x16x32_bf16 v[100:103], v[168:171], v[192:195], v[100:103]
	v_mfma_f32_16x16x32_bf16 v[84:87], v[168:171], v[202:205], v[84:87]
	v_mfma_f32_16x16x32_bf16 v[80:83], v[176:179], v[202:205], v[80:83]
	v_mfma_f32_16x16x32_bf16 v[64:67], v[176:179], v[210:213], v[64:67]
	v_mfma_f32_16x16x32_bf16 v[68:71], v[168:171], v[210:213], v[68:71]
	v_mfma_f32_16x16x32_bf16 v[116:119], v[172:175], v[188:191], v[116:119]
	v_mfma_f32_16x16x32_bf16 v[112:115], v[180:183], v[188:191], v[112:115]
	v_mfma_f32_16x16x32_bf16 v[96:99], v[180:183], v[196:199], v[96:99]
	v_mfma_f32_16x16x32_bf16 v[100:103], v[172:175], v[196:199], v[100:103]
	v_mfma_f32_16x16x32_bf16 v[84:87], v[172:175], v[206:209], v[84:87]
	v_mfma_f32_16x16x32_bf16 v[80:83], v[180:183], v[206:209], v[80:83]
	v_mfma_f32_16x16x32_bf16 v[64:67], v[180:183], v[214:217], v[64:67]
	v_mfma_f32_16x16x32_bf16 v[68:71], v[172:175], v[214:217], v[68:71]
	s_setprio 0
	s_barrier
; #define PG8_STAGE(bufoff, gbase, voff) do { _Pragma("unroll") for (int _i = 0; _i < 2; ++_i) \
;         __builtin_amdgcn_global_load_lds((const unsigned*)((const char*)(gbase) + (voff)[_i]), (PG8_LAS unsigned*)(lds + (bufoff) + ldsw + _i * 8192), 16, 0, 0); } while (0)
; #define PG8_LDA(dst, b, h) do { _Pragma("unroll") for (int m = 0; m < 4; ++m) _Pragma("unroll") for (int k = 0; k < 2; ++k) dst[m][k] = *(const PG8_LAS bf16x8*)(lds + PG8_SA(b, h) + aoff + m * 2048 + k * 1024); } while (0)
; #define PG8_MMA(ai, bj, At, Bt) do { __builtin_amdgcn_s_setprio(1); _Pragma("unroll") for (int m = 0; m < 4; ++m) _Pragma("unroll") for (int n = 0; n < 2; ++n) _Pragma("unroll") for (int k = 0; k < 2; ++k) \
;         acc[ai][bj][m][n] = __builtin_amdgcn_mfma_f32_16x16x32_bf16(Bt[n][k], At[m][k], acc[ai][bj][m][n], 0, 0, 0); __builtin_amdgcn_s_setprio(0); } while (0)
; #define PG8_WAIT_V(n) asm volatile("s_waitcnt vmcnt(" #n ")" ::: "memory")
; #define PG8_WAIT_L(n) asm volatile("s_waitcnt lgkmcnt(" #n ")" ::: "memory")
; #define PG8_BAR __builtin_amdgcn_s_barrier()
; #define PG8_SCHED __builtin_amdgcn_sched_barrier(0)
; template <class Epi, class Sched, bool ALIGN_EPI = false, bool SP2 = false>
; __device__ __forceinline__ void gemm_phase(PG8_LAS unsigned char* lds, const Gemm g, const Sched& S, const Epi& E) {
;     ...
;         for (int t = 0; t < nt; t += 2) {
;             const bool last = (t == nt - 2);
;             const char* a1 = cA + (size_t)(t + 1) * kstep;
;             const char* a2 = last ? nA : cA + (size_t)(t + 2) * kstep; const char* b2 = last ? nB : cB + (size_t)(t + 2) * kstep;
;             const char* a3 = a2 + kstep; const char* b3 = b2 + kstep;
;     ...
;             PG8_LDA(At, 1, 1); PG8_STAGE(PG8_SB(1, 0), b3, voffB); PG8_STAGE(PG8_SB(1, 1), b3 + hstep, voffB); PG8_STAGE(PG8_SA(1, 0), a3, voffA);
;             PG8_WAIT_V(8); PG8_WAIT_L(0); PG8_BAR; PG8_MMA(1, 0, At, B0); PG8_MMA(1, 1, At, B1); PG8_BAR; PG8_SCHED;
	s_add_i32 s76, s85, s21
	v_lshl_add_u64 v[156:157], v[156:157], 0, s[56:57]
	s_mov_b32 m0, s76
	ds_read_b128 v[184:187], v164 offset:49152
	ds_read_b128 v[188:191], v164 offset:50176
	ds_read_b128 v[192:195], v164 offset:51200
	ds_read_b128 v[196:199], v164 offset:52224
	ds_read_b128 v[202:205], v164 offset:53248
	ds_read_b128 v[206:209], v164 offset:54272
	ds_read_b128 v[210:213], v164 offset:55296
	ds_read_b128 v[214:217], v164 offset:56320
	global_load_lds_dwordx4 v[156:157], off
	s_add_i32 m0, s76, 0x2000
	s_add_u32 s74, s74, 0x40080
	v_lshl_add_u64 v[156:157], v[218:219], 0, s[56:57]
	s_addc_u32 s75, s75, 0
	s_add_i32 s76, s86, s21
	global_load_lds_dwordx4 v[156:157], off
	v_lshl_add_u64 v[156:157], s[74:75], 0, v[130:131]
	s_mov_b32 m0, s76
	s_nop 0
	global_load_lds_dwordx4 v[156:157], off
	v_lshl_add_u64 v[156:157], s[74:75], 0, v[134:135]
	s_add_i32 m0, s76, 0x2000
	s_nop 0
	global_load_lds_dwordx4 v[156:157], off
	v_lshl_add_u64 v[156:157], v[220:221], 0, s[56:57]
	s_mov_b32 m0, s39
	s_nop 0
	global_load_lds_dwordx4 v[156:157], off
	v_lshl_add_u64 v[156:157], v[222:223], 0, s[56:57]
	s_mov_b32 m0, s78
	s_nop 0
	global_load_lds_dwordx4 v[156:157], off
	s_waitcnt vmcnt(8)
	s_waitcnt lgkmcnt(0)
	s_barrier
	s_setprio 1
	s_waitcnt lgkmcnt(0)
	v_mfma_f32_16x16x32_bf16 v[60:63], v[140:143], v[184:187], v[60:63]
	v_mfma_f32_16x16x32_bf16 v[56:59], v[148:151], v[184:187], v[56:59]
	v_mfma_f32_16x16x32_bf16 v[40:43], v[148:151], v[192:195], v[40:43]
	v_mfma_f32_16x16x32_bf16 v[44:47], v[140:143], v[192:195], v[44:47]
	v_mfma_f32_16x16x32_bf16 v[28:31], v[140:143], v[202:205], v[28:31]
	v_mfma_f32_16x16x32_bf16 v[24:27], v[148:151], v[202:205], v[24:27]
	v_mfma_f32_16x16x32_bf16 v[8:11], v[148:151], v[210:213], v[8:11]
	v_mfma_f32_16x16x32_bf16 v[12:15], v[140:143], v[210:213], v[12:15]
	v_mfma_f32_16x16x32_bf16 v[60:63], v[144:147], v[188:191], v[60:63]
	v_mfma_f32_16x16x32_bf16 v[56:59], v[152:155], v[188:191], v[56:59]
	v_mfma_f32_16x16x32_bf16 v[40:43], v[152:155], v[196:199], v[40:43]
	v_mfma_f32_16x16x32_bf16 v[44:47], v[144:147], v[196:199], v[44:47]
	v_mfma_f32_16x16x32_bf16 v[28:31], v[144:147], v[206:209], v[28:31]
	v_mfma_f32_16x16x32_bf16 v[24:27], v[152:155], v[206:209], v[24:27]
	v_mfma_f32_16x16x32_bf16 v[8:11], v[152:155], v[214:217], v[8:11]
	v_mfma_f32_16x16x32_bf16 v[12:15], v[144:147], v[214:217], v[12:15]
	s_setprio 0
	s_setprio 1
	v_mfma_f32_16x16x32_bf16 v[52:55], v[168:171], v[184:187], v[52:55]
	v_mfma_f32_16x16x32_bf16 v[48:51], v[176:179], v[184:187], v[48:51]
	v_mfma_f32_16x16x32_bf16 v[32:35], v[176:179], v[192:195], v[32:35]
	v_mfma_f32_16x16x32_bf16 v[36:39], v[168:171], v[192:195], v[36:39]
	v_mfma_f32_16x16x32_bf16 v[20:23], v[168:171], v[202:205], v[20:23]
	v_mfma_f32_16x16x32_bf16 v[16:19], v[176:179], v[202:205], v[16:19]
	v_mfma_f32_16x16x32_bf16 v[0:3], v[176:179], v[210:213], v[0:3]
	v_mfma_f32_16x16x32_bf16 v[4:7], v[168:171], v[210:213], v[4:7]
	v_mfma_f32_16x16x32_bf16 v[52:55], v[172:175], v[188:191], v[52:55]
	v_mfma_f32_16x16x32_bf16 v[48:51], v[180:183], v[188:191], v[48:51]
	v_mfma_f32_16x16x32_bf16 v[32:35], v[180:183], v[196:199], v[32:35]
	v_mfma_f32_16x16x32_bf16 v[36:39], v[172:175], v[196:199], v[36:39]
	v_mfma_f32_16x16x32_bf16 v[20:23], v[172:175], v[206:209], v[20:23]
	v_mfma_f32_16x16x32_bf16 v[16:19], v[180:183], v[206:209], v[16:19]
	v_mfma_f32_16x16x32_bf16 v[0:3], v[180:183], v[214:217], v[0:3]
	v_mfma_f32_16x16x32_bf16 v[4:7], v[172:175], v[214:217], v[4:7]
	s_setprio 0
	s_barrier
	s_add_i32 s84, s84, 2
	s_add_u32 s72, s72, 0x100
	s_addc_u32 s73, s73, 0
	s_add_u32 s82, s82, 0x100
	s_addc_u32 s83, s83, 0
	s_cmp_gt_u32 s84, 13
	s_cbranch_scc0 .LBB0_325
	s_and_b64 vcc, exec, s[58:59]
	s_cbranch_vccz .LBB0_328
	s_barrier

; #define PG8_STAGE(bufoff, gbase, voff) do { _Pragma("unroll") for (int _i = 0; _i < 2; ++_i) \
;         __builtin_amdgcn_global_load_lds((const unsigned*)((const char*)(gbase) + (voff)[_i]), (PG8_LAS unsigned*)(lds + (bufoff) + ldsw + _i * 8192), 16, 0, 0); } while (0)
; #define PG8_LDA(dst, b, h) do { _Pragma("unroll") for (int m = 0; m < 4; ++m) _Pragma("unroll") for (int k = 0; k < 2; ++k) dst[m][k] = *(const PG8_LAS bf16x8*)(lds + PG8_SA(b, h) + aoff + m * 2048 + k * 1024); } while (0)
; #define PG8_LDB(dst, b, h) do { _Pragma("unroll") for (int n = 0; n < 2; ++n) _Pragma("unroll") for (int k = 0; k < 2; ++k) dst[n][k] = *(const PG8_LAS bf16x8*)(lds + PG8_SB(b, h) + boff + n * 2048 + k * 1024); } while (0)
; #define PG8_MMA(ai, bj, At, Bt) do { __builtin_amdgcn_s_setprio(1); _Pragma("unroll") for (int m = 0; m < 4; ++m) _Pragma("unroll") for (int n = 0; n < 2; ++n) _Pragma("unroll") for (int k = 0; k < 2; ++k) \
;         acc[ai][bj][m][n] = __builtin_amdgcn_mfma_f32_16x16x32_bf16(Bt[n][k], At[m][k], acc[ai][bj][m][n], 0, 0, 0); __builtin_amdgcn_s_setprio(0); } while (0)
; #define PG8_WAIT_V(n) asm volatile("s_waitcnt vmcnt(" #n ")" ::: "memory")
; #define PG8_WAIT_L(n) asm volatile("s_waitcnt lgkmcnt(" #n ")" ::: "memory")
; #define PG8_BAR __builtin_amdgcn_s_barrier()
; #define PG8_SCHED __builtin_amdgcn_sched_barrier(0)
; template <class Epi, class Sched, bool ALIGN_EPI = false, bool SP2 = false>
; __device__ __forceinline__ void gemm_phase(PG8_LAS unsigned char* lds, const Gemm g, const Sched& S, const Epi& E) {
;     ...
;             PG8_LDB(B0, 0, 0); PG8_LDB(B1, 0, 1); PG8_SCHED; PG8_LDA(At, 0, 0); PG8_STAGE(PG8_SA(1, 1), a1 + hstep, voffA);
;             PG8_WAIT_V(8); PG8_WAIT_L(0); PG8_BAR; PG8_MMA(0, 0, At, B0); PG8_MMA(0, 1, At, B1); PG8_BAR; PG8_SCHED;
;             PG8_LDA(At, 0, 1); PG8_STAGE(PG8_SB(0, 0), b2, voffB); PG8_STAGE(PG8_SB(0, 1), b2 + hstep, voffB); PG8_STAGE(PG8_SA(0, 0), a2, voffA);
.LBB0_582:
	ds_read_b128 v[128:131], v168
	ds_read_b128 v[132:135], v168 offset:1024
	ds_read_b128 v[136:139], v168 offset:2048
	ds_read_b128 v[140:143], v168 offset:3072
	ds_read_b128 v[158:161], v169
	ds_read_b128 v[162:165], v169 offset:1024
	ds_read_b128 v[172:175], v169 offset:2048
	ds_read_b128 v[176:179], v169 offset:3072
	s_add_u32 s58, s84, 0xfffc0080
	s_addc_u32 s59, s85, -1
	s_cmp_eq_u32 s91, 12
	s_cselect_b32 s89, s56, s59
	s_cselect_b32 s88, s57, s58
	s_cselect_b32 s87, s71, s90
	s_cselect_b32 s86, s73, s81
	v_lshl_add_u64 v[218:219], s[84:85], 0, v[154:155]
	s_add_i32 m0, s29, 0xc000
	ds_read_b128 v[180:183], v170
	ds_read_b128 v[184:187], v170 offset:1024
	ds_read_b128 v[188:191], v170 offset:2048
	ds_read_b128 v[192:195], v170 offset:3072
	ds_read_b128 v[196:199], v170 offset:4096
	ds_read_b128 v[206:209], v170 offset:5120
	ds_read_b128 v[210:213], v170 offset:6144
	ds_read_b128 v[214:217], v170 offset:7168
	global_load_lds_dwordx4 v[218:219], off
	v_lshl_add_u64 v[218:219], s[84:85], 0, v[156:157]
	s_add_i32 m0, s29, 0xe000
	s_nop 0
	global_load_lds_dwordx4 v[218:219], off
	s_waitcnt vmcnt(8)
	s_waitcnt lgkmcnt(0)
	s_barrier
	s_setprio 1
	s_waitcnt lgkmcnt(0)
	v_mfma_f32_16x16x32_bf16 v[124:127], v[128:131], v[180:183], v[124:127]
	v_mfma_f32_16x16x32_bf16 v[120:123], v[136:139], v[180:183], v[120:123]
	v_mfma_f32_16x16x32_bf16 v[104:107], v[136:139], v[188:191], v[104:107]
	v_mfma_f32_16x16x32_bf16 v[108:111], v[128:131], v[188:191], v[108:111]
	v_mfma_f32_16x16x32_bf16 v[96:99], v[128:131], v[196:199], v[96:99]
	v_mfma_f32_16x16x32_bf16 v[88:91], v[136:139], v[196:199], v[88:91]
	v_mfma_f32_16x16x32_bf16 v[72:75], v[136:139], v[210:213], v[72:75]
	v_mfma_f32_16x16x32_bf16 v[80:83], v[128:131], v[210:213], v[80:83]
	v_mfma_f32_16x16x32_bf16 v[124:127], v[132:135], v[184:187], v[124:127]
	v_mfma_f32_16x16x32_bf16 v[120:123], v[140:143], v[184:187], v[120:123]
	v_mfma_f32_16x16x32_bf16 v[104:107], v[140:143], v[192:195], v[104:107]
	v_mfma_f32_16x16x32_bf16 v[108:111], v[132:135], v[192:195], v[108:111]
	v_mfma_f32_16x16x32_bf16 v[96:99], v[132:135], v[206:209], v[96:99]
	v_mfma_f32_16x16x32_bf16 v[88:91], v[140:143], v[206:209], v[88:91]
	v_mfma_f32_16x16x32_bf16 v[72:75], v[140:143], v[214:217], v[72:75]
	v_mfma_f32_16x16x32_bf16 v[80:83], v[132:135], v[214:217], v[80:83]
	s_setprio 0
	s_setprio 1
	v_mfma_f32_16x16x32_bf16 v[116:119], v[158:161], v[180:183], v[116:119]
	v_mfma_f32_16x16x32_bf16 v[112:115], v[172:175], v[180:183], v[112:115]
	v_mfma_f32_16x16x32_bf16 v[92:95], v[172:175], v[188:191], v[92:95]
	v_mfma_f32_16x16x32_bf16 v[100:103], v[158:161], v[188:191], v[100:103]
	v_mfma_f32_16x16x32_bf16 v[84:87], v[158:161], v[196:199], v[84:87]
	v_mfma_f32_16x16x32_bf16 v[76:79], v[172:175], v[196:199], v[76:79]
	v_mfma_f32_16x16x32_bf16 v[64:67], v[172:175], v[210:213], v[64:67]
	v_mfma_f32_16x16x32_bf16 v[68:71], v[158:161], v[210:213], v[68:71]
	v_mfma_f32_16x16x32_bf16 v[116:119], v[162:165], v[184:187], v[116:119]
	v_mfma_f32_16x16x32_bf16 v[112:115], v[176:179], v[184:187], v[112:115]
	v_mfma_f32_16x16x32_bf16 v[92:95], v[176:179], v[192:195], v[92:95]
	v_mfma_f32_16x16x32_bf16 v[100:103], v[162:165], v[192:195], v[100:103]
	v_mfma_f32_16x16x32_bf16 v[84:87], v[162:165], v[206:209], v[84:87]
	v_mfma_f32_16x16x32_bf16 v[76:79], v[176:179], v[206:209], v[76:79]
	v_mfma_f32_16x16x32_bf16 v[64:67], v[176:179], v[214:217], v[64:67]
	v_mfma_f32_16x16x32_bf16 v[68:71], v[162:165], v[214:217], v[68:71]
	s_setprio 0
	s_barrier
	s_add_i32 s58, s11, s28
	v_lshl_add_u64 v[218:219], s[86:87], 0, v[148:149]
	s_mov_b32 m0, s58
	ds_read_b128 v[180:183], v170 offset:16384
	ds_read_b128 v[184:187], v170 offset:17408
	ds_read_b128 v[188:191], v170 offset:18432
	ds_read_b128 v[192:195], v170 offset:19456
	ds_read_b128 v[196:199], v170 offset:20480
	ds_read_b128 v[206:209], v170 offset:21504
	ds_read_b128 v[210:213], v170 offset:22528
	ds_read_b128 v[214:217], v170 offset:23552
	global_load_lds_dwordx4 v[218:219], off
	s_add_i32 m0, s58, 0x2000
	s_add_u32 s58, s86, 0x40000
	v_lshl_add_u64 v[220:221], s[86:87], 0, v[152:153]
	s_addc_u32 s59, s87, 0
	s_add_i32 s60, s83, s28
	global_load_lds_dwordx4 v[220:221], off
	v_lshl_add_u64 v[222:223], s[58:59], 0, v[148:149]
	s_mov_b32 m0, s60
	v_lshl_add_u64 v[224:225], s[88:89], 0, v[150:151]
	global_load_lds_dwordx4 v[222:223], off
	v_lshl_add_u64 v[222:223], s[58:59], 0, v[152:153]
	s_add_i32 m0, s60, 0x2000
	s_nop 0
	global_load_lds_dwordx4 v[222:223], off
	v_lshl_add_u64 v[222:223], s[88:89], 0, v[146:147]
	s_mov_b32 m0, s29
	s_nop 0
	global_load_lds_dwordx4 v[222:223], off
	s_mov_b32 m0, s30
	s_nop 0
	global_load_lds_dwordx4 v[224:225], off
	s_waitcnt vmcnt(8)
	s_waitcnt lgkmcnt(0)
	s_barrier
; #define PG8_STAGE(bufoff, gbase, voff) do { _Pragma("unroll") for (int _i = 0; _i < 2; ++_i) \
;         __builtin_amdgcn_global_load_lds((const unsigned*)((const char*)(gbase) + (voff)[_i]), (PG8_LAS unsigned*)(lds + (bufoff) + ldsw + _i * 8192), 16, 0, 0); } while (0)
; #define PG8_LDA(dst, b, h) do { _Pragma("unroll") for (int m = 0; m < 4; ++m) _Pragma("unroll") for (int k = 0; k < 2; ++k) dst[m][k] = *(const PG8_LAS bf16x8*)(lds + PG8_SA(b, h) + aoff + m * 2048 + k * 1024); } while (0)
; #define PG8_LDB(dst, b, h) do { _Pragma("unroll") for (int n = 0; n < 2; ++n) _Pragma("unroll") for (int k = 0; k < 2; ++k) dst[n][k] = *(const PG8_LAS bf16x8*)(lds + PG8_SB(b, h) + boff + n * 2048 + k * 1024); } while (0)
; #define PG8_MMA(ai, bj, At, Bt) do { __builtin_amdgcn_s_setprio(1); _Pragma("unroll") for (int m = 0; m < 4; ++m) _Pragma("unroll") for (int n = 0; n < 2; ++n) _Pragma("unroll") for (int k = 0; k < 2; ++k) \
;         acc[ai][bj][m][n] = __builtin_amdgcn_mfma_f32_16x16x32_bf16(Bt[n][k], At[m][k], acc[ai][bj][m][n], 0, 0, 0); __builtin_amdgcn_s_setprio(0); } while (0)
; #define PG8_WAIT_V(n) asm volatile("s_waitcnt vmcnt(" #n ")" ::: "memory")
; #define PG8_WAIT_L(n) asm volatile("s_waitcnt lgkmcnt(" #n ")" ::: "memory")
; #define PG8_BAR __builtin_amdgcn_s_barrier()
; #define PG8_SCHED __builtin_amdgcn_sched_barrier(0)
; template <class Epi, class Sched, bool ALIGN_EPI = false, bool SP2 = false>
; __device__ __forceinline__ void gemm_phase(PG8_LAS unsigned char* lds, const Gemm g, const Sched& S, const Epi& E) {
;     ...
;             PG8_WAIT_V(8); PG8_WAIT_L(0); PG8_BAR; PG8_MMA(1, 0, At, B0); PG8_MMA(1, 1, At, B1); PG8_BAR; PG8_SCHED;
;             PG8_LDB(B0, 1, 0); PG8_LDB(B1, 1, 1); PG8_SCHED; PG8_LDA(At, 1, 0); PG8_STAGE(PG8_SA(0, 1), a2 + hstep, voffA);
;             PG8_WAIT_V(8); PG8_WAIT_L(0); PG8_BAR; PG8_MMA(0, 0, At, B0); PG8_MMA(0, 1, At, B1); PG8_BAR; PG8_SCHED;
	s_setprio 1
	s_waitcnt lgkmcnt(0)
	v_mfma_f32_16x16x32_bf16 v[60:63], v[128:131], v[180:183], v[60:63]
	v_mfma_f32_16x16x32_bf16 v[56:59], v[136:139], v[180:183], v[56:59]
	v_mfma_f32_16x16x32_bf16 v[40:43], v[136:139], v[188:191], v[40:43]
	v_mfma_f32_16x16x32_bf16 v[48:51], v[128:131], v[188:191], v[48:51]
	v_mfma_f32_16x16x32_bf16 v[32:35], v[128:131], v[196:199], v[32:35]
	v_mfma_f32_16x16x32_bf16 v[24:27], v[136:139], v[196:199], v[24:27]
	v_mfma_f32_16x16x32_bf16 v[8:11], v[136:139], v[210:213], v[8:11]
	v_mfma_f32_16x16x32_bf16 v[16:19], v[128:131], v[210:213], v[16:19]
	v_mfma_f32_16x16x32_bf16 v[60:63], v[132:135], v[184:187], v[60:63]
	v_mfma_f32_16x16x32_bf16 v[56:59], v[140:143], v[184:187], v[56:59]
	v_mfma_f32_16x16x32_bf16 v[40:43], v[140:143], v[192:195], v[40:43]
	v_mfma_f32_16x16x32_bf16 v[48:51], v[132:135], v[192:195], v[48:51]
	v_mfma_f32_16x16x32_bf16 v[32:35], v[132:135], v[206:209], v[32:35]
	v_mfma_f32_16x16x32_bf16 v[24:27], v[140:143], v[206:209], v[24:27]
	v_mfma_f32_16x16x32_bf16 v[8:11], v[140:143], v[214:217], v[8:11]
	v_mfma_f32_16x16x32_bf16 v[16:19], v[132:135], v[214:217], v[16:19]
	s_setprio 0
	s_setprio 1
	v_mfma_f32_16x16x32_bf16 v[52:55], v[158:161], v[180:183], v[52:55]
	v_mfma_f32_16x16x32_bf16 v[44:47], v[172:175], v[180:183], v[44:47]
	v_mfma_f32_16x16x32_bf16 v[28:31], v[172:175], v[188:191], v[28:31]
	v_mfma_f32_16x16x32_bf16 v[36:39], v[158:161], v[188:191], v[36:39]
	v_mfma_f32_16x16x32_bf16 v[20:23], v[158:161], v[196:199], v[20:23]
	v_mfma_f32_16x16x32_bf16 v[12:15], v[172:175], v[196:199], v[12:15]
	v_mfma_f32_16x16x32_bf16 v[0:3], v[172:175], v[210:213], v[0:3]
	v_mfma_f32_16x16x32_bf16 v[4:7], v[158:161], v[210:213], v[4:7]
	v_mfma_f32_16x16x32_bf16 v[52:55], v[162:165], v[184:187], v[52:55]
	v_mfma_f32_16x16x32_bf16 v[44:47], v[176:179], v[184:187], v[44:47]
	v_mfma_f32_16x16x32_bf16 v[28:31], v[176:179], v[192:195], v[28:31]
	v_mfma_f32_16x16x32_bf16 v[36:39], v[162:165], v[192:195], v[36:39]
	v_mfma_f32_16x16x32_bf16 v[20:23], v[162:165], v[206:209], v[20:23]
	v_mfma_f32_16x16x32_bf16 v[12:15], v[176:179], v[206:209], v[12:15]
	v_mfma_f32_16x16x32_bf16 v[0:3], v[176:179], v[214:217], v[0:3]
	v_mfma_f32_16x16x32_bf16 v[4:7], v[162:165], v[214:217], v[4:7]
	s_setprio 0
	s_barrier
	s_add_i32 s60, 0, 0x18000
	s_add_i32 s61, 0, 0x1c000
	v_add_u32_e32 v140, s60, v166
	v_add_u32_e32 v176, s61, v166
	ds_read_b128 v[128:131], v140
	ds_read_b128 v[132:135], v140 offset:1024
	ds_read_b128 v[136:139], v140 offset:2048
	ds_read_b128 v[140:143], v140 offset:3072
	ds_read_b128 v[158:161], v176
	ds_read_b128 v[162:165], v176 offset:1024
	ds_read_b128 v[172:175], v176 offset:2048
	ds_read_b128 v[176:179], v176 offset:3072
	s_add_u32 s58, s88, 0x40000
	s_addc_u32 s59, s89, 0
	s_mov_b32 m0, s31
	v_lshl_add_u64 v[226:227], s[58:59], 0, v[146:147]
	ds_read_b128 v[180:183], v170 offset:32768
	ds_read_b128 v[184:187], v170 offset:33792
	ds_read_b128 v[188:191], v170 offset:34816
	ds_read_b128 v[192:195], v170 offset:35840
	ds_read_b128 v[196:199], v170 offset:36864
	ds_read_b128 v[206:209], v170 offset:37888
	ds_read_b128 v[210:213], v170 offset:38912
	ds_read_b128 v[214:217], v170 offset:39936
	global_load_lds_dwordx4 v[226:227], off
	v_lshl_add_u64 v[226:227], s[58:59], 0, v[150:151]
	s_mov_b32 m0, s37
	s_nop 0
	global_load_lds_dwordx4 v[226:227], off
	s_waitcnt vmcnt(8)
	s_waitcnt lgkmcnt(0)
	s_barrier
	s_setprio 1
	s_waitcnt lgkmcnt(0)
	v_mfma_f32_16x16x32_bf16 v[124:127], v[128:131], v[180:183], v[124:127]
	v_mfma_f32_16x16x32_bf16 v[120:123], v[136:139], v[180:183], v[120:123]
	v_mfma_f32_16x16x32_bf16 v[104:107], v[136:139], v[188:191], v[104:107]
	v_mfma_f32_16x16x32_bf16 v[108:111], v[128:131], v[188:191], v[108:111]
	v_mfma_f32_16x16x32_bf16 v[96:99], v[128:131], v[196:199], v[96:99]
	v_mfma_f32_16x16x32_bf16 v[88:91], v[136:139], v[196:199], v[88:91]
	v_mfma_f32_16x16x32_bf16 v[72:75], v[136:139], v[210:213], v[72:75]
	v_mfma_f32_16x16x32_bf16 v[80:83], v[128:131], v[210:213], v[80:83]
	v_mfma_f32_16x16x32_bf16 v[124:127], v[132:135], v[184:187], v[124:127]
	v_mfma_f32_16x16x32_bf16 v[120:123], v[140:143], v[184:187], v[120:123]
	v_mfma_f32_16x16x32_bf16 v[104:107], v[140:143], v[192:195], v[104:107]
	v_mfma_f32_16x16x32_bf16 v[108:111], v[132:135], v[192:195], v[108:111]
	v_mfma_f32_16x16x32_bf16 v[96:99], v[132:135], v[206:209], v[96:99]
	v_mfma_f32_16x16x32_bf16 v[88:91], v[140:143], v[206:209], v[88:91]
	v_mfma_f32_16x16x32_bf16 v[72:75], v[140:143], v[214:217], v[72:75]
	v_mfma_f32_16x16x32_bf16 v[80:83], v[132:135], v[214:217], v[80:83]
	s_setprio 0
	s_setprio 1
	v_mfma_f32_16x16x32_bf16 v[116:119], v[158:161], v[180:183], v[116:119]
	v_mfma_f32_16x16x32_bf16 v[112:115], v[172:175], v[180:183], v[112:115]
	v_mfma_f32_16x16x32_bf16 v[92:95], v[172:175], v[188:191], v[92:95]
	v_mfma_f32_16x16x32_bf16 v[100:103], v[158:161], v[188:191], v[100:103]
	v_mfma_f32_16x16x32_bf16 v[84:87], v[158:161], v[196:199], v[84:87]
	v_mfma_f32_16x16x32_bf16 v[76:79], v[172:175], v[196:199], v[76:79]
	v_mfma_f32_16x16x32_bf16 v[64:67], v[172:175], v[210:213], v[64:67]
	v_mfma_f32_16x16x32_bf16 v[68:71], v[158:161], v[210:213], v[68:71]
	v_mfma_f32_16x16x32_bf16 v[116:119], v[162:165], v[184:187], v[116:119]
	v_mfma_f32_16x16x32_bf16 v[112:115], v[176:179], v[184:187], v[112:115]
	v_mfma_f32_16x16x32_bf16 v[92:95], v[176:179], v[192:195], v[92:95]
	v_mfma_f32_16x16x32_bf16 v[100:103], v[162:165], v[192:195], v[100:103]
	v_mfma_f32_16x16x32_bf16 v[84:87], v[162:165], v[206:209], v[84:87]
	v_mfma_f32_16x16x32_bf16 v[76:79], v[176:179], v[206:209], v[76:79]
	v_mfma_f32_16x16x32_bf16 v[64:67], v[176:179], v[214:217], v[64:67]
	v_mfma_f32_16x16x32_bf16 v[68:71], v[162:165], v[214:217], v[68:71]
	s_setprio 0
	s_barrier
; #define PG8_STAGE(bufoff, gbase, voff) do { _Pragma("unroll") for (int _i = 0; _i < 2; ++_i) \
;         __builtin_amdgcn_global_load_lds((const unsigned*)((const char*)(gbase) + (voff)[_i]), (PG8_LAS unsigned*)(lds + (bufoff) + ldsw + _i * 8192), 16, 0, 0); } while (0)
; #define PG8_LDA(dst, b, h) do { _Pragma("unroll") for (int m = 0; m < 4; ++m) _Pragma("unroll") for (int k = 0; k < 2; ++k) dst[m][k] = *(const PG8_LAS bf16x8*)(lds + PG8_SA(b, h) + aoff + m * 2048 + k * 1024); } while (0)
; #define PG8_MMA(ai, bj, At, Bt) do { __builtin_amdgcn_s_setprio(1); _Pragma("unroll") for (int m = 0; m < 4; ++m) _Pragma("unroll") for (int n = 0; n < 2; ++n) _Pragma("unroll") for (int k = 0; k < 2; ++k) \
;         acc[ai][bj][m][n] = __builtin_amdgcn_mfma_f32_16x16x32_bf16(Bt[n][k], At[m][k], acc[ai][bj][m][n], 0, 0, 0); __builtin_amdgcn_s_setprio(0); } while (0)
; #define PG8_WAIT_V(n) asm volatile("s_waitcnt vmcnt(" #n ")" ::: "memory")
; #define PG8_WAIT_L(n) asm volatile("s_waitcnt lgkmcnt(" #n ")" ::: "memory")
; #define PG8_BAR __builtin_amdgcn_s_barrier()
; #define PG8_SCHED __builtin_amdgcn_sched_barrier(0)
; template <class Epi, class Sched, bool ALIGN_EPI = false, bool SP2 = false>
; __device__ __forceinline__ void gemm_phase(PG8_LAS unsigned char* lds, const Gemm g, const Sched& S, const Epi& E) {
;     ...
;         for (int t = 0; t < nt; t += 2) {
;             const bool last = (t == nt - 2);
;             const char* a1 = cA + (size_t)(t + 1) * kstep;
;             const char* a2 = last ? nA : cA + (size_t)(t + 2) * kstep; const char* b2 = last ? nB : cB + (size_t)(t + 2) * kstep;
;             const char* a3 = a2 + kstep; const char* b3 = b2 + kstep;
;     ...
;             PG8_LDA(At, 1, 1); PG8_STAGE(PG8_SB(1, 0), b3, voffB); PG8_STAGE(PG8_SB(1, 1), b3 + hstep, voffB); PG8_STAGE(PG8_SA(1, 0), a3, voffA);
;             PG8_WAIT_V(8); PG8_WAIT_L(0); PG8_BAR; PG8_MMA(1, 0, At, B0); PG8_MMA(1, 1, At, B1); PG8_BAR; PG8_SCHED;
	s_add_i32 s58, s60, s28
	v_lshl_add_u64 v[218:219], v[218:219], 0, s[66:67]
	s_mov_b32 m0, s58
	ds_read_b128 v[180:183], v170 offset:49152
	ds_read_b128 v[184:187], v170 offset:50176
	ds_read_b128 v[188:191], v170 offset:51200
	ds_read_b128 v[192:195], v170 offset:52224
	ds_read_b128 v[196:199], v170 offset:53248
	ds_read_b128 v[206:209], v170 offset:54272
	ds_read_b128 v[210:213], v170 offset:55296
	ds_read_b128 v[214:217], v170 offset:56320
	global_load_lds_dwordx4 v[218:219], off
	s_add_i32 m0, s58, 0x2000
	s_add_u32 s58, s86, 0x40080
	v_lshl_add_u64 v[218:219], v[220:221], 0, s[66:67]
	s_addc_u32 s59, s87, 0
	s_add_i32 s60, s61, s28
	global_load_lds_dwordx4 v[218:219], off
	v_lshl_add_u64 v[218:219], s[58:59], 0, v[148:149]
	s_mov_b32 m0, s60
	s_nop 0
	global_load_lds_dwordx4 v[218:219], off
	v_lshl_add_u64 v[218:219], s[58:59], 0, v[152:153]
	s_add_i32 m0, s60, 0x2000
	s_nop 0
	global_load_lds_dwordx4 v[218:219], off
	v_lshl_add_u64 v[218:219], v[222:223], 0, s[66:67]
	s_mov_b32 m0, s2
	s_nop 0
	global_load_lds_dwordx4 v[218:219], off
	v_lshl_add_u64 v[218:219], v[224:225], 0, s[66:67]
	s_mov_b32 m0, s3
	s_nop 0
	global_load_lds_dwordx4 v[218:219], off
	s_waitcnt vmcnt(8)
	s_waitcnt lgkmcnt(0)
	s_barrier
	s_setprio 1
	s_waitcnt lgkmcnt(0)
	v_mfma_f32_16x16x32_bf16 v[60:63], v[128:131], v[180:183], v[60:63]
	v_mfma_f32_16x16x32_bf16 v[56:59], v[136:139], v[180:183], v[56:59]
	v_mfma_f32_16x16x32_bf16 v[40:43], v[136:139], v[188:191], v[40:43]
	v_mfma_f32_16x16x32_bf16 v[48:51], v[128:131], v[188:191], v[48:51]
	v_mfma_f32_16x16x32_bf16 v[32:35], v[128:131], v[196:199], v[32:35]
	v_mfma_f32_16x16x32_bf16 v[24:27], v[136:139], v[196:199], v[24:27]
	v_mfma_f32_16x16x32_bf16 v[8:11], v[136:139], v[210:213], v[8:11]
	v_mfma_f32_16x16x32_bf16 v[16:19], v[128:131], v[210:213], v[16:19]
	v_mfma_f32_16x16x32_bf16 v[60:63], v[132:135], v[184:187], v[60:63]
	v_mfma_f32_16x16x32_bf16 v[56:59], v[140:143], v[184:187], v[56:59]
	v_mfma_f32_16x16x32_bf16 v[40:43], v[140:143], v[192:195], v[40:43]
	v_mfma_f32_16x16x32_bf16 v[48:51], v[132:135], v[192:195], v[48:51]
	v_mfma_f32_16x16x32_bf16 v[32:35], v[132:135], v[206:209], v[32:35]
	v_mfma_f32_16x16x32_bf16 v[24:27], v[140:143], v[206:209], v[24:27]
	v_mfma_f32_16x16x32_bf16 v[8:11], v[140:143], v[214:217], v[8:11]
	v_mfma_f32_16x16x32_bf16 v[16:19], v[132:135], v[214:217], v[16:19]
	s_setprio 0
	s_setprio 1
	v_mfma_f32_16x16x32_bf16 v[52:55], v[158:161], v[180:183], v[52:55]
	v_mfma_f32_16x16x32_bf16 v[44:47], v[172:175], v[180:183], v[44:47]
	v_mfma_f32_16x16x32_bf16 v[28:31], v[172:175], v[188:191], v[28:31]
	v_mfma_f32_16x16x32_bf16 v[36:39], v[158:161], v[188:191], v[36:39]
	v_mfma_f32_16x16x32_bf16 v[20:23], v[158:161], v[196:199], v[20:23]
	v_mfma_f32_16x16x32_bf16 v[12:15], v[172:175], v[196:199], v[12:15]
	v_mfma_f32_16x16x32_bf16 v[0:3], v[172:175], v[210:213], v[0:3]
	v_mfma_f32_16x16x32_bf16 v[4:7], v[158:161], v[210:213], v[4:7]
	v_mfma_f32_16x16x32_bf16 v[52:55], v[162:165], v[184:187], v[52:55]
	v_mfma_f32_16x16x32_bf16 v[44:47], v[176:179], v[184:187], v[44:47]
	v_mfma_f32_16x16x32_bf16 v[28:31], v[176:179], v[192:195], v[28:31]
	v_mfma_f32_16x16x32_bf16 v[36:39], v[162:165], v[192:195], v[36:39]
	v_mfma_f32_16x16x32_bf16 v[20:23], v[162:165], v[206:209], v[20:23]
	v_mfma_f32_16x16x32_bf16 v[12:15], v[176:179], v[206:209], v[12:15]
	v_mfma_f32_16x16x32_bf16 v[0:3], v[176:179], v[214:217], v[0:3]
	v_mfma_f32_16x16x32_bf16 v[4:7], v[162:165], v[214:217], v[4:7]
	s_setprio 0
	s_barrier
	s_add_i32 s91, s91, 2
	s_add_u32 s84, s84, 0x100
	s_addc_u32 s85, s85, 0
	s_add_u32 s81, s81, 0x100
	s_addc_u32 s90, s90, 0
	s_cmp_gt_u32 s91, 13
	s_cbranch_scc0 .LBB0_582
	s_and_b64 vcc, exec, s[68:69]
	s_cbranch_vccz .LBB0_585
	s_barrier

; #define PG8_STAGE(bufoff, gbase, voff) do { _Pragma("unroll") for (int _i = 0; _i < 2; ++_i) \
;         __builtin_amdgcn_global_load_lds((const unsigned*)((const char*)(gbase) + (voff)[_i]), (PG8_LAS unsigned*)(lds + (bufoff) + ldsw + _i * 8192), 16, 0, 0); } while (0)
; #define PG8_LDA(dst, b, h) do { _Pragma("unroll") for (int m = 0; m < 4; ++m) _Pragma("unroll") for (int k = 0; k < 2; ++k) dst[m][k] = *(const PG8_LAS bf16x8*)(lds + PG8_SA(b, h) + aoff + m * 2048 + k * 1024); } while (0)
; #define PG8_LDB(dst, b, h) do { _Pragma("unroll") for (int n = 0; n < 2; ++n) _Pragma("unroll") for (int k = 0; k < 2; ++k) dst[n][k] = *(const PG8_LAS bf16x8*)(lds + PG8_SB(b, h) + boff + n * 2048 + k * 1024); } while (0)
; #define PG8_MMA(ai, bj, At, Bt) do { __builtin_amdgcn_s_setprio(1); _Pragma("unroll") for (int m = 0; m < 4; ++m) _Pragma("unroll") for (int n = 0; n < 2; ++n) _Pragma("unroll") for (int k = 0; k < 2; ++k) \
;         acc[ai][bj][m][n] = __builtin_amdgcn_mfma_f32_16x16x32_bf16(Bt[n][k], At[m][k], acc[ai][bj][m][n], 0, 0, 0); __builtin_amdgcn_s_setprio(0); } while (0)
; #define PG8_WAIT_V(n) asm volatile("s_waitcnt vmcnt(" #n ")" ::: "memory")
; #define PG8_WAIT_L(n) asm volatile("s_waitcnt lgkmcnt(" #n ")" ::: "memory")
; #define PG8_BAR __builtin_amdgcn_s_barrier()
; #define PG8_SCHED __builtin_amdgcn_sched_barrier(0)
; template <class Epi, class Sched, bool ALIGN_EPI = false, bool SP2 = false>
; __device__ __forceinline__ void gemm_phase(PG8_LAS unsigned char* lds, const Gemm g, const Sched& S, const Epi& E) {
;     ...
;             PG8_LDB(B0, 0, 0); PG8_LDB(B1, 0, 1); PG8_SCHED; PG8_LDA(At, 0, 0); PG8_STAGE(PG8_SA(1, 1), a1 + hstep, voffA);
;             PG8_WAIT_V(8); PG8_WAIT_L(0); PG8_BAR; PG8_MMA(0, 0, At, B0); PG8_MMA(0, 1, At, B1); PG8_BAR; PG8_SCHED;
;             PG8_LDA(At, 0, 1); PG8_STAGE(PG8_SB(0, 0), b2, voffB); PG8_STAGE(PG8_SB(0, 1), b2 + hstep, voffB); PG8_STAGE(PG8_SA(0, 0), a2, voffA);
.LBB0_660:
	ds_read_b128 v[140:143], v190
	ds_read_b128 v[146:149], v190 offset:1024
	ds_read_b128 v[150:153], v190 offset:2048
	ds_read_b128 v[154:157], v190 offset:3072
	ds_read_b128 v[158:161], v191
	ds_read_b128 v[162:165], v191 offset:1024
	ds_read_b128 v[166:169], v191 offset:2048
	ds_read_b128 v[170:173], v191 offset:3072
	s_add_u32 s58, s80, 0xfffc0080
	s_addc_u32 s59, s81, -1
	s_cmp_eq_u32 s90, 12
	s_cselect_b32 s85, s5, s59
	s_cselect_b32 s84, s71, s58
	s_cselect_b32 s83, s73, s89
	s_cselect_b32 s82, s87, s88
	v_lshl_add_u64 v[186:187], s[80:81], 0, v[136:137]
	s_add_i32 m0, s20, 0xc000
	ds_read_b128 v[174:177], v192
	ds_read_b128 v[178:181], v192 offset:1024
	ds_read_b128 v[182:185], v192 offset:2048
	ds_read_b128 v[194:197], v192 offset:3072
	ds_read_b128 v[206:209], v192 offset:4096
	ds_read_b128 v[210:213], v192 offset:5120
	ds_read_b128 v[214:217], v192 offset:6144
	ds_read_b128 v[218:221], v192 offset:7168
	global_load_lds_dwordx4 v[186:187], off
	v_lshl_add_u64 v[186:187], s[80:81], 0, v[138:139]
	s_add_i32 m0, s20, 0xe000
	s_nop 0
	global_load_lds_dwordx4 v[186:187], off
	s_waitcnt vmcnt(8)
	s_waitcnt lgkmcnt(0)
	s_barrier
	s_setprio 1
	s_waitcnt lgkmcnt(0)
	v_mfma_f32_16x16x32_bf16 v[124:127], v[140:143], v[174:177], v[124:127]
	v_mfma_f32_16x16x32_bf16 v[120:123], v[150:153], v[174:177], v[120:123]
	v_mfma_f32_16x16x32_bf16 v[104:107], v[150:153], v[182:185], v[104:107]
	v_mfma_f32_16x16x32_bf16 v[108:111], v[140:143], v[182:185], v[108:111]
	v_mfma_f32_16x16x32_bf16 v[92:95], v[140:143], v[206:209], v[92:95]
	v_mfma_f32_16x16x32_bf16 v[88:91], v[150:153], v[206:209], v[88:91]
	v_mfma_f32_16x16x32_bf16 v[72:75], v[150:153], v[214:217], v[72:75]
	v_mfma_f32_16x16x32_bf16 v[76:79], v[140:143], v[214:217], v[76:79]
	v_mfma_f32_16x16x32_bf16 v[124:127], v[146:149], v[178:181], v[124:127]
	v_mfma_f32_16x16x32_bf16 v[120:123], v[154:157], v[178:181], v[120:123]
	v_mfma_f32_16x16x32_bf16 v[104:107], v[154:157], v[194:197], v[104:107]
	v_mfma_f32_16x16x32_bf16 v[108:111], v[146:149], v[194:197], v[108:111]
	v_mfma_f32_16x16x32_bf16 v[92:95], v[146:149], v[210:213], v[92:95]
	v_mfma_f32_16x16x32_bf16 v[88:91], v[154:157], v[210:213], v[88:91]
	v_mfma_f32_16x16x32_bf16 v[72:75], v[154:157], v[218:221], v[72:75]
	v_mfma_f32_16x16x32_bf16 v[76:79], v[146:149], v[218:221], v[76:79]
	s_setprio 0
	s_setprio 1
	v_mfma_f32_16x16x32_bf16 v[116:119], v[158:161], v[174:177], v[116:119]
	v_mfma_f32_16x16x32_bf16 v[112:115], v[166:169], v[174:177], v[112:115]
	v_mfma_f32_16x16x32_bf16 v[96:99], v[166:169], v[182:185], v[96:99]
	v_mfma_f32_16x16x32_bf16 v[100:103], v[158:161], v[182:185], v[100:103]
	v_mfma_f32_16x16x32_bf16 v[84:87], v[158:161], v[206:209], v[84:87]
	v_mfma_f32_16x16x32_bf16 v[80:83], v[166:169], v[206:209], v[80:83]
	v_mfma_f32_16x16x32_bf16 v[64:67], v[166:169], v[214:217], v[64:67]
	v_mfma_f32_16x16x32_bf16 v[68:71], v[158:161], v[214:217], v[68:71]
	v_mfma_f32_16x16x32_bf16 v[116:119], v[162:165], v[178:181], v[116:119]
	v_mfma_f32_16x16x32_bf16 v[112:115], v[170:173], v[178:181], v[112:115]
	v_mfma_f32_16x16x32_bf16 v[96:99], v[170:173], v[194:197], v[96:99]
	v_mfma_f32_16x16x32_bf16 v[100:103], v[162:165], v[194:197], v[100:103]
	v_mfma_f32_16x16x32_bf16 v[84:87], v[162:165], v[210:213], v[84:87]
	v_mfma_f32_16x16x32_bf16 v[80:83], v[170:173], v[210:213], v[80:83]
	v_mfma_f32_16x16x32_bf16 v[64:67], v[170:173], v[218:221], v[64:67]
	v_mfma_f32_16x16x32_bf16 v[68:71], v[162:165], v[218:221], v[68:71]
	s_setprio 0
	s_barrier
	s_add_i32 s58, s39, s11
	v_lshl_add_u64 v[186:187], s[82:83], 0, v[132:133]
	s_mov_b32 m0, s58
	ds_read_b128 v[174:177], v192 offset:16384
	ds_read_b128 v[178:181], v192 offset:17408
	ds_read_b128 v[182:185], v192 offset:18432
	ds_read_b128 v[194:197], v192 offset:19456
	ds_read_b128 v[206:209], v192 offset:20480
	ds_read_b128 v[210:213], v192 offset:21504
	ds_read_b128 v[214:217], v192 offset:22528
	ds_read_b128 v[218:221], v192 offset:23552
	global_load_lds_dwordx4 v[186:187], off
	s_add_i32 m0, s58, 0x2000
	s_add_u32 s58, s82, 0x40000
	v_lshl_add_u64 v[198:199], s[82:83], 0, v[128:129]
	s_addc_u32 s59, s83, 0
	s_add_i32 s60, s56, s11
	global_load_lds_dwordx4 v[198:199], off
	v_lshl_add_u64 v[222:223], s[58:59], 0, v[132:133]
	s_mov_b32 m0, s60
	v_lshl_add_u64 v[224:225], s[84:85], 0, v[130:131]
	global_load_lds_dwordx4 v[222:223], off
	v_lshl_add_u64 v[222:223], s[58:59], 0, v[128:129]
	s_add_i32 m0, s60, 0x2000
	s_nop 0
	global_load_lds_dwordx4 v[222:223], off
	v_lshl_add_u64 v[222:223], s[84:85], 0, v[134:135]
	s_mov_b32 m0, s20
	s_nop 0
	global_load_lds_dwordx4 v[222:223], off
	s_mov_b32 m0, s21
	s_nop 0
	global_load_lds_dwordx4 v[224:225], off
	s_waitcnt vmcnt(8)
	s_waitcnt lgkmcnt(0)
	s_barrier
; #define PG8_STAGE(bufoff, gbase, voff) do { _Pragma("unroll") for (int _i = 0; _i < 2; ++_i) \
;         __builtin_amdgcn_global_load_lds((const unsigned*)((const char*)(gbase) + (voff)[_i]), (PG8_LAS unsigned*)(lds + (bufoff) + ldsw + _i * 8192), 16, 0, 0); } while (0)
; #define PG8_LDA(dst, b, h) do { _Pragma("unroll") for (int m = 0; m < 4; ++m) _Pragma("unroll") for (int k = 0; k < 2; ++k) dst[m][k] = *(const PG8_LAS bf16x8*)(lds + PG8_SA(b, h) + aoff + m * 2048 + k * 1024); } while (0)
; #define PG8_LDB(dst, b, h) do { _Pragma("unroll") for (int n = 0; n < 2; ++n) _Pragma("unroll") for (int k = 0; k < 2; ++k) dst[n][k] = *(const PG8_LAS bf16x8*)(lds + PG8_SB(b, h) + boff + n * 2048 + k * 1024); } while (0)
; #define PG8_MMA(ai, bj, At, Bt) do { __builtin_amdgcn_s_setprio(1); _Pragma("unroll") for (int m = 0; m < 4; ++m) _Pragma("unroll") for (int n = 0; n < 2; ++n) _Pragma("unroll") for (int k = 0; k < 2; ++k) \
;         acc[ai][bj][m][n] = __builtin_amdgcn_mfma_f32_16x16x32_bf16(Bt[n][k], At[m][k], acc[ai][bj][m][n], 0, 0, 0); __builtin_amdgcn_s_setprio(0); } while (0)
; #define PG8_WAIT_V(n) asm volatile("s_waitcnt vmcnt(" #n ")" ::: "memory")
; #define PG8_WAIT_L(n) asm volatile("s_waitcnt lgkmcnt(" #n ")" ::: "memory")
; #define PG8_BAR __builtin_amdgcn_s_barrier()
; #define PG8_SCHED __builtin_amdgcn_sched_barrier(0)
; template <class Epi, class Sched, bool ALIGN_EPI = false, bool SP2 = false>
; __device__ __forceinline__ void gemm_phase(PG8_LAS unsigned char* lds, const Gemm g, const Sched& S, const Epi& E) {
;     ...
;             PG8_WAIT_V(8); PG8_WAIT_L(0); PG8_BAR; PG8_MMA(1, 0, At, B0); PG8_MMA(1, 1, At, B1); PG8_BAR; PG8_SCHED;
;             PG8_LDB(B0, 1, 0); PG8_LDB(B1, 1, 1); PG8_SCHED; PG8_LDA(At, 1, 0); PG8_STAGE(PG8_SA(0, 1), a2 + hstep, voffA);
;             PG8_WAIT_V(8); PG8_WAIT_L(0); PG8_BAR; PG8_MMA(0, 0, At, B0); PG8_MMA(0, 1, At, B1); PG8_BAR; PG8_SCHED;
	s_setprio 1
	s_waitcnt lgkmcnt(0)
	v_mfma_f32_16x16x32_bf16 v[60:63], v[140:143], v[174:177], v[60:63]
	v_mfma_f32_16x16x32_bf16 v[56:59], v[150:153], v[174:177], v[56:59]
	v_mfma_f32_16x16x32_bf16 v[40:43], v[150:153], v[182:185], v[40:43]
	v_mfma_f32_16x16x32_bf16 v[44:47], v[140:143], v[182:185], v[44:47]
	v_mfma_f32_16x16x32_bf16 v[28:31], v[140:143], v[206:209], v[28:31]
	v_mfma_f32_16x16x32_bf16 v[24:27], v[150:153], v[206:209], v[24:27]
	v_mfma_f32_16x16x32_bf16 v[8:11], v[150:153], v[214:217], v[8:11]
	v_mfma_f32_16x16x32_bf16 v[12:15], v[140:143], v[214:217], v[12:15]
	v_mfma_f32_16x16x32_bf16 v[60:63], v[146:149], v[178:181], v[60:63]
	v_mfma_f32_16x16x32_bf16 v[56:59], v[154:157], v[178:181], v[56:59]
	v_mfma_f32_16x16x32_bf16 v[40:43], v[154:157], v[194:197], v[40:43]
	v_mfma_f32_16x16x32_bf16 v[44:47], v[146:149], v[194:197], v[44:47]
	v_mfma_f32_16x16x32_bf16 v[28:31], v[146:149], v[210:213], v[28:31]
	v_mfma_f32_16x16x32_bf16 v[24:27], v[154:157], v[210:213], v[24:27]
	v_mfma_f32_16x16x32_bf16 v[8:11], v[154:157], v[218:221], v[8:11]
	v_mfma_f32_16x16x32_bf16 v[12:15], v[146:149], v[218:221], v[12:15]
	s_setprio 0
	s_setprio 1
	v_mfma_f32_16x16x32_bf16 v[52:55], v[158:161], v[174:177], v[52:55]
	v_mfma_f32_16x16x32_bf16 v[48:51], v[166:169], v[174:177], v[48:51]
	v_mfma_f32_16x16x32_bf16 v[32:35], v[166:169], v[182:185], v[32:35]
	v_mfma_f32_16x16x32_bf16 v[36:39], v[158:161], v[182:185], v[36:39]
	v_mfma_f32_16x16x32_bf16 v[20:23], v[158:161], v[206:209], v[20:23]
	v_mfma_f32_16x16x32_bf16 v[16:19], v[166:169], v[206:209], v[16:19]
	v_mfma_f32_16x16x32_bf16 v[0:3], v[166:169], v[214:217], v[0:3]
	v_mfma_f32_16x16x32_bf16 v[4:7], v[158:161], v[214:217], v[4:7]
	v_mfma_f32_16x16x32_bf16 v[52:55], v[162:165], v[178:181], v[52:55]
	v_mfma_f32_16x16x32_bf16 v[48:51], v[170:173], v[178:181], v[48:51]
	v_mfma_f32_16x16x32_bf16 v[32:35], v[170:173], v[194:197], v[32:35]
	v_mfma_f32_16x16x32_bf16 v[36:39], v[162:165], v[194:197], v[36:39]
	v_mfma_f32_16x16x32_bf16 v[20:23], v[162:165], v[210:213], v[20:23]
	v_mfma_f32_16x16x32_bf16 v[16:19], v[170:173], v[210:213], v[16:19]
	v_mfma_f32_16x16x32_bf16 v[0:3], v[170:173], v[218:221], v[0:3]
	v_mfma_f32_16x16x32_bf16 v[4:7], v[162:165], v[218:221], v[4:7]
	s_setprio 0
	s_barrier
	s_add_i32 s60, 0, 0x18000
	s_add_i32 s61, 0, 0x1c000
	v_add_u32_e32 v154, s60, v188
	v_add_u32_e32 v170, s61, v188
	ds_read_b128 v[140:143], v154
	ds_read_b128 v[146:149], v154 offset:1024
	ds_read_b128 v[150:153], v154 offset:2048
	ds_read_b128 v[154:157], v154 offset:3072
	ds_read_b128 v[158:161], v170
	ds_read_b128 v[162:165], v170 offset:1024
	ds_read_b128 v[166:169], v170 offset:2048
	ds_read_b128 v[170:173], v170 offset:3072
	s_add_u32 s58, s84, 0x40000
	s_addc_u32 s59, s85, 0
	s_mov_b32 m0, s28
	v_lshl_add_u64 v[226:227], s[58:59], 0, v[134:135]
	ds_read_b128 v[174:177], v192 offset:32768
	ds_read_b128 v[178:181], v192 offset:33792
	ds_read_b128 v[182:185], v192 offset:34816
	ds_read_b128 v[194:197], v192 offset:35840
	ds_read_b128 v[206:209], v192 offset:36864
	ds_read_b128 v[210:213], v192 offset:37888
	ds_read_b128 v[214:217], v192 offset:38912
	ds_read_b128 v[218:221], v192 offset:39936
	global_load_lds_dwordx4 v[226:227], off
	v_lshl_add_u64 v[226:227], s[58:59], 0, v[130:131]
	s_mov_b32 m0, s29
	s_nop 0
	global_load_lds_dwordx4 v[226:227], off
	s_waitcnt vmcnt(8)
	s_waitcnt lgkmcnt(0)
	s_barrier
	s_setprio 1
	s_waitcnt lgkmcnt(0)
	v_mfma_f32_16x16x32_bf16 v[124:127], v[140:143], v[174:177], v[124:127]
	v_mfma_f32_16x16x32_bf16 v[120:123], v[150:153], v[174:177], v[120:123]
	v_mfma_f32_16x16x32_bf16 v[104:107], v[150:153], v[182:185], v[104:107]
	v_mfma_f32_16x16x32_bf16 v[108:111], v[140:143], v[182:185], v[108:111]
	v_mfma_f32_16x16x32_bf16 v[92:95], v[140:143], v[206:209], v[92:95]
	v_mfma_f32_16x16x32_bf16 v[88:91], v[150:153], v[206:209], v[88:91]
	v_mfma_f32_16x16x32_bf16 v[72:75], v[150:153], v[214:217], v[72:75]
	v_mfma_f32_16x16x32_bf16 v[76:79], v[140:143], v[214:217], v[76:79]
	v_mfma_f32_16x16x32_bf16 v[124:127], v[146:149], v[178:181], v[124:127]
	v_mfma_f32_16x16x32_bf16 v[120:123], v[154:157], v[178:181], v[120:123]
	v_mfma_f32_16x16x32_bf16 v[104:107], v[154:157], v[194:197], v[104:107]
	v_mfma_f32_16x16x32_bf16 v[108:111], v[146:149], v[194:197], v[108:111]
	v_mfma_f32_16x16x32_bf16 v[92:95], v[146:149], v[210:213], v[92:95]
	v_mfma_f32_16x16x32_bf16 v[88:91], v[154:157], v[210:213], v[88:91]
	v_mfma_f32_16x16x32_bf16 v[72:75], v[154:157], v[218:221], v[72:75]
	v_mfma_f32_16x16x32_bf16 v[76:79], v[146:149], v[218:221], v[76:79]
	s_setprio 0
	s_setprio 1
	v_mfma_f32_16x16x32_bf16 v[116:119], v[158:161], v[174:177], v[116:119]
	v_mfma_f32_16x16x32_bf16 v[112:115], v[166:169], v[174:177], v[112:115]
	v_mfma_f32_16x16x32_bf16 v[96:99], v[166:169], v[182:185], v[96:99]
	v_mfma_f32_16x16x32_bf16 v[100:103], v[158:161], v[182:185], v[100:103]
	v_mfma_f32_16x16x32_bf16 v[84:87], v[158:161], v[206:209], v[84:87]
	v_mfma_f32_16x16x32_bf16 v[80:83], v[166:169], v[206:209], v[80:83]
	v_mfma_f32_16x16x32_bf16 v[64:67], v[166:169], v[214:217], v[64:67]
	v_mfma_f32_16x16x32_bf16 v[68:71], v[158:161], v[214:217], v[68:71]
	v_mfma_f32_16x16x32_bf16 v[116:119], v[162:165], v[178:181], v[116:119]
	v_mfma_f32_16x16x32_bf16 v[112:115], v[170:173], v[178:181], v[112:115]
	v_mfma_f32_16x16x32_bf16 v[96:99], v[170:173], v[194:197], v[96:99]
	v_mfma_f32_16x16x32_bf16 v[100:103], v[162:165], v[194:197], v[100:103]
	v_mfma_f32_16x16x32_bf16 v[84:87], v[162:165], v[210:213], v[84:87]
	v_mfma_f32_16x16x32_bf16 v[80:83], v[170:173], v[210:213], v[80:83]
	v_mfma_f32_16x16x32_bf16 v[64:67], v[170:173], v[218:221], v[64:67]
	v_mfma_f32_16x16x32_bf16 v[68:71], v[162:165], v[218:221], v[68:71]
	s_setprio 0
	s_barrier
; #define PG8_STAGE(bufoff, gbase, voff) do { _Pragma("unroll") for (int _i = 0; _i < 2; ++_i) \
;         __builtin_amdgcn_global_load_lds((const unsigned*)((const char*)(gbase) + (voff)[_i]), (PG8_LAS unsigned*)(lds + (bufoff) + ldsw + _i * 8192), 16, 0, 0); } while (0)
; #define PG8_LDA(dst, b, h) do { _Pragma("unroll") for (int m = 0; m < 4; ++m) _Pragma("unroll") for (int k = 0; k < 2; ++k) dst[m][k] = *(const PG8_LAS bf16x8*)(lds + PG8_SA(b, h) + aoff + m * 2048 + k * 1024); } while (0)
; #define PG8_MMA(ai, bj, At, Bt) do { __builtin_amdgcn_s_setprio(1); _Pragma("unroll") for (int m = 0; m < 4; ++m) _Pragma("unroll") for (int n = 0; n < 2; ++n) _Pragma("unroll") for (int k = 0; k < 2; ++k) \
;         acc[ai][bj][m][n] = __builtin_amdgcn_mfma_f32_16x16x32_bf16(Bt[n][k], At[m][k], acc[ai][bj][m][n], 0, 0, 0); __builtin_amdgcn_s_setprio(0); } while (0)
; #define PG8_WAIT_V(n) asm volatile("s_waitcnt vmcnt(" #n ")" ::: "memory")
; #define PG8_WAIT_L(n) asm volatile("s_waitcnt lgkmcnt(" #n ")" ::: "memory")
; #define PG8_BAR __builtin_amdgcn_s_barrier()
; #define PG8_SCHED __builtin_amdgcn_sched_barrier(0)
; template <class Epi, class Sched, bool ALIGN_EPI = false, bool SP2 = false>
; __device__ __forceinline__ void gemm_phase(PG8_LAS unsigned char* lds, const Gemm g, const Sched& S, const Epi& E) {
;     ...
;         for (int t = 0; t < nt; t += 2) {
;             const bool last = (t == nt - 2);
;             const char* a1 = cA + (size_t)(t + 1) * kstep;
;             const char* a2 = last ? nA : cA + (size_t)(t + 2) * kstep; const char* b2 = last ? nB : cB + (size_t)(t + 2) * kstep;
;             const char* a3 = a2 + kstep; const char* b3 = b2 + kstep;
;     ...
;             PG8_LDA(At, 1, 1); PG8_STAGE(PG8_SB(1, 0), b3, voffB); PG8_STAGE(PG8_SB(1, 1), b3 + hstep, voffB); PG8_STAGE(PG8_SA(1, 0), a3, voffA);
;             PG8_WAIT_V(8); PG8_WAIT_L(0); PG8_BAR; PG8_MMA(1, 0, At, B0); PG8_MMA(1, 1, At, B1); PG8_BAR; PG8_SCHED;
	s_add_i32 s58, s60, s11
	v_lshl_add_u64 v[186:187], v[186:187], 0, s[66:67]
	s_mov_b32 m0, s58
	ds_read_b128 v[174:177], v192 offset:49152
	ds_read_b128 v[178:181], v192 offset:50176
	ds_read_b128 v[182:185], v192 offset:51200
	ds_read_b128 v[194:197], v192 offset:52224
	ds_read_b128 v[206:209], v192 offset:53248
	ds_read_b128 v[210:213], v192 offset:54272
	ds_read_b128 v[214:217], v192 offset:55296
	ds_read_b128 v[218:221], v192 offset:56320
	global_load_lds_dwordx4 v[186:187], off
	s_add_i32 m0, s58, 0x2000
	s_add_u32 s58, s82, 0x40080
	v_lshl_add_u64 v[186:187], v[198:199], 0, s[66:67]
	s_addc_u32 s59, s83, 0
	s_add_i32 s60, s61, s11
	global_load_lds_dwordx4 v[186:187], off
	v_lshl_add_u64 v[186:187], s[58:59], 0, v[132:133]
	s_mov_b32 m0, s60
	s_nop 0
	global_load_lds_dwordx4 v[186:187], off
	v_lshl_add_u64 v[186:187], s[58:59], 0, v[128:129]
	s_add_i32 m0, s60, 0x2000
	s_nop 0
	global_load_lds_dwordx4 v[186:187], off
	v_lshl_add_u64 v[186:187], v[222:223], 0, s[66:67]
	s_mov_b32 m0, s31
	s_nop 0
	global_load_lds_dwordx4 v[186:187], off
	v_lshl_add_u64 v[186:187], v[224:225], 0, s[66:67]
	s_mov_b32 m0, s37
	s_nop 0
	global_load_lds_dwordx4 v[186:187], off
	s_waitcnt vmcnt(8)
	s_waitcnt lgkmcnt(0)
	s_barrier
	s_setprio 1
	s_waitcnt lgkmcnt(0)
	v_mfma_f32_16x16x32_bf16 v[60:63], v[140:143], v[174:177], v[60:63]
	v_mfma_f32_16x16x32_bf16 v[56:59], v[150:153], v[174:177], v[56:59]
	v_mfma_f32_16x16x32_bf16 v[40:43], v[150:153], v[182:185], v[40:43]
	v_mfma_f32_16x16x32_bf16 v[44:47], v[140:143], v[182:185], v[44:47]
	v_mfma_f32_16x16x32_bf16 v[28:31], v[140:143], v[206:209], v[28:31]
	v_mfma_f32_16x16x32_bf16 v[24:27], v[150:153], v[206:209], v[24:27]
	v_mfma_f32_16x16x32_bf16 v[8:11], v[150:153], v[214:217], v[8:11]
	v_mfma_f32_16x16x32_bf16 v[12:15], v[140:143], v[214:217], v[12:15]
	v_mfma_f32_16x16x32_bf16 v[60:63], v[146:149], v[178:181], v[60:63]
	v_mfma_f32_16x16x32_bf16 v[56:59], v[154:157], v[178:181], v[56:59]
	v_mfma_f32_16x16x32_bf16 v[40:43], v[154:157], v[194:197], v[40:43]
	v_mfma_f32_16x16x32_bf16 v[44:47], v[146:149], v[194:197], v[44:47]
	v_mfma_f32_16x16x32_bf16 v[28:31], v[146:149], v[210:213], v[28:31]
	v_mfma_f32_16x16x32_bf16 v[24:27], v[154:157], v[210:213], v[24:27]
	v_mfma_f32_16x16x32_bf16 v[8:11], v[154:157], v[218:221], v[8:11]
	v_mfma_f32_16x16x32_bf16 v[12:15], v[146:149], v[218:221], v[12:15]
	s_setprio 0
	s_setprio 1
	v_mfma_f32_16x16x32_bf16 v[52:55], v[158:161], v[174:177], v[52:55]
	v_mfma_f32_16x16x32_bf16 v[48:51], v[166:169], v[174:177], v[48:51]
	v_mfma_f32_16x16x32_bf16 v[32:35], v[166:169], v[182:185], v[32:35]
	v_mfma_f32_16x16x32_bf16 v[36:39], v[158:161], v[182:185], v[36:39]
	v_mfma_f32_16x16x32_bf16 v[20:23], v[158:161], v[206:209], v[20:23]
	v_mfma_f32_16x16x32_bf16 v[16:19], v[166:169], v[206:209], v[16:19]
	v_mfma_f32_16x16x32_bf16 v[0:3], v[166:169], v[214:217], v[0:3]
	v_mfma_f32_16x16x32_bf16 v[4:7], v[158:161], v[214:217], v[4:7]
	v_mfma_f32_16x16x32_bf16 v[52:55], v[162:165], v[178:181], v[52:55]
	v_mfma_f32_16x16x32_bf16 v[48:51], v[170:173], v[178:181], v[48:51]
	v_mfma_f32_16x16x32_bf16 v[32:35], v[170:173], v[194:197], v[32:35]
	v_mfma_f32_16x16x32_bf16 v[36:39], v[162:165], v[194:197], v[36:39]
	v_mfma_f32_16x16x32_bf16 v[20:23], v[162:165], v[210:213], v[20:23]
	v_mfma_f32_16x16x32_bf16 v[16:19], v[170:173], v[210:213], v[16:19]
	v_mfma_f32_16x16x32_bf16 v[0:3], v[170:173], v[218:221], v[0:3]
	v_mfma_f32_16x16x32_bf16 v[4:7], v[162:165], v[218:221], v[4:7]
	s_setprio 0
	s_barrier
	s_add_i32 s90, s90, 2
	s_add_u32 s80, s80, 0x100
	s_addc_u32 s81, s81, 0
	s_add_u32 s88, s88, 0x100
	s_addc_u32 s89, s89, 0
	s_cmp_gt_u32 s90, 13
	s_cbranch_scc0 .LBB0_660
	s_and_b64 vcc, exec, s[68:69]
	s_cbranch_vccz .LBB0_663
	s_barrier

; #define PG8_STAGE(bufoff, gbase, voff) do { _Pragma("unroll") for (int _i = 0; _i < 2; ++_i) \
;         __builtin_amdgcn_global_load_lds((const unsigned*)((const char*)(gbase) + (voff)[_i]), (PG8_LAS unsigned*)(lds + (bufoff) + ldsw + _i * 8192), 16, 0, 0); } while (0)
; #define PG8_LDA(dst, b, h) do { _Pragma("unroll") for (int m = 0; m < 4; ++m) _Pragma("unroll") for (int k = 0; k < 2; ++k) dst[m][k] = *(const PG8_LAS bf16x8*)(lds + PG8_SA(b, h) + aoff + m * 2048 + k * 1024); } while (0)
; #define PG8_LDB(dst, b, h) do { _Pragma("unroll") for (int n = 0; n < 2; ++n) _Pragma("unroll") for (int k = 0; k < 2; ++k) dst[n][k] = *(const PG8_LAS bf16x8*)(lds + PG8_SB(b, h) + boff + n * 2048 + k * 1024); } while (0)
; #define PG8_MMA(ai, bj, At, Bt) do { __builtin_amdgcn_s_setprio(1); _Pragma("unroll") for (int m = 0; m < 4; ++m) _Pragma("unroll") for (int n = 0; n < 2; ++n) _Pragma("unroll") for (int k = 0; k < 2; ++k) \
;         acc[ai][bj][m][n] = __builtin_amdgcn_mfma_f32_16x16x32_bf16(Bt[n][k], At[m][k], acc[ai][bj][m][n], 0, 0, 0); __builtin_amdgcn_s_setprio(0); } while (0)
; #define PG8_WAIT_V(n) asm volatile("s_waitcnt vmcnt(" #n ")" ::: "memory")
; #define PG8_WAIT_L(n) asm volatile("s_waitcnt lgkmcnt(" #n ")" ::: "memory")
; #define PG8_BAR __builtin_amdgcn_s_barrier()
; #define PG8_SCHED __builtin_amdgcn_sched_barrier(0)
; template <class Epi, class Sched, bool ALIGN_EPI = false, bool SP2 = false>
; __device__ __forceinline__ void gemm_phase(PG8_LAS unsigned char* lds, const Gemm g, const Sched& S, const Epi& E) {
;     ...
;             PG8_LDB(B0, 0, 0); PG8_LDB(B1, 0, 1); PG8_SCHED; PG8_LDA(At, 0, 0); PG8_STAGE(PG8_SA(1, 1), a1 + hstep, voffA);
;             PG8_WAIT_V(8); PG8_WAIT_L(0); PG8_BAR; PG8_MMA(0, 0, At, B0); PG8_MMA(0, 1, At, B1); PG8_BAR; PG8_SCHED;
;             PG8_LDA(At, 0, 1); PG8_STAGE(PG8_SB(0, 0), b2, voffB); PG8_STAGE(PG8_SB(0, 1), b2 + hstep, voffB); PG8_STAGE(PG8_SA(0, 0), a2, voffA);
.LBB0_730:
	ds_read_b128 v[128:131], v167
	ds_read_b128 v[132:135], v167 offset:1024
	ds_read_b128 v[136:139], v167 offset:2048
	ds_read_b128 v[140:143], v167 offset:3072
	ds_read_b128 v[158:161], v168
	ds_read_b128 v[162:165], v168 offset:1024
	ds_read_b128 v[174:177], v168 offset:2048
	ds_read_b128 v[178:181], v168 offset:3072
	s_add_u32 s60, s76, 0xfff50080
	s_addc_u32 s61, s77, -1
	s_cmp_eq_u32 s59, 40
	s_cselect_b32 s81, s73, s61
	s_cselect_b32 s80, s72, s60
	s_cselect_b32 s79, s75, s58
	s_cselect_b32 s78, s74, s57
	s_mov_b32 m0, s84
	v_lshl_add_u64 v[198:199], s[76:77], 0, v[154:155]
	ds_read_b128 v[182:185], v169
	ds_read_b128 v[186:189], v169 offset:1024
	ds_read_b128 v[190:193], v169 offset:2048
	ds_read_b128 v[194:197], v169 offset:3072
	ds_read_b128 v[206:209], v169 offset:4096
	ds_read_b128 v[210:213], v169 offset:5120
	ds_read_b128 v[214:217], v169 offset:6144
	ds_read_b128 v[218:221], v169 offset:7168
	global_load_lds_dwordx4 v[198:199], off
	v_lshl_add_u64 v[198:199], s[76:77], 0, v[156:157]
	s_mov_b32 m0, s85
	s_nop 0
	global_load_lds_dwordx4 v[198:199], off
	s_waitcnt vmcnt(8)
	s_waitcnt lgkmcnt(0)
	s_barrier
	s_setprio 1
	s_waitcnt lgkmcnt(0)
	v_mfma_f32_16x16x32_bf16 v[124:127], v[128:131], v[182:185], v[124:127]
	v_mfma_f32_16x16x32_bf16 v[120:123], v[136:139], v[182:185], v[120:123]
	v_mfma_f32_16x16x32_bf16 v[104:107], v[136:139], v[190:193], v[104:107]
	v_mfma_f32_16x16x32_bf16 v[108:111], v[128:131], v[190:193], v[108:111]
	v_mfma_f32_16x16x32_bf16 v[92:95], v[128:131], v[206:209], v[92:95]
	v_mfma_f32_16x16x32_bf16 v[88:91], v[136:139], v[206:209], v[88:91]
	v_mfma_f32_16x16x32_bf16 v[72:75], v[136:139], v[214:217], v[72:75]
	v_mfma_f32_16x16x32_bf16 v[76:79], v[128:131], v[214:217], v[76:79]
	v_mfma_f32_16x16x32_bf16 v[124:127], v[132:135], v[186:189], v[124:127]
	v_mfma_f32_16x16x32_bf16 v[120:123], v[140:143], v[186:189], v[120:123]
	v_mfma_f32_16x16x32_bf16 v[104:107], v[140:143], v[194:197], v[104:107]
	v_mfma_f32_16x16x32_bf16 v[108:111], v[132:135], v[194:197], v[108:111]
	v_mfma_f32_16x16x32_bf16 v[92:95], v[132:135], v[210:213], v[92:95]
	v_mfma_f32_16x16x32_bf16 v[88:91], v[140:143], v[210:213], v[88:91]
	v_mfma_f32_16x16x32_bf16 v[72:75], v[140:143], v[218:221], v[72:75]
	v_mfma_f32_16x16x32_bf16 v[76:79], v[132:135], v[218:221], v[76:79]
	s_setprio 0
	s_setprio 1
	v_mfma_f32_16x16x32_bf16 v[116:119], v[158:161], v[182:185], v[116:119]
	v_mfma_f32_16x16x32_bf16 v[112:115], v[174:177], v[182:185], v[112:115]
	v_mfma_f32_16x16x32_bf16 v[96:99], v[174:177], v[190:193], v[96:99]
	v_mfma_f32_16x16x32_bf16 v[100:103], v[158:161], v[190:193], v[100:103]
	v_mfma_f32_16x16x32_bf16 v[84:87], v[158:161], v[206:209], v[84:87]
	v_mfma_f32_16x16x32_bf16 v[80:83], v[174:177], v[206:209], v[80:83]
	v_mfma_f32_16x16x32_bf16 v[64:67], v[174:177], v[214:217], v[64:67]
	v_mfma_f32_16x16x32_bf16 v[68:71], v[158:161], v[214:217], v[68:71]
	v_mfma_f32_16x16x32_bf16 v[116:119], v[162:165], v[186:189], v[116:119]
	v_mfma_f32_16x16x32_bf16 v[112:115], v[178:181], v[186:189], v[112:115]
	v_mfma_f32_16x16x32_bf16 v[96:99], v[178:181], v[194:197], v[96:99]
	v_mfma_f32_16x16x32_bf16 v[100:103], v[162:165], v[194:197], v[100:103]
	v_mfma_f32_16x16x32_bf16 v[84:87], v[162:165], v[210:213], v[84:87]
	v_mfma_f32_16x16x32_bf16 v[80:83], v[178:181], v[210:213], v[80:83]
	v_mfma_f32_16x16x32_bf16 v[64:67], v[178:181], v[218:221], v[64:67]
	v_mfma_f32_16x16x32_bf16 v[68:71], v[162:165], v[218:221], v[68:71]
	s_setprio 0
	s_barrier
	s_mov_b32 m0, s86
	v_lshl_add_u64 v[198:199], s[78:79], 0, v[148:149]
	s_add_u32 vcc_lo, s78, 0xb0000
	ds_read_b128 v[182:185], v169 offset:16384
	ds_read_b128 v[186:189], v169 offset:17408
	ds_read_b128 v[190:193], v169 offset:18432
	ds_read_b128 v[194:197], v169 offset:19456
	ds_read_b128 v[206:209], v169 offset:20480
	ds_read_b128 v[210:213], v169 offset:21504
	ds_read_b128 v[214:217], v169 offset:22528
	ds_read_b128 v[218:221], v169 offset:23552
	global_load_lds_dwordx4 v[198:199], off
	v_lshl_add_u64 v[222:223], s[78:79], 0, v[152:153]
	s_mov_b32 m0, s87
	s_addc_u32 vcc_hi, s79, 0
	global_load_lds_dwordx4 v[222:223], off
	v_lshl_add_u64 v[224:225], vcc, 0, v[148:149]
	s_mov_b32 m0, s88
	v_lshl_add_u64 v[226:227], s[80:81], 0, v[150:151]
	global_load_lds_dwordx4 v[224:225], off
	v_lshl_add_u64 v[224:225], vcc, 0, v[152:153]
	s_mov_b32 m0, s89
	s_nop 0
	global_load_lds_dwordx4 v[224:225], off
	v_lshl_add_u64 v[224:225], s[80:81], 0, v[146:147]
	s_mov_b32 m0, s29
	s_nop 0
	global_load_lds_dwordx4 v[224:225], off
	s_mov_b32 m0, s30
	s_nop 0
	global_load_lds_dwordx4 v[226:227], off
	s_waitcnt vmcnt(8)
	s_waitcnt lgkmcnt(0)
	s_barrier
; #define PG8_STAGE(bufoff, gbase, voff) do { _Pragma("unroll") for (int _i = 0; _i < 2; ++_i) \
;         __builtin_amdgcn_global_load_lds((const unsigned*)((const char*)(gbase) + (voff)[_i]), (PG8_LAS unsigned*)(lds + (bufoff) + ldsw + _i * 8192), 16, 0, 0); } while (0)
; #define PG8_LDA(dst, b, h) do { _Pragma("unroll") for (int m = 0; m < 4; ++m) _Pragma("unroll") for (int k = 0; k < 2; ++k) dst[m][k] = *(const PG8_LAS bf16x8*)(lds + PG8_SA(b, h) + aoff + m * 2048 + k * 1024); } while (0)
; #define PG8_LDB(dst, b, h) do { _Pragma("unroll") for (int n = 0; n < 2; ++n) _Pragma("unroll") for (int k = 0; k < 2; ++k) dst[n][k] = *(const PG8_LAS bf16x8*)(lds + PG8_SB(b, h) + boff + n * 2048 + k * 1024); } while (0)
; #define PG8_MMA(ai, bj, At, Bt) do { __builtin_amdgcn_s_setprio(1); _Pragma("unroll") for (int m = 0; m < 4; ++m) _Pragma("unroll") for (int n = 0; n < 2; ++n) _Pragma("unroll") for (int k = 0; k < 2; ++k) \
;         acc[ai][bj][m][n] = __builtin_amdgcn_mfma_f32_16x16x32_bf16(Bt[n][k], At[m][k], acc[ai][bj][m][n], 0, 0, 0); __builtin_amdgcn_s_setprio(0); } while (0)
; #define PG8_WAIT_V(n) asm volatile("s_waitcnt vmcnt(" #n ")" ::: "memory")
; #define PG8_WAIT_L(n) asm volatile("s_waitcnt lgkmcnt(" #n ")" ::: "memory")
; #define PG8_BAR __builtin_amdgcn_s_barrier()
; #define PG8_SCHED __builtin_amdgcn_sched_barrier(0)
; template <class Epi, class Sched, bool ALIGN_EPI = false, bool SP2 = false>
; __device__ __forceinline__ void gemm_phase(PG8_LAS unsigned char* lds, const Gemm g, const Sched& S, const Epi& E) {
;     ...
;             PG8_WAIT_V(8); PG8_WAIT_L(0); PG8_BAR; PG8_MMA(1, 0, At, B0); PG8_MMA(1, 1, At, B1); PG8_BAR; PG8_SCHED;
;             PG8_LDB(B0, 1, 0); PG8_LDB(B1, 1, 1); PG8_SCHED; PG8_LDA(At, 1, 0); PG8_STAGE(PG8_SA(0, 1), a2 + hstep, voffA);
;             PG8_WAIT_V(8); PG8_WAIT_L(0); PG8_BAR; PG8_MMA(0, 0, At, B0); PG8_MMA(0, 1, At, B1); PG8_BAR; PG8_SCHED;
	s_setprio 1
	s_waitcnt lgkmcnt(0)
	v_mfma_f32_16x16x32_bf16 v[60:63], v[128:131], v[182:185], v[60:63]
	v_mfma_f32_16x16x32_bf16 v[56:59], v[136:139], v[182:185], v[56:59]
	v_mfma_f32_16x16x32_bf16 v[40:43], v[136:139], v[190:193], v[40:43]
	v_mfma_f32_16x16x32_bf16 v[44:47], v[128:131], v[190:193], v[44:47]
	v_mfma_f32_16x16x32_bf16 v[32:35], v[128:131], v[206:209], v[32:35]
	v_mfma_f32_16x16x32_bf16 v[24:27], v[136:139], v[206:209], v[24:27]
	v_mfma_f32_16x16x32_bf16 v[8:11], v[136:139], v[214:217], v[8:11]
	v_mfma_f32_16x16x32_bf16 v[16:19], v[128:131], v[214:217], v[16:19]
	v_mfma_f32_16x16x32_bf16 v[60:63], v[132:135], v[186:189], v[60:63]
	v_mfma_f32_16x16x32_bf16 v[56:59], v[140:143], v[186:189], v[56:59]
	v_mfma_f32_16x16x32_bf16 v[40:43], v[140:143], v[194:197], v[40:43]
	v_mfma_f32_16x16x32_bf16 v[44:47], v[132:135], v[194:197], v[44:47]
	v_mfma_f32_16x16x32_bf16 v[32:35], v[132:135], v[210:213], v[32:35]
	v_mfma_f32_16x16x32_bf16 v[24:27], v[140:143], v[210:213], v[24:27]
	v_mfma_f32_16x16x32_bf16 v[8:11], v[140:143], v[218:221], v[8:11]
	v_mfma_f32_16x16x32_bf16 v[16:19], v[132:135], v[218:221], v[16:19]
	s_setprio 0
	s_setprio 1
	v_mfma_f32_16x16x32_bf16 v[52:55], v[158:161], v[182:185], v[52:55]
	v_mfma_f32_16x16x32_bf16 v[48:51], v[174:177], v[182:185], v[48:51]
	v_mfma_f32_16x16x32_bf16 v[28:31], v[174:177], v[190:193], v[28:31]
	v_mfma_f32_16x16x32_bf16 v[36:39], v[158:161], v[190:193], v[36:39]
	v_mfma_f32_16x16x32_bf16 v[20:23], v[158:161], v[206:209], v[20:23]
	v_mfma_f32_16x16x32_bf16 v[12:15], v[174:177], v[206:209], v[12:15]
	v_mfma_f32_16x16x32_bf16 v[0:3], v[174:177], v[214:217], v[0:3]
	v_mfma_f32_16x16x32_bf16 v[4:7], v[158:161], v[214:217], v[4:7]
	v_mfma_f32_16x16x32_bf16 v[52:55], v[162:165], v[186:189], v[52:55]
	v_mfma_f32_16x16x32_bf16 v[48:51], v[178:181], v[186:189], v[48:51]
	v_mfma_f32_16x16x32_bf16 v[28:31], v[178:181], v[194:197], v[28:31]
	v_mfma_f32_16x16x32_bf16 v[36:39], v[162:165], v[194:197], v[36:39]
	v_mfma_f32_16x16x32_bf16 v[20:23], v[162:165], v[210:213], v[20:23]
	v_mfma_f32_16x16x32_bf16 v[12:15], v[178:181], v[210:213], v[12:15]
	v_mfma_f32_16x16x32_bf16 v[0:3], v[178:181], v[218:221], v[0:3]
	v_mfma_f32_16x16x32_bf16 v[4:7], v[162:165], v[218:221], v[4:7]
	s_setprio 0
	s_barrier
	ds_read_b128 v[128:131], v171
	ds_read_b128 v[132:135], v171 offset:1024
	ds_read_b128 v[136:139], v171 offset:2048
	ds_read_b128 v[140:143], v171 offset:3072
	ds_read_b128 v[158:161], v172
	ds_read_b128 v[162:165], v172 offset:1024
	ds_read_b128 v[174:177], v172 offset:2048
	ds_read_b128 v[178:181], v172 offset:3072
	s_add_u32 s80, s80, 0xb0000
	s_addc_u32 s81, s81, 0
	s_mov_b32 m0, s31
	v_lshl_add_u64 v[228:229], s[80:81], 0, v[146:147]
	ds_read_b128 v[182:185], v169 offset:32768
	ds_read_b128 v[186:189], v169 offset:33792
	ds_read_b128 v[190:193], v169 offset:34816
	ds_read_b128 v[194:197], v169 offset:35840
	ds_read_b128 v[206:209], v169 offset:36864
	ds_read_b128 v[210:213], v169 offset:37888
	ds_read_b128 v[214:217], v169 offset:38912
	ds_read_b128 v[218:221], v169 offset:39936
	global_load_lds_dwordx4 v[228:229], off
	v_lshl_add_u64 v[228:229], s[80:81], 0, v[150:151]
	s_mov_b32 m0, s37
	s_nop 0
	global_load_lds_dwordx4 v[228:229], off
	s_waitcnt vmcnt(8)
	s_waitcnt lgkmcnt(0)
	s_barrier
	s_setprio 1
	s_waitcnt lgkmcnt(0)
	v_mfma_f32_16x16x32_bf16 v[124:127], v[128:131], v[182:185], v[124:127]
	v_mfma_f32_16x16x32_bf16 v[120:123], v[136:139], v[182:185], v[120:123]
	v_mfma_f32_16x16x32_bf16 v[104:107], v[136:139], v[190:193], v[104:107]
	v_mfma_f32_16x16x32_bf16 v[108:111], v[128:131], v[190:193], v[108:111]
	v_mfma_f32_16x16x32_bf16 v[92:95], v[128:131], v[206:209], v[92:95]
	v_mfma_f32_16x16x32_bf16 v[88:91], v[136:139], v[206:209], v[88:91]
	v_mfma_f32_16x16x32_bf16 v[72:75], v[136:139], v[214:217], v[72:75]
	v_mfma_f32_16x16x32_bf16 v[76:79], v[128:131], v[214:217], v[76:79]
	v_mfma_f32_16x16x32_bf16 v[124:127], v[132:135], v[186:189], v[124:127]
	v_mfma_f32_16x16x32_bf16 v[120:123], v[140:143], v[186:189], v[120:123]
	v_mfma_f32_16x16x32_bf16 v[104:107], v[140:143], v[194:197], v[104:107]
	v_mfma_f32_16x16x32_bf16 v[108:111], v[132:135], v[194:197], v[108:111]
	v_mfma_f32_16x16x32_bf16 v[92:95], v[132:135], v[210:213], v[92:95]
	v_mfma_f32_16x16x32_bf16 v[88:91], v[140:143], v[210:213], v[88:91]
	v_mfma_f32_16x16x32_bf16 v[72:75], v[140:143], v[218:221], v[72:75]
	v_mfma_f32_16x16x32_bf16 v[76:79], v[132:135], v[218:221], v[76:79]
	s_setprio 0
	s_setprio 1
	v_mfma_f32_16x16x32_bf16 v[116:119], v[158:161], v[182:185], v[116:119]
	v_mfma_f32_16x16x32_bf16 v[112:115], v[174:177], v[182:185], v[112:115]
	v_mfma_f32_16x16x32_bf16 v[96:99], v[174:177], v[190:193], v[96:99]
	v_mfma_f32_16x16x32_bf16 v[100:103], v[158:161], v[190:193], v[100:103]
	v_mfma_f32_16x16x32_bf16 v[84:87], v[158:161], v[206:209], v[84:87]
	v_mfma_f32_16x16x32_bf16 v[80:83], v[174:177], v[206:209], v[80:83]
	v_mfma_f32_16x16x32_bf16 v[64:67], v[174:177], v[214:217], v[64:67]
	v_mfma_f32_16x16x32_bf16 v[68:71], v[158:161], v[214:217], v[68:71]
	v_mfma_f32_16x16x32_bf16 v[116:119], v[162:165], v[186:189], v[116:119]
	v_mfma_f32_16x16x32_bf16 v[112:115], v[178:181], v[186:189], v[112:115]
	v_mfma_f32_16x16x32_bf16 v[96:99], v[178:181], v[194:197], v[96:99]
	v_mfma_f32_16x16x32_bf16 v[100:103], v[162:165], v[194:197], v[100:103]
	v_mfma_f32_16x16x32_bf16 v[84:87], v[162:165], v[210:213], v[84:87]
	v_mfma_f32_16x16x32_bf16 v[80:83], v[178:181], v[210:213], v[80:83]
	v_mfma_f32_16x16x32_bf16 v[64:67], v[178:181], v[218:221], v[64:67]
	v_mfma_f32_16x16x32_bf16 v[68:71], v[162:165], v[218:221], v[68:71]
	s_setprio 0
	s_barrier
; #define PG8_STAGE(bufoff, gbase, voff) do { _Pragma("unroll") for (int _i = 0; _i < 2; ++_i) \
;         __builtin_amdgcn_global_load_lds((const unsigned*)((const char*)(gbase) + (voff)[_i]), (PG8_LAS unsigned*)(lds + (bufoff) + ldsw + _i * 8192), 16, 0, 0); } while (0)
; #define PG8_LDA(dst, b, h) do { _Pragma("unroll") for (int m = 0; m < 4; ++m) _Pragma("unroll") for (int k = 0; k < 2; ++k) dst[m][k] = *(const PG8_LAS bf16x8*)(lds + PG8_SA(b, h) + aoff + m * 2048 + k * 1024); } while (0)
; #define PG8_MMA(ai, bj, At, Bt) do { __builtin_amdgcn_s_setprio(1); _Pragma("unroll") for (int m = 0; m < 4; ++m) _Pragma("unroll") for (int n = 0; n < 2; ++n) _Pragma("unroll") for (int k = 0; k < 2; ++k) \
;         acc[ai][bj][m][n] = __builtin_amdgcn_mfma_f32_16x16x32_bf16(Bt[n][k], At[m][k], acc[ai][bj][m][n], 0, 0, 0); __builtin_amdgcn_s_setprio(0); } while (0)
; #define PG8_WAIT_V(n) asm volatile("s_waitcnt vmcnt(" #n ")" ::: "memory")
; #define PG8_WAIT_L(n) asm volatile("s_waitcnt lgkmcnt(" #n ")" ::: "memory")
; #define PG8_BAR __builtin_amdgcn_s_barrier()
; #define PG8_SCHED __builtin_amdgcn_sched_barrier(0)
; template <class Epi, class Sched, bool ALIGN_EPI = false, bool SP2 = false>
; __device__ __forceinline__ void gemm_phase(PG8_LAS unsigned char* lds, const Gemm g, const Sched& S, const Epi& E) {
;     ...
;         for (int t = 0; t < nt; t += 2) {
;             const bool last = (t == nt - 2);
;             const char* a1 = cA + (size_t)(t + 1) * kstep;
;             const char* a2 = last ? nA : cA + (size_t)(t + 2) * kstep; const char* b2 = last ? nB : cB + (size_t)(t + 2) * kstep;
;             const char* a3 = a2 + kstep; const char* b3 = b2 + kstep;
;     ...
;             PG8_LDA(At, 1, 1); PG8_STAGE(PG8_SB(1, 0), b3, voffB); PG8_STAGE(PG8_SB(1, 1), b3 + hstep, voffB); PG8_STAGE(PG8_SA(1, 0), a3, voffA);
;             PG8_WAIT_V(8); PG8_WAIT_L(0); PG8_BAR; PG8_MMA(1, 0, At, B0); PG8_MMA(1, 1, At, B1); PG8_BAR; PG8_SCHED;
	s_add_i32 s60, s90, s28
	v_lshl_add_u64 v[198:199], v[198:199], 0, s[68:69]
	s_mov_b32 m0, s60
	ds_read_b128 v[182:185], v169 offset:49152
	ds_read_b128 v[186:189], v169 offset:50176
	ds_read_b128 v[190:193], v169 offset:51200
	ds_read_b128 v[194:197], v169 offset:52224
	ds_read_b128 v[206:209], v169 offset:53248
	ds_read_b128 v[210:213], v169 offset:54272
	ds_read_b128 v[214:217], v169 offset:55296
	ds_read_b128 v[218:221], v169 offset:56320
	global_load_lds_dwordx4 v[198:199], off
	s_add_i32 m0, s60, 0x2000
	s_add_u32 s78, s78, 0xb0080
	v_lshl_add_u64 v[198:199], v[222:223], 0, s[68:69]
	s_addc_u32 s79, s79, 0
	s_add_i32 s60, s91, s28
	global_load_lds_dwordx4 v[198:199], off
	v_lshl_add_u64 v[198:199], s[78:79], 0, v[148:149]
	s_mov_b32 m0, s60
	s_nop 0
	global_load_lds_dwordx4 v[198:199], off
	v_lshl_add_u64 v[198:199], s[78:79], 0, v[152:153]
	s_add_i32 m0, s60, 0x2000
	s_nop 0
	global_load_lds_dwordx4 v[198:199], off
	v_lshl_add_u64 v[198:199], v[224:225], 0, s[68:69]
	s_mov_b32 m0, s82
	s_nop 0
	global_load_lds_dwordx4 v[198:199], off
	v_lshl_add_u64 v[198:199], v[226:227], 0, s[68:69]
	s_mov_b32 m0, s83
	s_nop 0
	global_load_lds_dwordx4 v[198:199], off
	s_waitcnt vmcnt(8)
	s_waitcnt lgkmcnt(0)
	s_barrier
	s_setprio 1
	s_waitcnt lgkmcnt(0)
	v_mfma_f32_16x16x32_bf16 v[60:63], v[128:131], v[182:185], v[60:63]
	v_mfma_f32_16x16x32_bf16 v[56:59], v[136:139], v[182:185], v[56:59]
	v_mfma_f32_16x16x32_bf16 v[40:43], v[136:139], v[190:193], v[40:43]
	v_mfma_f32_16x16x32_bf16 v[44:47], v[128:131], v[190:193], v[44:47]
	v_mfma_f32_16x16x32_bf16 v[32:35], v[128:131], v[206:209], v[32:35]
	v_mfma_f32_16x16x32_bf16 v[24:27], v[136:139], v[206:209], v[24:27]
	v_mfma_f32_16x16x32_bf16 v[8:11], v[136:139], v[214:217], v[8:11]
	v_mfma_f32_16x16x32_bf16 v[16:19], v[128:131], v[214:217], v[16:19]
	v_mfma_f32_16x16x32_bf16 v[60:63], v[132:135], v[186:189], v[60:63]
	v_mfma_f32_16x16x32_bf16 v[56:59], v[140:143], v[186:189], v[56:59]
	v_mfma_f32_16x16x32_bf16 v[40:43], v[140:143], v[194:197], v[40:43]
	v_mfma_f32_16x16x32_bf16 v[44:47], v[132:135], v[194:197], v[44:47]
	v_mfma_f32_16x16x32_bf16 v[32:35], v[132:135], v[210:213], v[32:35]
	v_mfma_f32_16x16x32_bf16 v[24:27], v[140:143], v[210:213], v[24:27]
	v_mfma_f32_16x16x32_bf16 v[8:11], v[140:143], v[218:221], v[8:11]
	v_mfma_f32_16x16x32_bf16 v[16:19], v[132:135], v[218:221], v[16:19]
	s_setprio 0
	s_setprio 1
	v_mfma_f32_16x16x32_bf16 v[52:55], v[158:161], v[182:185], v[52:55]
	v_mfma_f32_16x16x32_bf16 v[48:51], v[174:177], v[182:185], v[48:51]
	v_mfma_f32_16x16x32_bf16 v[28:31], v[174:177], v[190:193], v[28:31]
	v_mfma_f32_16x16x32_bf16 v[36:39], v[158:161], v[190:193], v[36:39]
	v_mfma_f32_16x16x32_bf16 v[20:23], v[158:161], v[206:209], v[20:23]
	v_mfma_f32_16x16x32_bf16 v[12:15], v[174:177], v[206:209], v[12:15]
	v_mfma_f32_16x16x32_bf16 v[0:3], v[174:177], v[214:217], v[0:3]
	v_mfma_f32_16x16x32_bf16 v[4:7], v[158:161], v[214:217], v[4:7]
	v_mfma_f32_16x16x32_bf16 v[52:55], v[162:165], v[186:189], v[52:55]
	v_mfma_f32_16x16x32_bf16 v[48:51], v[178:181], v[186:189], v[48:51]
	v_mfma_f32_16x16x32_bf16 v[28:31], v[178:181], v[194:197], v[28:31]
	v_mfma_f32_16x16x32_bf16 v[36:39], v[162:165], v[194:197], v[36:39]
	v_mfma_f32_16x16x32_bf16 v[20:23], v[162:165], v[210:213], v[20:23]
	v_mfma_f32_16x16x32_bf16 v[12:15], v[178:181], v[210:213], v[12:15]
	v_mfma_f32_16x16x32_bf16 v[0:3], v[178:181], v[218:221], v[0:3]
	v_mfma_f32_16x16x32_bf16 v[4:7], v[162:165], v[218:221], v[4:7]
	s_setprio 0
	s_barrier
	s_add_i32 s59, s59, 2
	s_add_u32 s76, s76, 0x100
	s_addc_u32 s77, s77, 0
	s_add_u32 s57, s57, 0x100
	s_addc_u32 s58, s58, 0
	s_cmp_gt_u32 s59, 41
	s_cbranch_scc0 .LBB0_730
	s_and_b64 vcc, exec, s[70:71]
	s_cbranch_vccz .LBB0_733
	s_barrier

; #define PG8_STAGE(bufoff, gbase, voff) do { _Pragma("unroll") for (int _i = 0; _i < 2; ++_i) \
;         __builtin_amdgcn_global_load_lds((const unsigned*)((const char*)(gbase) + (voff)[_i]), (PG8_LAS unsigned*)(lds + (bufoff) + ldsw + _i * 8192), 16, 0, 0); } while (0)
; #define PG8_LDA(dst, b, h) do { _Pragma("unroll") for (int m = 0; m < 4; ++m) _Pragma("unroll") for (int k = 0; k < 2; ++k) dst[m][k] = *(const PG8_LAS bf16x8*)(lds + PG8_SA(b, h) + aoff + m * 2048 + k * 1024); } while (0)
; #define PG8_LDB(dst, b, h) do { _Pragma("unroll") for (int n = 0; n < 2; ++n) _Pragma("unroll") for (int k = 0; k < 2; ++k) dst[n][k] = *(const PG8_LAS bf16x8*)(lds + PG8_SB(b, h) + boff + n * 2048 + k * 1024); } while (0)
; #define PG8_MMA(ai, bj, At, Bt) do { __builtin_amdgcn_s_setprio(1); _Pragma("unroll") for (int m = 0; m < 4; ++m) _Pragma("unroll") for (int n = 0; n < 2; ++n) _Pragma("unroll") for (int k = 0; k < 2; ++k) \
;         acc[ai][bj][m][n] = __builtin_amdgcn_mfma_f32_16x16x32_bf16(Bt[n][k], At[m][k], acc[ai][bj][m][n], 0, 0, 0); __builtin_amdgcn_s_setprio(0); } while (0)
; #define PG8_WAIT_V(n) asm volatile("s_waitcnt vmcnt(" #n ")" ::: "memory")
; #define PG8_WAIT_L(n) asm volatile("s_waitcnt lgkmcnt(" #n ")" ::: "memory")
; #define PG8_BAR __builtin_amdgcn_s_barrier()
; #define PG8_SCHED __builtin_amdgcn_sched_barrier(0)
; template <class Epi, class Sched, bool ALIGN_EPI = false, bool SP2 = false>
; __device__ __forceinline__ void gemm_phase(PG8_LAS unsigned char* lds, const Gemm g, const Sched& S, const Epi& E) {
;     ...
;             PG8_LDB(B0, 0, 0); PG8_LDB(B1, 0, 1); PG8_SCHED; PG8_LDA(At, 0, 0); PG8_STAGE(PG8_SA(1, 1), a1 + hstep, voffA);
;             PG8_WAIT_V(8); PG8_WAIT_L(0); PG8_BAR; PG8_MMA(0, 0, At, B0); PG8_MMA(0, 1, At, B1); PG8_BAR; PG8_SCHED;
;             PG8_LDA(At, 0, 1); PG8_STAGE(PG8_SB(0, 0), b2, voffB); PG8_STAGE(PG8_SB(0, 1), b2 + hstep, voffB); PG8_STAGE(PG8_SA(0, 0), a2, voffA);
.LBB0_958:
	ds_read_b128 v[140:143], v163
	ds_read_b128 v[146:149], v163 offset:1024
	ds_read_b128 v[150:153], v163 offset:2048
	ds_read_b128 v[154:157], v163 offset:3072
	ds_read_b128 v[168:171], v164
	ds_read_b128 v[172:175], v164 offset:1024
	ds_read_b128 v[176:179], v164 offset:2048
	ds_read_b128 v[180:183], v164 offset:3072
	s_add_u32 s59, s86, 0xfffc0080
	s_addc_u32 s60, s87, -1
	s_cmp_eq_u32 s58, 12
	s_cselect_b32 s91, s7, s60
	s_cselect_b32 s90, s75, s59
	s_cselect_b32 s89, s77, vcc_hi
	s_cselect_b32 s88, s85, vcc_lo
	v_lshl_add_u64 v[158:159], s[86:87], 0, v[136:137]
	s_add_i32 m0, s20, 0xc000
	ds_read_b128 v[184:187], v165
	ds_read_b128 v[188:191], v165 offset:1024
	ds_read_b128 v[192:195], v165 offset:2048
	ds_read_b128 v[196:199], v165 offset:3072
	ds_read_b128 v[206:209], v165 offset:4096
	ds_read_b128 v[210:213], v165 offset:5120
	ds_read_b128 v[214:217], v165 offset:6144
	ds_read_b128 v[218:221], v165 offset:7168
	global_load_lds_dwordx4 v[158:159], off
	v_lshl_add_u64 v[158:159], s[86:87], 0, v[138:139]
	s_add_i32 m0, s20, 0xe000
	s_nop 0
	global_load_lds_dwordx4 v[158:159], off
	s_waitcnt vmcnt(8)
	s_waitcnt lgkmcnt(0)
	s_barrier
	s_setprio 1
	s_waitcnt lgkmcnt(0)
	v_mfma_f32_16x16x32_bf16 v[124:127], v[140:143], v[184:187], v[124:127]
	v_mfma_f32_16x16x32_bf16 v[120:123], v[150:153], v[184:187], v[120:123]
	v_mfma_f32_16x16x32_bf16 v[104:107], v[150:153], v[192:195], v[104:107]
	v_mfma_f32_16x16x32_bf16 v[108:111], v[140:143], v[192:195], v[108:111]
	v_mfma_f32_16x16x32_bf16 v[92:95], v[140:143], v[206:209], v[92:95]
	v_mfma_f32_16x16x32_bf16 v[88:91], v[150:153], v[206:209], v[88:91]
	v_mfma_f32_16x16x32_bf16 v[72:75], v[150:153], v[214:217], v[72:75]
	v_mfma_f32_16x16x32_bf16 v[76:79], v[140:143], v[214:217], v[76:79]
	v_mfma_f32_16x16x32_bf16 v[124:127], v[146:149], v[188:191], v[124:127]
	v_mfma_f32_16x16x32_bf16 v[120:123], v[154:157], v[188:191], v[120:123]
	v_mfma_f32_16x16x32_bf16 v[104:107], v[154:157], v[196:199], v[104:107]
	v_mfma_f32_16x16x32_bf16 v[108:111], v[146:149], v[196:199], v[108:111]
	v_mfma_f32_16x16x32_bf16 v[92:95], v[146:149], v[210:213], v[92:95]
	v_mfma_f32_16x16x32_bf16 v[88:91], v[154:157], v[210:213], v[88:91]
	v_mfma_f32_16x16x32_bf16 v[72:75], v[154:157], v[218:221], v[72:75]
	v_mfma_f32_16x16x32_bf16 v[76:79], v[146:149], v[218:221], v[76:79]
	s_setprio 0
	s_setprio 1
	v_mfma_f32_16x16x32_bf16 v[116:119], v[168:171], v[184:187], v[116:119]
	v_mfma_f32_16x16x32_bf16 v[112:115], v[176:179], v[184:187], v[112:115]
	v_mfma_f32_16x16x32_bf16 v[96:99], v[176:179], v[192:195], v[96:99]
	v_mfma_f32_16x16x32_bf16 v[100:103], v[168:171], v[192:195], v[100:103]
	v_mfma_f32_16x16x32_bf16 v[84:87], v[168:171], v[206:209], v[84:87]
	v_mfma_f32_16x16x32_bf16 v[80:83], v[176:179], v[206:209], v[80:83]
	v_mfma_f32_16x16x32_bf16 v[64:67], v[176:179], v[214:217], v[64:67]
	v_mfma_f32_16x16x32_bf16 v[68:71], v[168:171], v[214:217], v[68:71]
	v_mfma_f32_16x16x32_bf16 v[116:119], v[172:175], v[188:191], v[116:119]
	v_mfma_f32_16x16x32_bf16 v[112:115], v[180:183], v[188:191], v[112:115]
	v_mfma_f32_16x16x32_bf16 v[96:99], v[180:183], v[196:199], v[96:99]
	v_mfma_f32_16x16x32_bf16 v[100:103], v[172:175], v[196:199], v[100:103]
	v_mfma_f32_16x16x32_bf16 v[84:87], v[172:175], v[210:213], v[84:87]
	v_mfma_f32_16x16x32_bf16 v[80:83], v[180:183], v[210:213], v[80:83]
	v_mfma_f32_16x16x32_bf16 v[64:67], v[180:183], v[218:221], v[64:67]
	v_mfma_f32_16x16x32_bf16 v[68:71], v[172:175], v[218:221], v[68:71]
	s_setprio 0
	s_barrier
	s_add_i32 s59, s39, s11
	v_lshl_add_u64 v[158:159], s[88:89], 0, v[130:131]
	s_mov_b32 m0, s59
	ds_read_b128 v[184:187], v165 offset:16384
	ds_read_b128 v[188:191], v165 offset:17408
	ds_read_b128 v[192:195], v165 offset:18432
	ds_read_b128 v[196:199], v165 offset:19456
	ds_read_b128 v[206:209], v165 offset:20480
	ds_read_b128 v[210:213], v165 offset:21504
	ds_read_b128 v[214:217], v165 offset:22528
	ds_read_b128 v[218:221], v165 offset:23552
	global_load_lds_dwordx4 v[158:159], off
	s_add_i32 m0, s59, 0x2000
	s_add_u32 s60, s88, 0x40000
	v_lshl_add_u64 v[222:223], s[88:89], 0, v[134:135]
	s_addc_u32 s61, s89, 0
	s_add_i32 s59, s56, s11
	global_load_lds_dwordx4 v[222:223], off
	v_lshl_add_u64 v[224:225], s[60:61], 0, v[130:131]
	s_mov_b32 m0, s59
	v_lshl_add_u64 v[226:227], s[90:91], 0, v[132:133]
	global_load_lds_dwordx4 v[224:225], off
	v_lshl_add_u64 v[224:225], s[60:61], 0, v[134:135]
	s_add_i32 m0, s59, 0x2000
	s_nop 0
	global_load_lds_dwordx4 v[224:225], off
	v_lshl_add_u64 v[224:225], s[90:91], 0, v[128:129]
	s_mov_b32 m0, s20
	s_nop 0
	global_load_lds_dwordx4 v[224:225], off
	s_mov_b32 m0, s21
	s_nop 0
	global_load_lds_dwordx4 v[226:227], off
	s_waitcnt vmcnt(8)
	s_waitcnt lgkmcnt(0)
	s_barrier
; #define PG8_STAGE(bufoff, gbase, voff) do { _Pragma("unroll") for (int _i = 0; _i < 2; ++_i) \
;         __builtin_amdgcn_global_load_lds((const unsigned*)((const char*)(gbase) + (voff)[_i]), (PG8_LAS unsigned*)(lds + (bufoff) + ldsw + _i * 8192), 16, 0, 0); } while (0)
; #define PG8_LDA(dst, b, h) do { _Pragma("unroll") for (int m = 0; m < 4; ++m) _Pragma("unroll") for (int k = 0; k < 2; ++k) dst[m][k] = *(const PG8_LAS bf16x8*)(lds + PG8_SA(b, h) + aoff + m * 2048 + k * 1024); } while (0)
; #define PG8_LDB(dst, b, h) do { _Pragma("unroll") for (int n = 0; n < 2; ++n) _Pragma("unroll") for (int k = 0; k < 2; ++k) dst[n][k] = *(const PG8_LAS bf16x8*)(lds + PG8_SB(b, h) + boff + n * 2048 + k * 1024); } while (0)
; #define PG8_MMA(ai, bj, At, Bt) do { __builtin_amdgcn_s_setprio(1); _Pragma("unroll") for (int m = 0; m < 4; ++m) _Pragma("unroll") for (int n = 0; n < 2; ++n) _Pragma("unroll") for (int k = 0; k < 2; ++k) \
;         acc[ai][bj][m][n] = __builtin_amdgcn_mfma_f32_16x16x32_bf16(Bt[n][k], At[m][k], acc[ai][bj][m][n], 0, 0, 0); __builtin_amdgcn_s_setprio(0); } while (0)
; #define PG8_WAIT_V(n) asm volatile("s_waitcnt vmcnt(" #n ")" ::: "memory")
; #define PG8_WAIT_L(n) asm volatile("s_waitcnt lgkmcnt(" #n ")" ::: "memory")
; #define PG8_BAR __builtin_amdgcn_s_barrier()
; #define PG8_SCHED __builtin_amdgcn_sched_barrier(0)
; template <class Epi, class Sched, bool ALIGN_EPI = false, bool SP2 = false>
; __device__ __forceinline__ void gemm_phase(PG8_LAS unsigned char* lds, const Gemm g, const Sched& S, const Epi& E) {
;     ...
;             PG8_WAIT_V(8); PG8_WAIT_L(0); PG8_BAR; PG8_MMA(1, 0, At, B0); PG8_MMA(1, 1, At, B1); PG8_BAR; PG8_SCHED;
;             PG8_LDB(B0, 1, 0); PG8_LDB(B1, 1, 1); PG8_SCHED; PG8_LDA(At, 1, 0); PG8_STAGE(PG8_SA(0, 1), a2 + hstep, voffA);
;             PG8_WAIT_V(8); PG8_WAIT_L(0); PG8_BAR; PG8_MMA(0, 0, At, B0); PG8_MMA(0, 1, At, B1); PG8_BAR; PG8_SCHED;
	s_setprio 1
	s_waitcnt lgkmcnt(0)
	v_mfma_f32_16x16x32_bf16 v[60:63], v[140:143], v[184:187], v[60:63]
	v_mfma_f32_16x16x32_bf16 v[56:59], v[150:153], v[184:187], v[56:59]
	v_mfma_f32_16x16x32_bf16 v[40:43], v[150:153], v[192:195], v[40:43]
	v_mfma_f32_16x16x32_bf16 v[44:47], v[140:143], v[192:195], v[44:47]
	v_mfma_f32_16x16x32_bf16 v[28:31], v[140:143], v[206:209], v[28:31]
	v_mfma_f32_16x16x32_bf16 v[24:27], v[150:153], v[206:209], v[24:27]
	v_mfma_f32_16x16x32_bf16 v[8:11], v[150:153], v[214:217], v[8:11]
	v_mfma_f32_16x16x32_bf16 v[12:15], v[140:143], v[214:217], v[12:15]
	v_mfma_f32_16x16x32_bf16 v[60:63], v[146:149], v[188:191], v[60:63]
	v_mfma_f32_16x16x32_bf16 v[56:59], v[154:157], v[188:191], v[56:59]
	v_mfma_f32_16x16x32_bf16 v[40:43], v[154:157], v[196:199], v[40:43]
	v_mfma_f32_16x16x32_bf16 v[44:47], v[146:149], v[196:199], v[44:47]
	v_mfma_f32_16x16x32_bf16 v[28:31], v[146:149], v[210:213], v[28:31]
	v_mfma_f32_16x16x32_bf16 v[24:27], v[154:157], v[210:213], v[24:27]
	v_mfma_f32_16x16x32_bf16 v[8:11], v[154:157], v[218:221], v[8:11]
	v_mfma_f32_16x16x32_bf16 v[12:15], v[146:149], v[218:221], v[12:15]
	s_setprio 0
	s_setprio 1
	v_mfma_f32_16x16x32_bf16 v[52:55], v[168:171], v[184:187], v[52:55]
	v_mfma_f32_16x16x32_bf16 v[48:51], v[176:179], v[184:187], v[48:51]
	v_mfma_f32_16x16x32_bf16 v[32:35], v[176:179], v[192:195], v[32:35]
	v_mfma_f32_16x16x32_bf16 v[36:39], v[168:171], v[192:195], v[36:39]
	v_mfma_f32_16x16x32_bf16 v[20:23], v[168:171], v[206:209], v[20:23]
	v_mfma_f32_16x16x32_bf16 v[16:19], v[176:179], v[206:209], v[16:19]
	v_mfma_f32_16x16x32_bf16 v[0:3], v[176:179], v[214:217], v[0:3]
	v_mfma_f32_16x16x32_bf16 v[4:7], v[168:171], v[214:217], v[4:7]
	v_mfma_f32_16x16x32_bf16 v[52:55], v[172:175], v[188:191], v[52:55]
	v_mfma_f32_16x16x32_bf16 v[48:51], v[180:183], v[188:191], v[48:51]
	v_mfma_f32_16x16x32_bf16 v[32:35], v[180:183], v[196:199], v[32:35]
	v_mfma_f32_16x16x32_bf16 v[36:39], v[172:175], v[196:199], v[36:39]
	v_mfma_f32_16x16x32_bf16 v[20:23], v[172:175], v[210:213], v[20:23]
	v_mfma_f32_16x16x32_bf16 v[16:19], v[180:183], v[210:213], v[16:19]
	v_mfma_f32_16x16x32_bf16 v[0:3], v[180:183], v[218:221], v[0:3]
	v_mfma_f32_16x16x32_bf16 v[4:7], v[172:175], v[218:221], v[4:7]
	s_setprio 0
	s_barrier
	s_add_i32 s59, 0, 0x18000
	s_add_i32 s96, 0, 0x1c000
	v_add_u32_e32 v154, s59, v161
	v_add_u32_e32 v180, s96, v161
	ds_read_b128 v[140:143], v154
	ds_read_b128 v[146:149], v154 offset:1024
	ds_read_b128 v[150:153], v154 offset:2048
	ds_read_b128 v[154:157], v154 offset:3072
	ds_read_b128 v[168:171], v180
	ds_read_b128 v[172:175], v180 offset:1024
	ds_read_b128 v[176:179], v180 offset:2048
	ds_read_b128 v[180:183], v180 offset:3072
	s_add_u32 s60, s90, 0x40000
	s_addc_u32 s61, s91, 0
	s_mov_b32 m0, s28
	v_lshl_add_u64 v[228:229], s[60:61], 0, v[128:129]
	ds_read_b128 v[184:187], v165 offset:32768
	ds_read_b128 v[188:191], v165 offset:33792
	ds_read_b128 v[192:195], v165 offset:34816
	ds_read_b128 v[196:199], v165 offset:35840
	ds_read_b128 v[206:209], v165 offset:36864
	ds_read_b128 v[210:213], v165 offset:37888
	ds_read_b128 v[214:217], v165 offset:38912
	ds_read_b128 v[218:221], v165 offset:39936
	global_load_lds_dwordx4 v[228:229], off
	v_lshl_add_u64 v[228:229], s[60:61], 0, v[132:133]
	s_mov_b32 m0, s29
	s_nop 0
	global_load_lds_dwordx4 v[228:229], off
	s_waitcnt vmcnt(8)
	s_waitcnt lgkmcnt(0)
	s_barrier
	s_setprio 1
	s_waitcnt lgkmcnt(0)
	v_mfma_f32_16x16x32_bf16 v[124:127], v[140:143], v[184:187], v[124:127]
	v_mfma_f32_16x16x32_bf16 v[120:123], v[150:153], v[184:187], v[120:123]
	v_mfma_f32_16x16x32_bf16 v[104:107], v[150:153], v[192:195], v[104:107]
	v_mfma_f32_16x16x32_bf16 v[108:111], v[140:143], v[192:195], v[108:111]
	v_mfma_f32_16x16x32_bf16 v[92:95], v[140:143], v[206:209], v[92:95]
	v_mfma_f32_16x16x32_bf16 v[88:91], v[150:153], v[206:209], v[88:91]
	v_mfma_f32_16x16x32_bf16 v[72:75], v[150:153], v[214:217], v[72:75]
	v_mfma_f32_16x16x32_bf16 v[76:79], v[140:143], v[214:217], v[76:79]
	v_mfma_f32_16x16x32_bf16 v[124:127], v[146:149], v[188:191], v[124:127]
	v_mfma_f32_16x16x32_bf16 v[120:123], v[154:157], v[188:191], v[120:123]
	v_mfma_f32_16x16x32_bf16 v[104:107], v[154:157], v[196:199], v[104:107]
	v_mfma_f32_16x16x32_bf16 v[108:111], v[146:149], v[196:199], v[108:111]
	v_mfma_f32_16x16x32_bf16 v[92:95], v[146:149], v[210:213], v[92:95]
	v_mfma_f32_16x16x32_bf16 v[88:91], v[154:157], v[210:213], v[88:91]
	v_mfma_f32_16x16x32_bf16 v[72:75], v[154:157], v[218:221], v[72:75]
	v_mfma_f32_16x16x32_bf16 v[76:79], v[146:149], v[218:221], v[76:79]
	s_setprio 0
	s_setprio 1
	v_mfma_f32_16x16x32_bf16 v[116:119], v[168:171], v[184:187], v[116:119]
	v_mfma_f32_16x16x32_bf16 v[112:115], v[176:179], v[184:187], v[112:115]
	v_mfma_f32_16x16x32_bf16 v[96:99], v[176:179], v[192:195], v[96:99]
	v_mfma_f32_16x16x32_bf16 v[100:103], v[168:171], v[192:195], v[100:103]
	v_mfma_f32_16x16x32_bf16 v[84:87], v[168:171], v[206:209], v[84:87]
	v_mfma_f32_16x16x32_bf16 v[80:83], v[176:179], v[206:209], v[80:83]
	v_mfma_f32_16x16x32_bf16 v[64:67], v[176:179], v[214:217], v[64:67]
	v_mfma_f32_16x16x32_bf16 v[68:71], v[168:171], v[214:217], v[68:71]
	v_mfma_f32_16x16x32_bf16 v[116:119], v[172:175], v[188:191], v[116:119]
	v_mfma_f32_16x16x32_bf16 v[112:115], v[180:183], v[188:191], v[112:115]
	v_mfma_f32_16x16x32_bf16 v[96:99], v[180:183], v[196:199], v[96:99]
	v_mfma_f32_16x16x32_bf16 v[100:103], v[172:175], v[196:199], v[100:103]
	v_mfma_f32_16x16x32_bf16 v[84:87], v[172:175], v[210:213], v[84:87]
	v_mfma_f32_16x16x32_bf16 v[80:83], v[180:183], v[210:213], v[80:83]
	v_mfma_f32_16x16x32_bf16 v[64:67], v[180:183], v[218:221], v[64:67]
	v_mfma_f32_16x16x32_bf16 v[68:71], v[172:175], v[218:221], v[68:71]
	s_setprio 0
	s_barrier
; #define PG8_STAGE(bufoff, gbase, voff) do { _Pragma("unroll") for (int _i = 0; _i < 2; ++_i) \
;         __builtin_amdgcn_global_load_lds((const unsigned*)((const char*)(gbase) + (voff)[_i]), (PG8_LAS unsigned*)(lds + (bufoff) + ldsw + _i * 8192), 16, 0, 0); } while (0)
; #define PG8_LDA(dst, b, h) do { _Pragma("unroll") for (int m = 0; m < 4; ++m) _Pragma("unroll") for (int k = 0; k < 2; ++k) dst[m][k] = *(const PG8_LAS bf16x8*)(lds + PG8_SA(b, h) + aoff + m * 2048 + k * 1024); } while (0)
; #define PG8_MMA(ai, bj, At, Bt) do { __builtin_amdgcn_s_setprio(1); _Pragma("unroll") for (int m = 0; m < 4; ++m) _Pragma("unroll") for (int n = 0; n < 2; ++n) _Pragma("unroll") for (int k = 0; k < 2; ++k) \
;         acc[ai][bj][m][n] = __builtin_amdgcn_mfma_f32_16x16x32_bf16(Bt[n][k], At[m][k], acc[ai][bj][m][n], 0, 0, 0); __builtin_amdgcn_s_setprio(0); } while (0)
; #define PG8_WAIT_V(n) asm volatile("s_waitcnt vmcnt(" #n ")" ::: "memory")
; #define PG8_WAIT_L(n) asm volatile("s_waitcnt lgkmcnt(" #n ")" ::: "memory")
; #define PG8_BAR __builtin_amdgcn_s_barrier()
; #define PG8_SCHED __builtin_amdgcn_sched_barrier(0)
; template <class Epi, class Sched, bool ALIGN_EPI = false, bool SP2 = false>
; __device__ __forceinline__ void gemm_phase(PG8_LAS unsigned char* lds, const Gemm g, const Sched& S, const Epi& E) {
;     ...
;         for (int t = 0; t < nt; t += 2) {
;             const bool last = (t == nt - 2);
;             const char* a1 = cA + (size_t)(t + 1) * kstep;
;             const char* a2 = last ? nA : cA + (size_t)(t + 2) * kstep; const char* b2 = last ? nB : cB + (size_t)(t + 2) * kstep;
;             const char* a3 = a2 + kstep; const char* b3 = b2 + kstep;
;     ...
;             PG8_LDA(At, 1, 1); PG8_STAGE(PG8_SB(1, 0), b3, voffB); PG8_STAGE(PG8_SB(1, 1), b3 + hstep, voffB); PG8_STAGE(PG8_SA(1, 0), a3, voffA);
;             PG8_WAIT_V(8); PG8_WAIT_L(0); PG8_BAR; PG8_MMA(1, 0, At, B0); PG8_MMA(1, 1, At, B1); PG8_BAR; PG8_SCHED;
	s_add_i32 s59, s59, s11
	v_lshl_add_u64 v[158:159], v[158:159], 0, s[70:71]
	s_mov_b32 m0, s59
	ds_read_b128 v[184:187], v165 offset:49152
	ds_read_b128 v[188:191], v165 offset:50176
	ds_read_b128 v[192:195], v165 offset:51200
	ds_read_b128 v[196:199], v165 offset:52224
	ds_read_b128 v[206:209], v165 offset:53248
	ds_read_b128 v[210:213], v165 offset:54272
	ds_read_b128 v[214:217], v165 offset:55296
	ds_read_b128 v[218:221], v165 offset:56320
	global_load_lds_dwordx4 v[158:159], off
	s_add_i32 m0, s59, 0x2000
	s_add_u32 s60, s88, 0x40080
	v_lshl_add_u64 v[158:159], v[222:223], 0, s[70:71]
	s_addc_u32 s61, s89, 0
	s_add_i32 s59, s96, s11
	global_load_lds_dwordx4 v[158:159], off
	v_lshl_add_u64 v[158:159], s[60:61], 0, v[130:131]
	s_mov_b32 m0, s59
	s_nop 0
	global_load_lds_dwordx4 v[158:159], off
	v_lshl_add_u64 v[158:159], s[60:61], 0, v[134:135]
	s_add_i32 m0, s59, 0x2000
	s_nop 0
	global_load_lds_dwordx4 v[158:159], off
	v_lshl_add_u64 v[158:159], v[224:225], 0, s[70:71]
	s_mov_b32 m0, s31
	s_nop 0
	global_load_lds_dwordx4 v[158:159], off
	v_lshl_add_u64 v[158:159], v[226:227], 0, s[70:71]
	s_mov_b32 m0, s37
	s_nop 0
	global_load_lds_dwordx4 v[158:159], off
	s_waitcnt vmcnt(8)
	s_waitcnt lgkmcnt(0)
	s_barrier
	s_setprio 1
	s_waitcnt lgkmcnt(0)
	v_mfma_f32_16x16x32_bf16 v[60:63], v[140:143], v[184:187], v[60:63]
	v_mfma_f32_16x16x32_bf16 v[56:59], v[150:153], v[184:187], v[56:59]
	v_mfma_f32_16x16x32_bf16 v[40:43], v[150:153], v[192:195], v[40:43]
	v_mfma_f32_16x16x32_bf16 v[44:47], v[140:143], v[192:195], v[44:47]
	v_mfma_f32_16x16x32_bf16 v[28:31], v[140:143], v[206:209], v[28:31]
	v_mfma_f32_16x16x32_bf16 v[24:27], v[150:153], v[206:209], v[24:27]
	v_mfma_f32_16x16x32_bf16 v[8:11], v[150:153], v[214:217], v[8:11]
	v_mfma_f32_16x16x32_bf16 v[12:15], v[140:143], v[214:217], v[12:15]
	v_mfma_f32_16x16x32_bf16 v[60:63], v[146:149], v[188:191], v[60:63]
	v_mfma_f32_16x16x32_bf16 v[56:59], v[154:157], v[188:191], v[56:59]
	v_mfma_f32_16x16x32_bf16 v[40:43], v[154:157], v[196:199], v[40:43]
	v_mfma_f32_16x16x32_bf16 v[44:47], v[146:149], v[196:199], v[44:47]
	v_mfma_f32_16x16x32_bf16 v[28:31], v[146:149], v[210:213], v[28:31]
	v_mfma_f32_16x16x32_bf16 v[24:27], v[154:157], v[210:213], v[24:27]
	v_mfma_f32_16x16x32_bf16 v[8:11], v[154:157], v[218:221], v[8:11]
	v_mfma_f32_16x16x32_bf16 v[12:15], v[146:149], v[218:221], v[12:15]
	s_setprio 0
	s_setprio 1
	v_mfma_f32_16x16x32_bf16 v[52:55], v[168:171], v[184:187], v[52:55]
	v_mfma_f32_16x16x32_bf16 v[48:51], v[176:179], v[184:187], v[48:51]
	v_mfma_f32_16x16x32_bf16 v[32:35], v[176:179], v[192:195], v[32:35]
	v_mfma_f32_16x16x32_bf16 v[36:39], v[168:171], v[192:195], v[36:39]
	v_mfma_f32_16x16x32_bf16 v[20:23], v[168:171], v[206:209], v[20:23]
	v_mfma_f32_16x16x32_bf16 v[16:19], v[176:179], v[206:209], v[16:19]
	v_mfma_f32_16x16x32_bf16 v[0:3], v[176:179], v[214:217], v[0:3]
	v_mfma_f32_16x16x32_bf16 v[4:7], v[168:171], v[214:217], v[4:7]
	v_mfma_f32_16x16x32_bf16 v[52:55], v[172:175], v[188:191], v[52:55]
	v_mfma_f32_16x16x32_bf16 v[48:51], v[180:183], v[188:191], v[48:51]
	v_mfma_f32_16x16x32_bf16 v[32:35], v[180:183], v[196:199], v[32:35]
	v_mfma_f32_16x16x32_bf16 v[36:39], v[172:175], v[196:199], v[36:39]
	v_mfma_f32_16x16x32_bf16 v[20:23], v[172:175], v[210:213], v[20:23]
	v_mfma_f32_16x16x32_bf16 v[16:19], v[180:183], v[210:213], v[16:19]
	v_mfma_f32_16x16x32_bf16 v[0:3], v[180:183], v[218:221], v[0:3]
	v_mfma_f32_16x16x32_bf16 v[4:7], v[172:175], v[218:221], v[4:7]
	s_setprio 0
	s_barrier
	s_add_i32 s58, s58, 2
	s_add_u32 s86, s86, 0x100
	s_addc_u32 s87, s87, 0
	s_add_u32 vcc_lo, vcc_lo, 0x100
	s_addc_u32 vcc_hi, vcc_hi, 0
	s_cmp_gt_u32 s58, 13
	s_cbranch_scc0 .LBB0_958
	s_and_b64 vcc, exec, s[72:73]
	s_cbranch_vccz .LBB0_961
	s_barrier

; #define PG8_STAGE(bufoff, gbase, voff) do { _Pragma("unroll") for (int _i = 0; _i < 2; ++_i) \
;         __builtin_amdgcn_global_load_lds((const unsigned*)((const char*)(gbase) + (voff)[_i]), (PG8_LAS unsigned*)(lds + (bufoff) + ldsw + _i * 8192), 16, 0, 0); } while (0)
; #define PG8_LDA(dst, b, h) do { _Pragma("unroll") for (int m = 0; m < 4; ++m) _Pragma("unroll") for (int k = 0; k < 2; ++k) dst[m][k] = *(const PG8_LAS bf16x8*)(lds + PG8_SA(b, h) + aoff + m * 2048 + k * 1024); } while (0)
; #define PG8_LDB(dst, b, h) do { _Pragma("unroll") for (int n = 0; n < 2; ++n) _Pragma("unroll") for (int k = 0; k < 2; ++k) dst[n][k] = *(const PG8_LAS bf16x8*)(lds + PG8_SB(b, h) + boff + n * 2048 + k * 1024); } while (0)
; #define PG8_MMA(ai, bj, At, Bt) do { __builtin_amdgcn_s_setprio(1); _Pragma("unroll") for (int m = 0; m < 4; ++m) _Pragma("unroll") for (int n = 0; n < 2; ++n) _Pragma("unroll") for (int k = 0; k < 2; ++k) \
;         acc[ai][bj][m][n] = __builtin_amdgcn_mfma_f32_16x16x32_bf16(Bt[n][k], At[m][k], acc[ai][bj][m][n], 0, 0, 0); __builtin_amdgcn_s_setprio(0); } while (0)
; #define PG8_WAIT_V(n) asm volatile("s_waitcnt vmcnt(" #n ")" ::: "memory")
; #define PG8_WAIT_L(n) asm volatile("s_waitcnt lgkmcnt(" #n ")" ::: "memory")
; #define PG8_BAR __builtin_amdgcn_s_barrier()
; #define PG8_SCHED __builtin_amdgcn_sched_barrier(0)
; template <class Epi, class Sched, bool ALIGN_EPI = false, bool SP2 = false>
; __device__ __forceinline__ void gemm_phase(PG8_LAS unsigned char* lds, const Gemm g, const Sched& S, const Epi& E) {
;     ...
;             PG8_LDB(B0, 0, 0); PG8_LDB(B1, 0, 1); PG8_SCHED; PG8_LDA(At, 0, 0); PG8_STAGE(PG8_SA(1, 1), a1 + hstep, voffA);
;             PG8_WAIT_V(8); PG8_WAIT_L(0); PG8_BAR; PG8_MMA(0, 0, At, B0); PG8_MMA(0, 1, At, B1); PG8_BAR; PG8_SCHED;
;             PG8_LDA(At, 0, 1); PG8_STAGE(PG8_SB(0, 0), b2, voffB); PG8_STAGE(PG8_SB(0, 1), b2 + hstep, voffB); PG8_STAGE(PG8_SA(0, 0), a2, voffA);
.LBB0_1215:
	ds_read_b128 v[140:143], v149
	ds_read_b128 v[154:157], v149 offset:1024
	ds_read_b128 v[158:161], v149 offset:2048
	ds_read_b128 v[162:165], v149 offset:3072
	ds_read_b128 v[166:169], v150
	ds_read_b128 v[170:173], v150 offset:1024
	ds_read_b128 v[174:177], v150 offset:2048
	ds_read_b128 v[178:181], v150 offset:3072
	s_add_u32 s60, s58, 0xfffc0080
	s_addc_u32 s61, s59, -1
	s_cmp_eq_u32 s75, 12
	s_cselect_b32 s63, s17, s61
	s_cselect_b32 s62, s51, s60
	s_cselect_b32 s61, s19, s74
	s_cselect_b32 s60, s72, s73
	v_lshl_add_u64 v[144:145], s[58:59], 0, v[136:137]
	s_add_i32 m0, s28, 0xc000
	ds_read_b128 v[182:185], v151
	ds_read_b128 v[186:189], v151 offset:1024
	ds_read_b128 v[190:193], v151 offset:2048
	ds_read_b128 v[194:197], v151 offset:3072
	ds_read_b128 v[202:205], v151 offset:4096
	ds_read_b128 v[206:209], v151 offset:5120
	ds_read_b128 v[210:213], v151 offset:6144
	ds_read_b128 v[214:217], v151 offset:7168
	global_load_lds_dwordx4 v[144:145], off
	v_lshl_add_u64 v[144:145], s[58:59], 0, v[138:139]
	s_add_i32 m0, s28, 0xe000
	s_nop 0
	global_load_lds_dwordx4 v[144:145], off
	s_waitcnt vmcnt(8)
	s_waitcnt lgkmcnt(0)
	s_barrier
	s_setprio 1
	s_waitcnt lgkmcnt(0)
	v_mfma_f32_16x16x32_bf16 v[124:127], v[140:143], v[182:185], v[124:127]
	v_mfma_f32_16x16x32_bf16 v[120:123], v[158:161], v[182:185], v[120:123]
	v_mfma_f32_16x16x32_bf16 v[104:107], v[158:161], v[190:193], v[104:107]
	v_mfma_f32_16x16x32_bf16 v[108:111], v[140:143], v[190:193], v[108:111]
	v_mfma_f32_16x16x32_bf16 v[96:99], v[140:143], v[202:205], v[96:99]
	v_mfma_f32_16x16x32_bf16 v[88:91], v[158:161], v[202:205], v[88:91]
	v_mfma_f32_16x16x32_bf16 v[72:75], v[158:161], v[210:213], v[72:75]
	v_mfma_f32_16x16x32_bf16 v[80:83], v[140:143], v[210:213], v[80:83]
	v_mfma_f32_16x16x32_bf16 v[124:127], v[154:157], v[186:189], v[124:127]
	v_mfma_f32_16x16x32_bf16 v[120:123], v[162:165], v[186:189], v[120:123]
	v_mfma_f32_16x16x32_bf16 v[104:107], v[162:165], v[194:197], v[104:107]
	v_mfma_f32_16x16x32_bf16 v[108:111], v[154:157], v[194:197], v[108:111]
	v_mfma_f32_16x16x32_bf16 v[96:99], v[154:157], v[206:209], v[96:99]
	v_mfma_f32_16x16x32_bf16 v[88:91], v[162:165], v[206:209], v[88:91]
	v_mfma_f32_16x16x32_bf16 v[72:75], v[162:165], v[214:217], v[72:75]
	v_mfma_f32_16x16x32_bf16 v[80:83], v[154:157], v[214:217], v[80:83]
	s_setprio 0
	s_setprio 1
	v_mfma_f32_16x16x32_bf16 v[116:119], v[166:169], v[182:185], v[116:119]
	v_mfma_f32_16x16x32_bf16 v[112:115], v[174:177], v[182:185], v[112:115]
	v_mfma_f32_16x16x32_bf16 v[92:95], v[174:177], v[190:193], v[92:95]
	v_mfma_f32_16x16x32_bf16 v[100:103], v[166:169], v[190:193], v[100:103]
	v_mfma_f32_16x16x32_bf16 v[84:87], v[166:169], v[202:205], v[84:87]
	v_mfma_f32_16x16x32_bf16 v[76:79], v[174:177], v[202:205], v[76:79]
	v_mfma_f32_16x16x32_bf16 v[64:67], v[174:177], v[210:213], v[64:67]
	v_mfma_f32_16x16x32_bf16 v[68:71], v[166:169], v[210:213], v[68:71]
	v_mfma_f32_16x16x32_bf16 v[116:119], v[170:173], v[186:189], v[116:119]
	v_mfma_f32_16x16x32_bf16 v[112:115], v[178:181], v[186:189], v[112:115]
	v_mfma_f32_16x16x32_bf16 v[92:95], v[178:181], v[194:197], v[92:95]
	v_mfma_f32_16x16x32_bf16 v[100:103], v[170:173], v[194:197], v[100:103]
	v_mfma_f32_16x16x32_bf16 v[84:87], v[170:173], v[206:209], v[84:87]
	v_mfma_f32_16x16x32_bf16 v[76:79], v[178:181], v[206:209], v[76:79]
	v_mfma_f32_16x16x32_bf16 v[64:67], v[178:181], v[214:217], v[64:67]
	v_mfma_f32_16x16x32_bf16 v[68:71], v[170:173], v[214:217], v[68:71]
	s_setprio 0
	s_barrier
	s_add_i32 s76, s66, s21
	v_lshl_add_u64 v[144:145], s[60:61], 0, v[130:131]
	s_mov_b32 m0, s76
	ds_read_b128 v[182:185], v151 offset:16384
	ds_read_b128 v[186:189], v151 offset:17408
	ds_read_b128 v[190:193], v151 offset:18432
	ds_read_b128 v[194:197], v151 offset:19456
	ds_read_b128 v[202:205], v151 offset:20480
	ds_read_b128 v[206:209], v151 offset:21504
	ds_read_b128 v[210:213], v151 offset:22528
	ds_read_b128 v[214:217], v151 offset:23552
	global_load_lds_dwordx4 v[144:145], off
	s_add_i32 m0, s76, 0x2000
	s_add_u32 s76, s60, 0x40000
	v_lshl_add_u64 v[198:199], s[60:61], 0, v[134:135]
	s_addc_u32 s77, s61, 0
	s_add_i32 s78, s67, s21
	global_load_lds_dwordx4 v[198:199], off
	v_lshl_add_u64 v[218:219], s[76:77], 0, v[130:131]
	s_mov_b32 m0, s78
	v_lshl_add_u64 v[220:221], s[62:63], 0, v[132:133]
	global_load_lds_dwordx4 v[218:219], off
	v_lshl_add_u64 v[218:219], s[76:77], 0, v[134:135]
	s_add_i32 m0, s78, 0x2000
	s_nop 0
	global_load_lds_dwordx4 v[218:219], off
	v_lshl_add_u64 v[218:219], s[62:63], 0, v[128:129]
	s_mov_b32 m0, s28
	s_nop 0
	global_load_lds_dwordx4 v[218:219], off
	s_mov_b32 m0, s29
	s_nop 0
	global_load_lds_dwordx4 v[220:221], off
	s_waitcnt vmcnt(8)
	s_waitcnt lgkmcnt(0)
	s_barrier
; #define PG8_STAGE(bufoff, gbase, voff) do { _Pragma("unroll") for (int _i = 0; _i < 2; ++_i) \
;         __builtin_amdgcn_global_load_lds((const unsigned*)((const char*)(gbase) + (voff)[_i]), (PG8_LAS unsigned*)(lds + (bufoff) + ldsw + _i * 8192), 16, 0, 0); } while (0)
; #define PG8_LDA(dst, b, h) do { _Pragma("unroll") for (int m = 0; m < 4; ++m) _Pragma("unroll") for (int k = 0; k < 2; ++k) dst[m][k] = *(const PG8_LAS bf16x8*)(lds + PG8_SA(b, h) + aoff + m * 2048 + k * 1024); } while (0)
; #define PG8_LDB(dst, b, h) do { _Pragma("unroll") for (int n = 0; n < 2; ++n) _Pragma("unroll") for (int k = 0; k < 2; ++k) dst[n][k] = *(const PG8_LAS bf16x8*)(lds + PG8_SB(b, h) + boff + n * 2048 + k * 1024); } while (0)
; #define PG8_MMA(ai, bj, At, Bt) do { __builtin_amdgcn_s_setprio(1); _Pragma("unroll") for (int m = 0; m < 4; ++m) _Pragma("unroll") for (int n = 0; n < 2; ++n) _Pragma("unroll") for (int k = 0; k < 2; ++k) \
;         acc[ai][bj][m][n] = __builtin_amdgcn_mfma_f32_16x16x32_bf16(Bt[n][k], At[m][k], acc[ai][bj][m][n], 0, 0, 0); __builtin_amdgcn_s_setprio(0); } while (0)
; #define PG8_WAIT_V(n) asm volatile("s_waitcnt vmcnt(" #n ")" ::: "memory")
; #define PG8_WAIT_L(n) asm volatile("s_waitcnt lgkmcnt(" #n ")" ::: "memory")
; #define PG8_BAR __builtin_amdgcn_s_barrier()
; #define PG8_SCHED __builtin_amdgcn_sched_barrier(0)
; template <class Epi, class Sched, bool ALIGN_EPI = false, bool SP2 = false>
; __device__ __forceinline__ void gemm_phase(PG8_LAS unsigned char* lds, const Gemm g, const Sched& S, const Epi& E) {
;     ...
;             PG8_WAIT_V(8); PG8_WAIT_L(0); PG8_BAR; PG8_MMA(1, 0, At, B0); PG8_MMA(1, 1, At, B1); PG8_BAR; PG8_SCHED;
;             PG8_LDB(B0, 1, 0); PG8_LDB(B1, 1, 1); PG8_SCHED; PG8_LDA(At, 1, 0); PG8_STAGE(PG8_SA(0, 1), a2 + hstep, voffA);
;             PG8_WAIT_V(8); PG8_WAIT_L(0); PG8_BAR; PG8_MMA(0, 0, At, B0); PG8_MMA(0, 1, At, B1); PG8_BAR; PG8_SCHED;
	s_setprio 1
	s_waitcnt lgkmcnt(0)
	v_mfma_f32_16x16x32_bf16 v[60:63], v[140:143], v[182:185], v[60:63]
	v_mfma_f32_16x16x32_bf16 v[56:59], v[158:161], v[182:185], v[56:59]
	v_mfma_f32_16x16x32_bf16 v[40:43], v[158:161], v[190:193], v[40:43]
	v_mfma_f32_16x16x32_bf16 v[48:51], v[140:143], v[190:193], v[48:51]
	v_mfma_f32_16x16x32_bf16 v[32:35], v[140:143], v[202:205], v[32:35]
	v_mfma_f32_16x16x32_bf16 v[24:27], v[158:161], v[202:205], v[24:27]
	v_mfma_f32_16x16x32_bf16 v[8:11], v[158:161], v[210:213], v[8:11]
	v_mfma_f32_16x16x32_bf16 v[16:19], v[140:143], v[210:213], v[16:19]
	v_mfma_f32_16x16x32_bf16 v[60:63], v[154:157], v[186:189], v[60:63]
	v_mfma_f32_16x16x32_bf16 v[56:59], v[162:165], v[186:189], v[56:59]
	v_mfma_f32_16x16x32_bf16 v[40:43], v[162:165], v[194:197], v[40:43]
	v_mfma_f32_16x16x32_bf16 v[48:51], v[154:157], v[194:197], v[48:51]
	v_mfma_f32_16x16x32_bf16 v[32:35], v[154:157], v[206:209], v[32:35]
	v_mfma_f32_16x16x32_bf16 v[24:27], v[162:165], v[206:209], v[24:27]
	v_mfma_f32_16x16x32_bf16 v[8:11], v[162:165], v[214:217], v[8:11]
	v_mfma_f32_16x16x32_bf16 v[16:19], v[154:157], v[214:217], v[16:19]
	s_setprio 0
	s_setprio 1
	v_mfma_f32_16x16x32_bf16 v[52:55], v[166:169], v[182:185], v[52:55]
	v_mfma_f32_16x16x32_bf16 v[44:47], v[174:177], v[182:185], v[44:47]
	v_mfma_f32_16x16x32_bf16 v[28:31], v[174:177], v[190:193], v[28:31]
	v_mfma_f32_16x16x32_bf16 v[36:39], v[166:169], v[190:193], v[36:39]
	v_mfma_f32_16x16x32_bf16 v[20:23], v[166:169], v[202:205], v[20:23]
	v_mfma_f32_16x16x32_bf16 v[12:15], v[174:177], v[202:205], v[12:15]
	v_mfma_f32_16x16x32_bf16 v[0:3], v[174:177], v[210:213], v[0:3]
	v_mfma_f32_16x16x32_bf16 v[4:7], v[166:169], v[210:213], v[4:7]
	v_mfma_f32_16x16x32_bf16 v[52:55], v[170:173], v[186:189], v[52:55]
	v_mfma_f32_16x16x32_bf16 v[44:47], v[178:181], v[186:189], v[44:47]
	v_mfma_f32_16x16x32_bf16 v[28:31], v[178:181], v[194:197], v[28:31]
	v_mfma_f32_16x16x32_bf16 v[36:39], v[170:173], v[194:197], v[36:39]
	v_mfma_f32_16x16x32_bf16 v[20:23], v[170:173], v[206:209], v[20:23]
	v_mfma_f32_16x16x32_bf16 v[12:15], v[178:181], v[206:209], v[12:15]
	v_mfma_f32_16x16x32_bf16 v[0:3], v[178:181], v[214:217], v[0:3]
	v_mfma_f32_16x16x32_bf16 v[4:7], v[170:173], v[214:217], v[4:7]
	s_setprio 0
	s_barrier
	s_add_i32 s76, 0, 0x18000
	v_add_u32_e32 v153, s76, v147
	s_add_i32 s77, 0, 0x1c000
	ds_read_b128 v[140:143], v153
	ds_read_b128 v[154:157], v153 offset:1024
	ds_read_b128 v[158:161], v153 offset:2048
	ds_read_b128 v[162:165], v153 offset:3072
	v_add_u32_e32 v153, s77, v147
	ds_read_b128 v[166:169], v153
	ds_read_b128 v[170:173], v153 offset:1024
	ds_read_b128 v[174:177], v153 offset:2048
	ds_read_b128 v[178:181], v153 offset:3072
	s_add_u32 s62, s62, 0x40000
	s_addc_u32 s63, s63, 0
	s_mov_b32 m0, s30
	v_lshl_add_u64 v[222:223], s[62:63], 0, v[128:129]
	ds_read_b128 v[182:185], v151 offset:32768
	ds_read_b128 v[186:189], v151 offset:33792
	ds_read_b128 v[190:193], v151 offset:34816
	ds_read_b128 v[194:197], v151 offset:35840
	ds_read_b128 v[202:205], v151 offset:36864
	ds_read_b128 v[206:209], v151 offset:37888
	ds_read_b128 v[210:213], v151 offset:38912
	ds_read_b128 v[214:217], v151 offset:39936
	global_load_lds_dwordx4 v[222:223], off
	v_lshl_add_u64 v[222:223], s[62:63], 0, v[132:133]
	s_mov_b32 m0, s31
	s_nop 0
	global_load_lds_dwordx4 v[222:223], off
	s_waitcnt vmcnt(8)
	s_waitcnt lgkmcnt(0)
	s_barrier
	s_setprio 1
	s_waitcnt lgkmcnt(0)
	v_mfma_f32_16x16x32_bf16 v[124:127], v[140:143], v[182:185], v[124:127]
	v_mfma_f32_16x16x32_bf16 v[120:123], v[158:161], v[182:185], v[120:123]
	v_mfma_f32_16x16x32_bf16 v[104:107], v[158:161], v[190:193], v[104:107]
	v_mfma_f32_16x16x32_bf16 v[108:111], v[140:143], v[190:193], v[108:111]
	v_mfma_f32_16x16x32_bf16 v[96:99], v[140:143], v[202:205], v[96:99]
	v_mfma_f32_16x16x32_bf16 v[88:91], v[158:161], v[202:205], v[88:91]
	v_mfma_f32_16x16x32_bf16 v[72:75], v[158:161], v[210:213], v[72:75]
	v_mfma_f32_16x16x32_bf16 v[80:83], v[140:143], v[210:213], v[80:83]
	v_mfma_f32_16x16x32_bf16 v[124:127], v[154:157], v[186:189], v[124:127]
	v_mfma_f32_16x16x32_bf16 v[120:123], v[162:165], v[186:189], v[120:123]
	v_mfma_f32_16x16x32_bf16 v[104:107], v[162:165], v[194:197], v[104:107]
	v_mfma_f32_16x16x32_bf16 v[108:111], v[154:157], v[194:197], v[108:111]
	v_mfma_f32_16x16x32_bf16 v[96:99], v[154:157], v[206:209], v[96:99]
	v_mfma_f32_16x16x32_bf16 v[88:91], v[162:165], v[206:209], v[88:91]
	v_mfma_f32_16x16x32_bf16 v[72:75], v[162:165], v[214:217], v[72:75]
	v_mfma_f32_16x16x32_bf16 v[80:83], v[154:157], v[214:217], v[80:83]
	s_setprio 0
	s_setprio 1
	v_mfma_f32_16x16x32_bf16 v[116:119], v[166:169], v[182:185], v[116:119]
	v_mfma_f32_16x16x32_bf16 v[112:115], v[174:177], v[182:185], v[112:115]
	v_mfma_f32_16x16x32_bf16 v[92:95], v[174:177], v[190:193], v[92:95]
	v_mfma_f32_16x16x32_bf16 v[100:103], v[166:169], v[190:193], v[100:103]
	v_mfma_f32_16x16x32_bf16 v[84:87], v[166:169], v[202:205], v[84:87]
	v_mfma_f32_16x16x32_bf16 v[76:79], v[174:177], v[202:205], v[76:79]
	v_mfma_f32_16x16x32_bf16 v[64:67], v[174:177], v[210:213], v[64:67]
	v_mfma_f32_16x16x32_bf16 v[68:71], v[166:169], v[210:213], v[68:71]
	v_mfma_f32_16x16x32_bf16 v[116:119], v[170:173], v[186:189], v[116:119]
	v_mfma_f32_16x16x32_bf16 v[112:115], v[178:181], v[186:189], v[112:115]
	v_mfma_f32_16x16x32_bf16 v[92:95], v[178:181], v[194:197], v[92:95]
	v_mfma_f32_16x16x32_bf16 v[100:103], v[170:173], v[194:197], v[100:103]
	v_mfma_f32_16x16x32_bf16 v[84:87], v[170:173], v[206:209], v[84:87]
	v_mfma_f32_16x16x32_bf16 v[76:79], v[178:181], v[206:209], v[76:79]
	v_mfma_f32_16x16x32_bf16 v[64:67], v[178:181], v[214:217], v[64:67]
	v_mfma_f32_16x16x32_bf16 v[68:71], v[170:173], v[214:217], v[68:71]
	s_setprio 0
	s_barrier
; #define PG8_STAGE(bufoff, gbase, voff) do { _Pragma("unroll") for (int _i = 0; _i < 2; ++_i) \
;         __builtin_amdgcn_global_load_lds((const unsigned*)((const char*)(gbase) + (voff)[_i]), (PG8_LAS unsigned*)(lds + (bufoff) + ldsw + _i * 8192), 16, 0, 0); } while (0)
; #define PG8_LDA(dst, b, h) do { _Pragma("unroll") for (int m = 0; m < 4; ++m) _Pragma("unroll") for (int k = 0; k < 2; ++k) dst[m][k] = *(const PG8_LAS bf16x8*)(lds + PG8_SA(b, h) + aoff + m * 2048 + k * 1024); } while (0)
; #define PG8_MMA(ai, bj, At, Bt) do { __builtin_amdgcn_s_setprio(1); _Pragma("unroll") for (int m = 0; m < 4; ++m) _Pragma("unroll") for (int n = 0; n < 2; ++n) _Pragma("unroll") for (int k = 0; k < 2; ++k) \
;         acc[ai][bj][m][n] = __builtin_amdgcn_mfma_f32_16x16x32_bf16(Bt[n][k], At[m][k], acc[ai][bj][m][n], 0, 0, 0); __builtin_amdgcn_s_setprio(0); } while (0)
; #define PG8_WAIT_V(n) asm volatile("s_waitcnt vmcnt(" #n ")" ::: "memory")
; #define PG8_WAIT_L(n) asm volatile("s_waitcnt lgkmcnt(" #n ")" ::: "memory")
; #define PG8_BAR __builtin_amdgcn_s_barrier()
; #define PG8_SCHED __builtin_amdgcn_sched_barrier(0)
; template <class Epi, class Sched, bool ALIGN_EPI = false, bool SP2 = false>
; __device__ __forceinline__ void gemm_phase(PG8_LAS unsigned char* lds, const Gemm g, const Sched& S, const Epi& E) {
;     ...
;         for (int t = 0; t < nt; t += 2) {
;             const bool last = (t == nt - 2);
;             const char* a1 = cA + (size_t)(t + 1) * kstep;
;             const char* a2 = last ? nA : cA + (size_t)(t + 2) * kstep; const char* b2 = last ? nB : cB + (size_t)(t + 2) * kstep;
;             const char* a3 = a2 + kstep; const char* b3 = b2 + kstep;
;     ...
;             PG8_LDA(At, 1, 1); PG8_STAGE(PG8_SB(1, 0), b3, voffB); PG8_STAGE(PG8_SB(1, 1), b3 + hstep, voffB); PG8_STAGE(PG8_SA(1, 0), a3, voffA);
;             PG8_WAIT_V(8); PG8_WAIT_L(0); PG8_BAR; PG8_MMA(1, 0, At, B0); PG8_MMA(1, 1, At, B1); PG8_BAR; PG8_SCHED;
	s_add_i32 s62, s76, s21
	v_lshl_add_u64 v[144:145], v[144:145], 0, s[12:13]
	s_mov_b32 m0, s62
	ds_read_b128 v[182:185], v151 offset:49152
	ds_read_b128 v[186:189], v151 offset:50176
	ds_read_b128 v[190:193], v151 offset:51200
	ds_read_b128 v[194:197], v151 offset:52224
	ds_read_b128 v[202:205], v151 offset:53248
	ds_read_b128 v[206:209], v151 offset:54272
	ds_read_b128 v[210:213], v151 offset:55296
	ds_read_b128 v[214:217], v151 offset:56320
	global_load_lds_dwordx4 v[144:145], off
	s_add_i32 m0, s62, 0x2000
	s_add_u32 s60, s60, 0x40080
	v_lshl_add_u64 v[144:145], v[198:199], 0, s[12:13]
	s_addc_u32 s61, s61, 0
	s_add_i32 s62, s77, s21
	global_load_lds_dwordx4 v[144:145], off
	v_lshl_add_u64 v[144:145], s[60:61], 0, v[130:131]
	s_mov_b32 m0, s62
	s_nop 0
	global_load_lds_dwordx4 v[144:145], off
	v_lshl_add_u64 v[144:145], s[60:61], 0, v[134:135]
	s_add_i32 m0, s62, 0x2000
	s_nop 0
	global_load_lds_dwordx4 v[144:145], off
	v_lshl_add_u64 v[144:145], v[218:219], 0, s[12:13]
	s_mov_b32 m0, s57
	s_nop 0
	global_load_lds_dwordx4 v[144:145], off
	v_lshl_add_u64 v[144:145], v[220:221], 0, s[12:13]
	s_mov_b32 m0, s64
	s_nop 0
	global_load_lds_dwordx4 v[144:145], off
	s_waitcnt vmcnt(8)
	s_waitcnt lgkmcnt(0)
	s_barrier
	s_setprio 1
	s_waitcnt lgkmcnt(0)
	v_mfma_f32_16x16x32_bf16 v[60:63], v[140:143], v[182:185], v[60:63]
	v_mfma_f32_16x16x32_bf16 v[56:59], v[158:161], v[182:185], v[56:59]
	v_mfma_f32_16x16x32_bf16 v[40:43], v[158:161], v[190:193], v[40:43]
	v_mfma_f32_16x16x32_bf16 v[48:51], v[140:143], v[190:193], v[48:51]
	v_mfma_f32_16x16x32_bf16 v[32:35], v[140:143], v[202:205], v[32:35]
	v_mfma_f32_16x16x32_bf16 v[24:27], v[158:161], v[202:205], v[24:27]
	v_mfma_f32_16x16x32_bf16 v[8:11], v[158:161], v[210:213], v[8:11]
	v_mfma_f32_16x16x32_bf16 v[16:19], v[140:143], v[210:213], v[16:19]
	v_mfma_f32_16x16x32_bf16 v[60:63], v[154:157], v[186:189], v[60:63]
	v_mfma_f32_16x16x32_bf16 v[56:59], v[162:165], v[186:189], v[56:59]
	v_mfma_f32_16x16x32_bf16 v[40:43], v[162:165], v[194:197], v[40:43]
	v_mfma_f32_16x16x32_bf16 v[48:51], v[154:157], v[194:197], v[48:51]
	v_mfma_f32_16x16x32_bf16 v[32:35], v[154:157], v[206:209], v[32:35]
	v_mfma_f32_16x16x32_bf16 v[24:27], v[162:165], v[206:209], v[24:27]
	v_mfma_f32_16x16x32_bf16 v[8:11], v[162:165], v[214:217], v[8:11]
	v_mfma_f32_16x16x32_bf16 v[16:19], v[154:157], v[214:217], v[16:19]
	s_setprio 0
	s_setprio 1
	v_mfma_f32_16x16x32_bf16 v[52:55], v[166:169], v[182:185], v[52:55]
	v_mfma_f32_16x16x32_bf16 v[44:47], v[174:177], v[182:185], v[44:47]
	v_mfma_f32_16x16x32_bf16 v[28:31], v[174:177], v[190:193], v[28:31]
	v_mfma_f32_16x16x32_bf16 v[36:39], v[166:169], v[190:193], v[36:39]
	v_mfma_f32_16x16x32_bf16 v[20:23], v[166:169], v[202:205], v[20:23]
	v_mfma_f32_16x16x32_bf16 v[12:15], v[174:177], v[202:205], v[12:15]
	v_mfma_f32_16x16x32_bf16 v[0:3], v[174:177], v[210:213], v[0:3]
	v_mfma_f32_16x16x32_bf16 v[4:7], v[166:169], v[210:213], v[4:7]
	v_mfma_f32_16x16x32_bf16 v[52:55], v[170:173], v[186:189], v[52:55]
	v_mfma_f32_16x16x32_bf16 v[44:47], v[178:181], v[186:189], v[44:47]
	v_mfma_f32_16x16x32_bf16 v[28:31], v[178:181], v[194:197], v[28:31]
	v_mfma_f32_16x16x32_bf16 v[36:39], v[170:173], v[194:197], v[36:39]
	v_mfma_f32_16x16x32_bf16 v[20:23], v[170:173], v[206:209], v[20:23]
	v_mfma_f32_16x16x32_bf16 v[12:15], v[178:181], v[206:209], v[12:15]
	v_mfma_f32_16x16x32_bf16 v[0:3], v[178:181], v[214:217], v[0:3]
	v_mfma_f32_16x16x32_bf16 v[4:7], v[170:173], v[214:217], v[4:7]
	s_setprio 0
	s_barrier
	s_add_i32 s75, s75, 2
	s_add_u32 s58, s58, 0x100
	s_addc_u32 s59, s59, 0
	s_add_u32 s73, s73, 0x100
	s_addc_u32 s74, s74, 0
	s_cmp_gt_u32 s75, 13
	s_cbranch_scc0 .LBB0_1215
	s_and_b64 vcc, exec, s[14:15]
	s_cbranch_vccz .LBB0_1218
	s_barrier

; #define PG8_STAGE(bufoff, gbase, voff) do { _Pragma("unroll") for (int _i = 0; _i < 2; ++_i) \
;         __builtin_amdgcn_global_load_lds((const unsigned*)((const char*)(gbase) + (voff)[_i]), (PG8_LAS unsigned*)(lds + (bufoff) + ldsw + _i * 8192), 16, 0, 0); } while (0)
; #define PG8_LDA(dst, b, h) do { _Pragma("unroll") for (int m = 0; m < 4; ++m) _Pragma("unroll") for (int k = 0; k < 2; ++k) dst[m][k] = *(const PG8_LAS bf16x8*)(lds + PG8_SA(b, h) + aoff + m * 2048 + k * 1024); } while (0)
; #define PG8_LDB(dst, b, h) do { _Pragma("unroll") for (int n = 0; n < 2; ++n) _Pragma("unroll") for (int k = 0; k < 2; ++k) dst[n][k] = *(const PG8_LAS bf16x8*)(lds + PG8_SB(b, h) + boff + n * 2048 + k * 1024); } while (0)
; #define PG8_MMA(ai, bj, At, Bt) do { __builtin_amdgcn_s_setprio(1); _Pragma("unroll") for (int m = 0; m < 4; ++m) _Pragma("unroll") for (int n = 0; n < 2; ++n) _Pragma("unroll") for (int k = 0; k < 2; ++k) \
;         acc[ai][bj][m][n] = __builtin_amdgcn_mfma_f32_16x16x32_bf16(Bt[n][k], At[m][k], acc[ai][bj][m][n], 0, 0, 0); __builtin_amdgcn_s_setprio(0); } while (0)
; #define PG8_WAIT_V(n) asm volatile("s_waitcnt vmcnt(" #n ")" ::: "memory")
; #define PG8_WAIT_L(n) asm volatile("s_waitcnt lgkmcnt(" #n ")" ::: "memory")
; #define PG8_BAR __builtin_amdgcn_s_barrier()
; #define PG8_SCHED __builtin_amdgcn_sched_barrier(0)
; template <class Epi, class Sched, bool ALIGN_EPI = false, bool SP2 = false>
; __device__ __forceinline__ void gemm_phase(PG8_LAS unsigned char* lds, const Gemm g, const Sched& S, const Epi& E) {
;     ...
;             PG8_LDB(B0, 0, 0); PG8_LDB(B1, 0, 1); PG8_SCHED; PG8_LDA(At, 0, 0); PG8_STAGE(PG8_SA(1, 1), a1 + hstep, voffA);
;             PG8_WAIT_V(8); PG8_WAIT_L(0); PG8_BAR; PG8_MMA(0, 0, At, B0); PG8_MMA(0, 1, At, B1); PG8_BAR; PG8_SCHED;
;             PG8_LDA(At, 0, 1); PG8_STAGE(PG8_SB(0, 0), b2, voffB); PG8_STAGE(PG8_SB(0, 1), b2 + hstep, voffB); PG8_STAGE(PG8_SA(0, 0), a2, voffA);
.LBB0_1293:
	ds_read_b128 v[140:143], v189
	ds_read_b128 v[144:147], v189 offset:1024
	ds_read_b128 v[148:151], v189 offset:2048
	ds_read_b128 v[152:155], v189 offset:3072
	ds_read_b128 v[156:159], v190
	ds_read_b128 v[160:163], v190 offset:1024
	ds_read_b128 v[164:167], v190 offset:2048
	ds_read_b128 v[168:171], v190 offset:3072
	s_add_u32 s50, s48, 0xfffc0080
	s_addc_u32 s51, s49, -1
	s_cmp_eq_u32 s66, 12
	s_cselect_b32 s57, s3, s51
	s_cselect_b32 s56, s17, s50
	s_cselect_b32 s51, s19, s65
	s_cselect_b32 s50, s63, s64
	v_lshl_add_u64 v[184:185], s[48:49], 0, v[136:137]
	s_add_i32 m0, s28, 0xc000
	ds_read_b128 v[172:175], v191
	ds_read_b128 v[176:179], v191 offset:1024
	ds_read_b128 v[180:183], v191 offset:2048
	ds_read_b128 v[194:197], v191 offset:3072
	ds_read_b128 v[202:205], v191 offset:4096
	ds_read_b128 v[206:209], v191 offset:5120
	ds_read_b128 v[210:213], v191 offset:6144
	ds_read_b128 v[214:217], v191 offset:7168
	global_load_lds_dwordx4 v[184:185], off
	v_lshl_add_u64 v[184:185], s[48:49], 0, v[138:139]
	s_add_i32 m0, s28, 0xe000
	s_nop 0
	global_load_lds_dwordx4 v[184:185], off
	s_waitcnt vmcnt(8)
	s_waitcnt lgkmcnt(0)
	s_barrier
	s_setprio 1
	s_waitcnt lgkmcnt(0)
	v_mfma_f32_16x16x32_bf16 v[124:127], v[140:143], v[172:175], v[124:127]
	v_mfma_f32_16x16x32_bf16 v[120:123], v[148:151], v[172:175], v[120:123]
	v_mfma_f32_16x16x32_bf16 v[104:107], v[148:151], v[180:183], v[104:107]
	v_mfma_f32_16x16x32_bf16 v[108:111], v[140:143], v[180:183], v[108:111]
	v_mfma_f32_16x16x32_bf16 v[92:95], v[140:143], v[202:205], v[92:95]
	v_mfma_f32_16x16x32_bf16 v[88:91], v[148:151], v[202:205], v[88:91]
	v_mfma_f32_16x16x32_bf16 v[72:75], v[148:151], v[210:213], v[72:75]
	v_mfma_f32_16x16x32_bf16 v[76:79], v[140:143], v[210:213], v[76:79]
	v_mfma_f32_16x16x32_bf16 v[124:127], v[144:147], v[176:179], v[124:127]
	v_mfma_f32_16x16x32_bf16 v[120:123], v[152:155], v[176:179], v[120:123]
	v_mfma_f32_16x16x32_bf16 v[104:107], v[152:155], v[194:197], v[104:107]
	v_mfma_f32_16x16x32_bf16 v[108:111], v[144:147], v[194:197], v[108:111]
	v_mfma_f32_16x16x32_bf16 v[92:95], v[144:147], v[206:209], v[92:95]
	v_mfma_f32_16x16x32_bf16 v[88:91], v[152:155], v[206:209], v[88:91]
	v_mfma_f32_16x16x32_bf16 v[72:75], v[152:155], v[214:217], v[72:75]
	v_mfma_f32_16x16x32_bf16 v[76:79], v[144:147], v[214:217], v[76:79]
	s_setprio 0
	s_setprio 1
	v_mfma_f32_16x16x32_bf16 v[116:119], v[156:159], v[172:175], v[116:119]
	v_mfma_f32_16x16x32_bf16 v[112:115], v[164:167], v[172:175], v[112:115]
	v_mfma_f32_16x16x32_bf16 v[96:99], v[164:167], v[180:183], v[96:99]
	v_mfma_f32_16x16x32_bf16 v[100:103], v[156:159], v[180:183], v[100:103]
	v_mfma_f32_16x16x32_bf16 v[84:87], v[156:159], v[202:205], v[84:87]
	v_mfma_f32_16x16x32_bf16 v[80:83], v[164:167], v[202:205], v[80:83]
	v_mfma_f32_16x16x32_bf16 v[64:67], v[164:167], v[210:213], v[64:67]
	v_mfma_f32_16x16x32_bf16 v[68:71], v[156:159], v[210:213], v[68:71]
	v_mfma_f32_16x16x32_bf16 v[116:119], v[160:163], v[176:179], v[116:119]
	v_mfma_f32_16x16x32_bf16 v[112:115], v[168:171], v[176:179], v[112:115]
	v_mfma_f32_16x16x32_bf16 v[96:99], v[168:171], v[194:197], v[96:99]
	v_mfma_f32_16x16x32_bf16 v[100:103], v[160:163], v[194:197], v[100:103]
	v_mfma_f32_16x16x32_bf16 v[84:87], v[160:163], v[206:209], v[84:87]
	v_mfma_f32_16x16x32_bf16 v[80:83], v[168:171], v[206:209], v[80:83]
	v_mfma_f32_16x16x32_bf16 v[64:67], v[168:171], v[214:217], v[64:67]
	v_mfma_f32_16x16x32_bf16 v[68:71], v[160:163], v[214:217], v[68:71]
	s_setprio 0
	s_barrier
	s_add_i32 s67, s59, s21
	v_lshl_add_u64 v[184:185], s[50:51], 0, v[132:133]
	s_mov_b32 m0, s67
	ds_read_b128 v[172:175], v191 offset:16384
	ds_read_b128 v[176:179], v191 offset:17408
	ds_read_b128 v[180:183], v191 offset:18432
	ds_read_b128 v[194:197], v191 offset:19456
	ds_read_b128 v[202:205], v191 offset:20480
	ds_read_b128 v[206:209], v191 offset:21504
	ds_read_b128 v[210:213], v191 offset:22528
	ds_read_b128 v[214:217], v191 offset:23552
	global_load_lds_dwordx4 v[184:185], off
	s_add_i32 m0, s67, 0x2000
	s_add_u32 s68, s50, 0x40000
	v_lshl_add_u64 v[198:199], s[50:51], 0, v[128:129]
	s_addc_u32 s69, s51, 0
	s_add_i32 s67, s60, s21
	global_load_lds_dwordx4 v[198:199], off
	v_lshl_add_u64 v[218:219], s[68:69], 0, v[132:133]
	s_mov_b32 m0, s67
	v_lshl_add_u64 v[220:221], s[56:57], 0, v[130:131]
	global_load_lds_dwordx4 v[218:219], off
	v_lshl_add_u64 v[218:219], s[68:69], 0, v[128:129]
	s_add_i32 m0, s67, 0x2000
	s_nop 0
	global_load_lds_dwordx4 v[218:219], off
	v_lshl_add_u64 v[218:219], s[56:57], 0, v[134:135]
	s_mov_b32 m0, s28
	s_nop 0
	global_load_lds_dwordx4 v[218:219], off
	s_mov_b32 m0, s29
	s_nop 0
	global_load_lds_dwordx4 v[220:221], off
	s_waitcnt vmcnt(8)
	s_waitcnt lgkmcnt(0)
	s_barrier
; #define PG8_STAGE(bufoff, gbase, voff) do { _Pragma("unroll") for (int _i = 0; _i < 2; ++_i) \
;         __builtin_amdgcn_global_load_lds((const unsigned*)((const char*)(gbase) + (voff)[_i]), (PG8_LAS unsigned*)(lds + (bufoff) + ldsw + _i * 8192), 16, 0, 0); } while (0)
; #define PG8_LDA(dst, b, h) do { _Pragma("unroll") for (int m = 0; m < 4; ++m) _Pragma("unroll") for (int k = 0; k < 2; ++k) dst[m][k] = *(const PG8_LAS bf16x8*)(lds + PG8_SA(b, h) + aoff + m * 2048 + k * 1024); } while (0)
; #define PG8_LDB(dst, b, h) do { _Pragma("unroll") for (int n = 0; n < 2; ++n) _Pragma("unroll") for (int k = 0; k < 2; ++k) dst[n][k] = *(const PG8_LAS bf16x8*)(lds + PG8_SB(b, h) + boff + n * 2048 + k * 1024); } while (0)
; #define PG8_MMA(ai, bj, At, Bt) do { __builtin_amdgcn_s_setprio(1); _Pragma("unroll") for (int m = 0; m < 4; ++m) _Pragma("unroll") for (int n = 0; n < 2; ++n) _Pragma("unroll") for (int k = 0; k < 2; ++k) \
;         acc[ai][bj][m][n] = __builtin_amdgcn_mfma_f32_16x16x32_bf16(Bt[n][k], At[m][k], acc[ai][bj][m][n], 0, 0, 0); __builtin_amdgcn_s_setprio(0); } while (0)
; #define PG8_WAIT_V(n) asm volatile("s_waitcnt vmcnt(" #n ")" ::: "memory")
; #define PG8_WAIT_L(n) asm volatile("s_waitcnt lgkmcnt(" #n ")" ::: "memory")
; #define PG8_BAR __builtin_amdgcn_s_barrier()
; #define PG8_SCHED __builtin_amdgcn_sched_barrier(0)
; template <class Epi, class Sched, bool ALIGN_EPI = false, bool SP2 = false>
; __device__ __forceinline__ void gemm_phase(PG8_LAS unsigned char* lds, const Gemm g, const Sched& S, const Epi& E) {
;     ...
;             PG8_WAIT_V(8); PG8_WAIT_L(0); PG8_BAR; PG8_MMA(1, 0, At, B0); PG8_MMA(1, 1, At, B1); PG8_BAR; PG8_SCHED;
;             PG8_LDB(B0, 1, 0); PG8_LDB(B1, 1, 1); PG8_SCHED; PG8_LDA(At, 1, 0); PG8_STAGE(PG8_SA(0, 1), a2 + hstep, voffA);
;             PG8_WAIT_V(8); PG8_WAIT_L(0); PG8_BAR; PG8_MMA(0, 0, At, B0); PG8_MMA(0, 1, At, B1); PG8_BAR; PG8_SCHED;
	s_setprio 1
	s_waitcnt lgkmcnt(0)
	v_mfma_f32_16x16x32_bf16 v[60:63], v[140:143], v[172:175], v[60:63]
	v_mfma_f32_16x16x32_bf16 v[56:59], v[148:151], v[172:175], v[56:59]
	v_mfma_f32_16x16x32_bf16 v[40:43], v[148:151], v[180:183], v[40:43]
	v_mfma_f32_16x16x32_bf16 v[44:47], v[140:143], v[180:183], v[44:47]
	v_mfma_f32_16x16x32_bf16 v[28:31], v[140:143], v[202:205], v[28:31]
	v_mfma_f32_16x16x32_bf16 v[24:27], v[148:151], v[202:205], v[24:27]
	v_mfma_f32_16x16x32_bf16 v[8:11], v[148:151], v[210:213], v[8:11]
	v_mfma_f32_16x16x32_bf16 v[12:15], v[140:143], v[210:213], v[12:15]
	v_mfma_f32_16x16x32_bf16 v[60:63], v[144:147], v[176:179], v[60:63]
	v_mfma_f32_16x16x32_bf16 v[56:59], v[152:155], v[176:179], v[56:59]
	v_mfma_f32_16x16x32_bf16 v[40:43], v[152:155], v[194:197], v[40:43]
	v_mfma_f32_16x16x32_bf16 v[44:47], v[144:147], v[194:197], v[44:47]
	v_mfma_f32_16x16x32_bf16 v[28:31], v[144:147], v[206:209], v[28:31]
	v_mfma_f32_16x16x32_bf16 v[24:27], v[152:155], v[206:209], v[24:27]
	v_mfma_f32_16x16x32_bf16 v[8:11], v[152:155], v[214:217], v[8:11]
	v_mfma_f32_16x16x32_bf16 v[12:15], v[144:147], v[214:217], v[12:15]
	s_setprio 0
	s_setprio 1
	v_mfma_f32_16x16x32_bf16 v[52:55], v[156:159], v[172:175], v[52:55]
	v_mfma_f32_16x16x32_bf16 v[48:51], v[164:167], v[172:175], v[48:51]
	v_mfma_f32_16x16x32_bf16 v[32:35], v[164:167], v[180:183], v[32:35]
	v_mfma_f32_16x16x32_bf16 v[36:39], v[156:159], v[180:183], v[36:39]
	v_mfma_f32_16x16x32_bf16 v[20:23], v[156:159], v[202:205], v[20:23]
	v_mfma_f32_16x16x32_bf16 v[16:19], v[164:167], v[202:205], v[16:19]
	v_mfma_f32_16x16x32_bf16 v[0:3], v[164:167], v[210:213], v[0:3]
	v_mfma_f32_16x16x32_bf16 v[4:7], v[156:159], v[210:213], v[4:7]
	v_mfma_f32_16x16x32_bf16 v[52:55], v[160:163], v[176:179], v[52:55]
	v_mfma_f32_16x16x32_bf16 v[48:51], v[168:171], v[176:179], v[48:51]
	v_mfma_f32_16x16x32_bf16 v[32:35], v[168:171], v[194:197], v[32:35]
	v_mfma_f32_16x16x32_bf16 v[36:39], v[160:163], v[194:197], v[36:39]
	v_mfma_f32_16x16x32_bf16 v[20:23], v[160:163], v[206:209], v[20:23]
	v_mfma_f32_16x16x32_bf16 v[16:19], v[168:171], v[206:209], v[16:19]
	v_mfma_f32_16x16x32_bf16 v[0:3], v[168:171], v[214:217], v[0:3]
	v_mfma_f32_16x16x32_bf16 v[4:7], v[160:163], v[214:217], v[4:7]
	s_setprio 0
	s_barrier
	s_add_i32 s67, 0, 0x18000
	s_add_i32 s68, 0, 0x1c000
	v_add_u32_e32 v152, s67, v187
	v_add_u32_e32 v168, s68, v187
	ds_read_b128 v[140:143], v152
	ds_read_b128 v[144:147], v152 offset:1024
	ds_read_b128 v[148:151], v152 offset:2048
	ds_read_b128 v[152:155], v152 offset:3072
	ds_read_b128 v[156:159], v168
	ds_read_b128 v[160:163], v168 offset:1024
	ds_read_b128 v[164:167], v168 offset:2048
	ds_read_b128 v[168:171], v168 offset:3072
	s_add_u32 s56, s56, 0x40000
	s_addc_u32 s57, s57, 0
	s_mov_b32 m0, s30
	v_lshl_add_u64 v[222:223], s[56:57], 0, v[134:135]
	ds_read_b128 v[172:175], v191 offset:32768
	ds_read_b128 v[176:179], v191 offset:33792
	ds_read_b128 v[180:183], v191 offset:34816
	ds_read_b128 v[194:197], v191 offset:35840
	ds_read_b128 v[202:205], v191 offset:36864
	ds_read_b128 v[206:209], v191 offset:37888
	ds_read_b128 v[210:213], v191 offset:38912
	ds_read_b128 v[214:217], v191 offset:39936
	global_load_lds_dwordx4 v[222:223], off
	v_lshl_add_u64 v[222:223], s[56:57], 0, v[130:131]
	s_mov_b32 m0, s31
	s_nop 0
	global_load_lds_dwordx4 v[222:223], off
	s_waitcnt vmcnt(8)
	s_waitcnt lgkmcnt(0)
	s_barrier
	s_setprio 1
	s_waitcnt lgkmcnt(0)
	v_mfma_f32_16x16x32_bf16 v[124:127], v[140:143], v[172:175], v[124:127]
	v_mfma_f32_16x16x32_bf16 v[120:123], v[148:151], v[172:175], v[120:123]
	v_mfma_f32_16x16x32_bf16 v[104:107], v[148:151], v[180:183], v[104:107]
	v_mfma_f32_16x16x32_bf16 v[108:111], v[140:143], v[180:183], v[108:111]
	v_mfma_f32_16x16x32_bf16 v[92:95], v[140:143], v[202:205], v[92:95]
	v_mfma_f32_16x16x32_bf16 v[88:91], v[148:151], v[202:205], v[88:91]
	v_mfma_f32_16x16x32_bf16 v[72:75], v[148:151], v[210:213], v[72:75]
	v_mfma_f32_16x16x32_bf16 v[76:79], v[140:143], v[210:213], v[76:79]
	v_mfma_f32_16x16x32_bf16 v[124:127], v[144:147], v[176:179], v[124:127]
	v_mfma_f32_16x16x32_bf16 v[120:123], v[152:155], v[176:179], v[120:123]
	v_mfma_f32_16x16x32_bf16 v[104:107], v[152:155], v[194:197], v[104:107]
	v_mfma_f32_16x16x32_bf16 v[108:111], v[144:147], v[194:197], v[108:111]
	v_mfma_f32_16x16x32_bf16 v[92:95], v[144:147], v[206:209], v[92:95]
	v_mfma_f32_16x16x32_bf16 v[88:91], v[152:155], v[206:209], v[88:91]
	v_mfma_f32_16x16x32_bf16 v[72:75], v[152:155], v[214:217], v[72:75]
	v_mfma_f32_16x16x32_bf16 v[76:79], v[144:147], v[214:217], v[76:79]
	s_setprio 0
	s_setprio 1
	v_mfma_f32_16x16x32_bf16 v[116:119], v[156:159], v[172:175], v[116:119]
	v_mfma_f32_16x16x32_bf16 v[112:115], v[164:167], v[172:175], v[112:115]
	v_mfma_f32_16x16x32_bf16 v[96:99], v[164:167], v[180:183], v[96:99]
	v_mfma_f32_16x16x32_bf16 v[100:103], v[156:159], v[180:183], v[100:103]
	v_mfma_f32_16x16x32_bf16 v[84:87], v[156:159], v[202:205], v[84:87]
	v_mfma_f32_16x16x32_bf16 v[80:83], v[164:167], v[202:205], v[80:83]
	v_mfma_f32_16x16x32_bf16 v[64:67], v[164:167], v[210:213], v[64:67]
	v_mfma_f32_16x16x32_bf16 v[68:71], v[156:159], v[210:213], v[68:71]
	v_mfma_f32_16x16x32_bf16 v[116:119], v[160:163], v[176:179], v[116:119]
	v_mfma_f32_16x16x32_bf16 v[112:115], v[168:171], v[176:179], v[112:115]
	v_mfma_f32_16x16x32_bf16 v[96:99], v[168:171], v[194:197], v[96:99]
	v_mfma_f32_16x16x32_bf16 v[100:103], v[160:163], v[194:197], v[100:103]
	v_mfma_f32_16x16x32_bf16 v[84:87], v[160:163], v[206:209], v[84:87]
	v_mfma_f32_16x16x32_bf16 v[80:83], v[168:171], v[206:209], v[80:83]
	v_mfma_f32_16x16x32_bf16 v[64:67], v[168:171], v[214:217], v[64:67]
	v_mfma_f32_16x16x32_bf16 v[68:71], v[160:163], v[214:217], v[68:71]
	s_setprio 0
	s_barrier
; #define PG8_STAGE(bufoff, gbase, voff) do { _Pragma("unroll") for (int _i = 0; _i < 2; ++_i) \
;         __builtin_amdgcn_global_load_lds((const unsigned*)((const char*)(gbase) + (voff)[_i]), (PG8_LAS unsigned*)(lds + (bufoff) + ldsw + _i * 8192), 16, 0, 0); } while (0)
; #define PG8_LDA(dst, b, h) do { _Pragma("unroll") for (int m = 0; m < 4; ++m) _Pragma("unroll") for (int k = 0; k < 2; ++k) dst[m][k] = *(const PG8_LAS bf16x8*)(lds + PG8_SA(b, h) + aoff + m * 2048 + k * 1024); } while (0)
; #define PG8_MMA(ai, bj, At, Bt) do { __builtin_amdgcn_s_setprio(1); _Pragma("unroll") for (int m = 0; m < 4; ++m) _Pragma("unroll") for (int n = 0; n < 2; ++n) _Pragma("unroll") for (int k = 0; k < 2; ++k) \
;         acc[ai][bj][m][n] = __builtin_amdgcn_mfma_f32_16x16x32_bf16(Bt[n][k], At[m][k], acc[ai][bj][m][n], 0, 0, 0); __builtin_amdgcn_s_setprio(0); } while (0)
; #define PG8_WAIT_V(n) asm volatile("s_waitcnt vmcnt(" #n ")" ::: "memory")
; #define PG8_WAIT_L(n) asm volatile("s_waitcnt lgkmcnt(" #n ")" ::: "memory")
; #define PG8_BAR __builtin_amdgcn_s_barrier()
; #define PG8_SCHED __builtin_amdgcn_sched_barrier(0)
; template <class Epi, class Sched, bool ALIGN_EPI = false, bool SP2 = false>
; __device__ __forceinline__ void gemm_phase(PG8_LAS unsigned char* lds, const Gemm g, const Sched& S, const Epi& E) {
;     ...
;         for (int t = 0; t < nt; t += 2) {
;             const bool last = (t == nt - 2);
;             const char* a1 = cA + (size_t)(t + 1) * kstep;
;             const char* a2 = last ? nA : cA + (size_t)(t + 2) * kstep; const char* b2 = last ? nB : cB + (size_t)(t + 2) * kstep;
;             const char* a3 = a2 + kstep; const char* b3 = b2 + kstep;
;     ...
;             PG8_LDA(At, 1, 1); PG8_STAGE(PG8_SB(1, 0), b3, voffB); PG8_STAGE(PG8_SB(1, 1), b3 + hstep, voffB); PG8_STAGE(PG8_SA(1, 0), a3, voffA);
;             PG8_WAIT_V(8); PG8_WAIT_L(0); PG8_BAR; PG8_MMA(1, 0, At, B0); PG8_MMA(1, 1, At, B1); PG8_BAR; PG8_SCHED;
	s_add_i32 s56, s67, s21
	v_lshl_add_u64 v[184:185], v[184:185], 0, s[12:13]
	s_mov_b32 m0, s56
	ds_read_b128 v[172:175], v191 offset:49152
	ds_read_b128 v[176:179], v191 offset:50176
	ds_read_b128 v[180:183], v191 offset:51200
	ds_read_b128 v[194:197], v191 offset:52224
	ds_read_b128 v[202:205], v191 offset:53248
	ds_read_b128 v[206:209], v191 offset:54272
	ds_read_b128 v[210:213], v191 offset:55296
	ds_read_b128 v[214:217], v191 offset:56320
	global_load_lds_dwordx4 v[184:185], off
	s_add_i32 m0, s56, 0x2000
	s_add_u32 s50, s50, 0x40080
	v_lshl_add_u64 v[184:185], v[198:199], 0, s[12:13]
	s_addc_u32 s51, s51, 0
	s_add_i32 s56, s68, s21
	global_load_lds_dwordx4 v[184:185], off
	v_lshl_add_u64 v[184:185], s[50:51], 0, v[132:133]
	s_mov_b32 m0, s56
	s_nop 0
	global_load_lds_dwordx4 v[184:185], off
	v_lshl_add_u64 v[184:185], s[50:51], 0, v[128:129]
	s_add_i32 m0, s56, 0x2000
	s_nop 0
	global_load_lds_dwordx4 v[184:185], off
	v_lshl_add_u64 v[184:185], v[218:219], 0, s[12:13]
	s_mov_b32 m0, s39
	s_nop 0
	global_load_lds_dwordx4 v[184:185], off
	v_lshl_add_u64 v[184:185], v[220:221], 0, s[12:13]
	s_mov_b32 m0, s58
	s_nop 0
	global_load_lds_dwordx4 v[184:185], off
	s_waitcnt vmcnt(8)
	s_waitcnt lgkmcnt(0)
	s_barrier
	s_setprio 1
	s_waitcnt lgkmcnt(0)
	v_mfma_f32_16x16x32_bf16 v[60:63], v[140:143], v[172:175], v[60:63]
	v_mfma_f32_16x16x32_bf16 v[56:59], v[148:151], v[172:175], v[56:59]
	v_mfma_f32_16x16x32_bf16 v[40:43], v[148:151], v[180:183], v[40:43]
	v_mfma_f32_16x16x32_bf16 v[44:47], v[140:143], v[180:183], v[44:47]
	v_mfma_f32_16x16x32_bf16 v[28:31], v[140:143], v[202:205], v[28:31]
	v_mfma_f32_16x16x32_bf16 v[24:27], v[148:151], v[202:205], v[24:27]
	v_mfma_f32_16x16x32_bf16 v[8:11], v[148:151], v[210:213], v[8:11]
	v_mfma_f32_16x16x32_bf16 v[12:15], v[140:143], v[210:213], v[12:15]
	v_mfma_f32_16x16x32_bf16 v[60:63], v[144:147], v[176:179], v[60:63]
	v_mfma_f32_16x16x32_bf16 v[56:59], v[152:155], v[176:179], v[56:59]
	v_mfma_f32_16x16x32_bf16 v[40:43], v[152:155], v[194:197], v[40:43]
	v_mfma_f32_16x16x32_bf16 v[44:47], v[144:147], v[194:197], v[44:47]
	v_mfma_f32_16x16x32_bf16 v[28:31], v[144:147], v[206:209], v[28:31]
	v_mfma_f32_16x16x32_bf16 v[24:27], v[152:155], v[206:209], v[24:27]
	v_mfma_f32_16x16x32_bf16 v[8:11], v[152:155], v[214:217], v[8:11]
	v_mfma_f32_16x16x32_bf16 v[12:15], v[144:147], v[214:217], v[12:15]
	s_setprio 0
	s_setprio 1
	v_mfma_f32_16x16x32_bf16 v[52:55], v[156:159], v[172:175], v[52:55]
	v_mfma_f32_16x16x32_bf16 v[48:51], v[164:167], v[172:175], v[48:51]
	v_mfma_f32_16x16x32_bf16 v[32:35], v[164:167], v[180:183], v[32:35]
	v_mfma_f32_16x16x32_bf16 v[36:39], v[156:159], v[180:183], v[36:39]
	v_mfma_f32_16x16x32_bf16 v[20:23], v[156:159], v[202:205], v[20:23]
	v_mfma_f32_16x16x32_bf16 v[16:19], v[164:167], v[202:205], v[16:19]
	v_mfma_f32_16x16x32_bf16 v[0:3], v[164:167], v[210:213], v[0:3]
	v_mfma_f32_16x16x32_bf16 v[4:7], v[156:159], v[210:213], v[4:7]
	v_mfma_f32_16x16x32_bf16 v[52:55], v[160:163], v[176:179], v[52:55]
	v_mfma_f32_16x16x32_bf16 v[48:51], v[168:171], v[176:179], v[48:51]
	v_mfma_f32_16x16x32_bf16 v[32:35], v[168:171], v[194:197], v[32:35]
	v_mfma_f32_16x16x32_bf16 v[36:39], v[160:163], v[194:197], v[36:39]
	v_mfma_f32_16x16x32_bf16 v[20:23], v[160:163], v[206:209], v[20:23]
	v_mfma_f32_16x16x32_bf16 v[16:19], v[168:171], v[206:209], v[16:19]
	v_mfma_f32_16x16x32_bf16 v[0:3], v[168:171], v[214:217], v[0:3]
	v_mfma_f32_16x16x32_bf16 v[4:7], v[160:163], v[214:217], v[4:7]
	s_setprio 0
	s_barrier
	s_add_i32 s66, s66, 2
	s_add_u32 s48, s48, 0x100
	s_addc_u32 s49, s49, 0
	s_add_u32 s64, s64, 0x100
	s_addc_u32 s65, s65, 0
	s_cmp_gt_u32 s66, 13
	s_cbranch_scc0 .LBB0_1293
	s_and_b64 vcc, exec, s[14:15]
	s_cbranch_vccz .LBB0_1296
	s_barrier

; #define PG8_STAGE(bufoff, gbase, voff) do { _Pragma("unroll") for (int _i = 0; _i < 2; ++_i) \
;         __builtin_amdgcn_global_load_lds((const unsigned*)((const char*)(gbase) + (voff)[_i]), (PG8_LAS unsigned*)(lds + (bufoff) + ldsw + _i * 8192), 16, 0, 0); } while (0)
; #define PG8_LDA(dst, b, h) do { _Pragma("unroll") for (int m = 0; m < 4; ++m) _Pragma("unroll") for (int k = 0; k < 2; ++k) dst[m][k] = *(const PG8_LAS bf16x8*)(lds + PG8_SA(b, h) + aoff + m * 2048 + k * 1024); } while (0)
; #define PG8_LDB(dst, b, h) do { _Pragma("unroll") for (int n = 0; n < 2; ++n) _Pragma("unroll") for (int k = 0; k < 2; ++k) dst[n][k] = *(const PG8_LAS bf16x8*)(lds + PG8_SB(b, h) + boff + n * 2048 + k * 1024); } while (0)
; #define PG8_MMA(ai, bj, At, Bt) do { __builtin_amdgcn_s_setprio(1); _Pragma("unroll") for (int m = 0; m < 4; ++m) _Pragma("unroll") for (int n = 0; n < 2; ++n) _Pragma("unroll") for (int k = 0; k < 2; ++k) \
;         acc[ai][bj][m][n] = __builtin_amdgcn_mfma_f32_16x16x32_bf16(Bt[n][k], At[m][k], acc[ai][bj][m][n], 0, 0, 0); __builtin_amdgcn_s_setprio(0); } while (0)
; #define PG8_WAIT_V(n) asm volatile("s_waitcnt vmcnt(" #n ")" ::: "memory")
; #define PG8_WAIT_L(n) asm volatile("s_waitcnt lgkmcnt(" #n ")" ::: "memory")
; #define PG8_BAR __builtin_amdgcn_s_barrier()
; #define PG8_SCHED __builtin_amdgcn_sched_barrier(0)
; template <class Epi, class Sched, bool ALIGN_EPI = false, bool SP2 = false>
; __device__ __forceinline__ void gemm_phase(PG8_LAS unsigned char* lds, const Gemm g, const Sched& S, const Epi& E) {
;     ...
;             PG8_LDB(B0, 0, 0); PG8_LDB(B1, 0, 1); PG8_SCHED; PG8_LDA(At, 0, 0); PG8_STAGE(PG8_SA(1, 1), a1 + hstep, voffA);
;             PG8_WAIT_V(8); PG8_WAIT_L(0); PG8_BAR; PG8_MMA(0, 0, At, B0); PG8_MMA(0, 1, At, B1); PG8_BAR; PG8_SCHED;
;             PG8_LDA(At, 0, 1); PG8_STAGE(PG8_SB(0, 0), b2, voffB); PG8_STAGE(PG8_SB(0, 1), b2 + hstep, voffB); PG8_STAGE(PG8_SA(0, 0), a2, voffA);
.LBB0_1363:
	ds_read_b128 v[128:131], v156
	ds_read_b128 v[132:135], v156 offset:1024
	ds_read_b128 v[148:151], v156 offset:2048
	ds_read_b128 v[162:165], v156 offset:3072
	ds_read_b128 v[166:169], v157
	ds_read_b128 v[170:173], v157 offset:1024
	ds_read_b128 v[174:177], v157 offset:2048
	ds_read_b128 v[178:181], v157 offset:3072
	s_add_u32 s42, s26, 0xfff50080
	s_addc_u32 s43, s27, -1
	s_cmp_eq_u32 s72, 40
	s_cselect_b32 s45, s17, s43
	s_cselect_b32 s44, s16, s42
	s_cselect_b32 s43, s19, s71
	s_cselect_b32 s42, s18, s70
	s_mov_b32 m0, s58
	v_lshl_add_u64 v[152:153], s[26:27], 0, v[144:145]
	ds_read_b128 v[182:185], v158
	ds_read_b128 v[186:189], v158 offset:1024
	ds_read_b128 v[190:193], v158 offset:2048
	ds_read_b128 v[194:197], v158 offset:3072
	ds_read_b128 v[202:205], v158 offset:4096
	ds_read_b128 v[206:209], v158 offset:5120
	ds_read_b128 v[210:213], v158 offset:6144
	ds_read_b128 v[214:217], v158 offset:7168
	global_load_lds_dwordx4 v[152:153], off
	v_lshl_add_u64 v[152:153], s[26:27], 0, v[146:147]
	s_mov_b32 m0, s59
	s_nop 0
	global_load_lds_dwordx4 v[152:153], off
	s_waitcnt vmcnt(8)
	s_waitcnt lgkmcnt(0)
	s_barrier
	s_setprio 1
	s_waitcnt lgkmcnt(0)
	v_mfma_f32_16x16x32_bf16 v[124:127], v[128:131], v[182:185], v[124:127]
	v_mfma_f32_16x16x32_bf16 v[120:123], v[148:151], v[182:185], v[120:123]
	v_mfma_f32_16x16x32_bf16 v[104:107], v[148:151], v[190:193], v[104:107]
	v_mfma_f32_16x16x32_bf16 v[108:111], v[128:131], v[190:193], v[108:111]
	v_mfma_f32_16x16x32_bf16 v[92:95], v[128:131], v[202:205], v[92:95]
	v_mfma_f32_16x16x32_bf16 v[88:91], v[148:151], v[202:205], v[88:91]
	v_mfma_f32_16x16x32_bf16 v[72:75], v[148:151], v[210:213], v[72:75]
	v_mfma_f32_16x16x32_bf16 v[76:79], v[128:131], v[210:213], v[76:79]
	v_mfma_f32_16x16x32_bf16 v[124:127], v[132:135], v[186:189], v[124:127]
	v_mfma_f32_16x16x32_bf16 v[120:123], v[162:165], v[186:189], v[120:123]
	v_mfma_f32_16x16x32_bf16 v[104:107], v[162:165], v[194:197], v[104:107]
	v_mfma_f32_16x16x32_bf16 v[108:111], v[132:135], v[194:197], v[108:111]
	v_mfma_f32_16x16x32_bf16 v[92:95], v[132:135], v[206:209], v[92:95]
	v_mfma_f32_16x16x32_bf16 v[88:91], v[162:165], v[206:209], v[88:91]
	v_mfma_f32_16x16x32_bf16 v[72:75], v[162:165], v[214:217], v[72:75]
	v_mfma_f32_16x16x32_bf16 v[76:79], v[132:135], v[214:217], v[76:79]
	s_setprio 0
	s_setprio 1
	v_mfma_f32_16x16x32_bf16 v[116:119], v[166:169], v[182:185], v[116:119]
	v_mfma_f32_16x16x32_bf16 v[112:115], v[174:177], v[182:185], v[112:115]
	v_mfma_f32_16x16x32_bf16 v[96:99], v[174:177], v[190:193], v[96:99]
	v_mfma_f32_16x16x32_bf16 v[100:103], v[166:169], v[190:193], v[100:103]
	v_mfma_f32_16x16x32_bf16 v[84:87], v[166:169], v[202:205], v[84:87]
	v_mfma_f32_16x16x32_bf16 v[80:83], v[174:177], v[202:205], v[80:83]
	v_mfma_f32_16x16x32_bf16 v[64:67], v[174:177], v[210:213], v[64:67]
	v_mfma_f32_16x16x32_bf16 v[68:71], v[166:169], v[210:213], v[68:71]
	v_mfma_f32_16x16x32_bf16 v[116:119], v[170:173], v[186:189], v[116:119]
	v_mfma_f32_16x16x32_bf16 v[112:115], v[178:181], v[186:189], v[112:115]
	v_mfma_f32_16x16x32_bf16 v[96:99], v[178:181], v[194:197], v[96:99]
	v_mfma_f32_16x16x32_bf16 v[100:103], v[170:173], v[194:197], v[100:103]
	v_mfma_f32_16x16x32_bf16 v[84:87], v[170:173], v[206:209], v[84:87]
	v_mfma_f32_16x16x32_bf16 v[80:83], v[178:181], v[206:209], v[80:83]
	v_mfma_f32_16x16x32_bf16 v[64:67], v[178:181], v[214:217], v[64:67]
	v_mfma_f32_16x16x32_bf16 v[68:71], v[170:173], v[214:217], v[68:71]
	s_setprio 0
	s_barrier
	s_mov_b32 m0, s60
	v_lshl_add_u64 v[152:153], s[42:43], 0, v[138:139]
	s_add_u32 s74, s42, 0xb0000
	ds_read_b128 v[182:185], v158 offset:16384
	ds_read_b128 v[186:189], v158 offset:17408
	ds_read_b128 v[190:193], v158 offset:18432
	ds_read_b128 v[194:197], v158 offset:19456
	ds_read_b128 v[202:205], v158 offset:20480
	ds_read_b128 v[206:209], v158 offset:21504
	ds_read_b128 v[210:213], v158 offset:22528
	ds_read_b128 v[214:217], v158 offset:23552
	global_load_lds_dwordx4 v[152:153], off
	v_lshl_add_u64 v[198:199], s[42:43], 0, v[142:143]
	s_mov_b32 m0, s61
	s_addc_u32 s75, s43, 0
	global_load_lds_dwordx4 v[198:199], off
	v_lshl_add_u64 v[218:219], s[74:75], 0, v[138:139]
	s_mov_b32 m0, s62
	v_lshl_add_u64 v[220:221], s[44:45], 0, v[140:141]
	global_load_lds_dwordx4 v[218:219], off
	v_lshl_add_u64 v[218:219], s[74:75], 0, v[142:143]
	s_mov_b32 m0, s63
	s_nop 0
	global_load_lds_dwordx4 v[218:219], off
	v_lshl_add_u64 v[218:219], s[44:45], 0, v[136:137]
	s_mov_b32 m0, s29
	s_nop 0
	global_load_lds_dwordx4 v[218:219], off
	s_mov_b32 m0, s30
	s_nop 0
	global_load_lds_dwordx4 v[220:221], off
	s_waitcnt vmcnt(8)
	s_waitcnt lgkmcnt(0)
	s_barrier
; #define PG8_STAGE(bufoff, gbase, voff) do { _Pragma("unroll") for (int _i = 0; _i < 2; ++_i) \
;         __builtin_amdgcn_global_load_lds((const unsigned*)((const char*)(gbase) + (voff)[_i]), (PG8_LAS unsigned*)(lds + (bufoff) + ldsw + _i * 8192), 16, 0, 0); } while (0)
; #define PG8_LDA(dst, b, h) do { _Pragma("unroll") for (int m = 0; m < 4; ++m) _Pragma("unroll") for (int k = 0; k < 2; ++k) dst[m][k] = *(const PG8_LAS bf16x8*)(lds + PG8_SA(b, h) + aoff + m * 2048 + k * 1024); } while (0)
; #define PG8_LDB(dst, b, h) do { _Pragma("unroll") for (int n = 0; n < 2; ++n) _Pragma("unroll") for (int k = 0; k < 2; ++k) dst[n][k] = *(const PG8_LAS bf16x8*)(lds + PG8_SB(b, h) + boff + n * 2048 + k * 1024); } while (0)
; #define PG8_MMA(ai, bj, At, Bt) do { __builtin_amdgcn_s_setprio(1); _Pragma("unroll") for (int m = 0; m < 4; ++m) _Pragma("unroll") for (int n = 0; n < 2; ++n) _Pragma("unroll") for (int k = 0; k < 2; ++k) \
;         acc[ai][bj][m][n] = __builtin_amdgcn_mfma_f32_16x16x32_bf16(Bt[n][k], At[m][k], acc[ai][bj][m][n], 0, 0, 0); __builtin_amdgcn_s_setprio(0); } while (0)
; #define PG8_WAIT_V(n) asm volatile("s_waitcnt vmcnt(" #n ")" ::: "memory")
; template <class Epi, class Sched, bool ALIGN_EPI = false, bool SP2 = false>
; __device__ __forceinline__ void gemm_phase(PG8_LAS unsigned char* lds, const Gemm g, const Sched& S, const Epi& E) {
;     ...
;             PG8_LDB(B0, 0, 0); PG8_LDB(B1, 0, 1); PG8_SCHED; PG8_LDA(At, 0, 0); PG8_STAGE(PG8_SA(1, 1), a1 + hstep, voffA);
;             PG8_WAIT_V(8); PG8_WAIT_L(0); PG8_BAR; PG8_MMA(0, 0, At, B0); PG8_MMA(0, 1, At, B1); PG8_BAR; PG8_SCHED;
;             PG8_LDA(At, 0, 1); PG8_STAGE(PG8_SB(0, 0), b2, voffB); PG8_STAGE(PG8_SB(0, 1), b2 + hstep, voffB); PG8_STAGE(PG8_SA(0, 0), a2, voffA);
;             PG8_WAIT_V(8); PG8_WAIT_L(0); PG8_BAR; PG8_MMA(1, 0, At, B0); PG8_MMA(1, 1, At, B1); PG8_BAR; PG8_SCHED;
;             PG8_LDB(B0, 1, 0); PG8_LDB(B1, 1, 1); PG8_SCHED; PG8_LDA(At, 1, 0); PG8_STAGE(PG8_SA(0, 1), a2 + hstep, voffA);
;             PG8_WAIT_V(8); PG8_WAIT_L(0); PG8_BAR; PG8_MMA(0, 0, At, B0); PG8_MMA(0, 1, At, B1); PG8_BAR; PG8_SCHED;
;             PG8_LDA(At, 1, 1); PG8_STAGE(PG8_SB(1, 0), b3, voffB); PG8_STAGE(PG8_SB(1, 1), b3 + hstep, voffB); PG8_STAGE(PG8_SA(1, 0), a3, voffA);
;             PG8_WAIT_V(8); PG8_WAIT_L(0); PG8_BAR; PG8_MMA(1, 0, At, B0); PG8_MMA(1, 1, At, B1); PG8_BAR; PG8_SCHED;
	s_setprio 1
	s_waitcnt lgkmcnt(0)
	v_mfma_f32_16x16x32_bf16 v[60:63], v[128:131], v[182:185], v[60:63]
	v_mfma_f32_16x16x32_bf16 v[56:59], v[148:151], v[182:185], v[56:59]
	v_mfma_f32_16x16x32_bf16 v[40:43], v[148:151], v[190:193], v[40:43]
	v_mfma_f32_16x16x32_bf16 v[44:47], v[128:131], v[190:193], v[44:47]
	v_mfma_f32_16x16x32_bf16 v[32:35], v[128:131], v[202:205], v[32:35]
	v_mfma_f32_16x16x32_bf16 v[24:27], v[148:151], v[202:205], v[24:27]
	v_mfma_f32_16x16x32_bf16 v[8:11], v[148:151], v[210:213], v[8:11]
	v_mfma_f32_16x16x32_bf16 v[16:19], v[128:131], v[210:213], v[16:19]
	v_mfma_f32_16x16x32_bf16 v[60:63], v[132:135], v[186:189], v[60:63]
	v_mfma_f32_16x16x32_bf16 v[56:59], v[162:165], v[186:189], v[56:59]
	v_mfma_f32_16x16x32_bf16 v[40:43], v[162:165], v[194:197], v[40:43]
	v_mfma_f32_16x16x32_bf16 v[44:47], v[132:135], v[194:197], v[44:47]
	v_mfma_f32_16x16x32_bf16 v[32:35], v[132:135], v[206:209], v[32:35]
	v_mfma_f32_16x16x32_bf16 v[24:27], v[162:165], v[206:209], v[24:27]
	v_mfma_f32_16x16x32_bf16 v[8:11], v[162:165], v[214:217], v[8:11]
	v_mfma_f32_16x16x32_bf16 v[16:19], v[132:135], v[214:217], v[16:19]
	s_setprio 0
	s_setprio 1
	v_mfma_f32_16x16x32_bf16 v[52:55], v[166:169], v[182:185], v[52:55]
	v_mfma_f32_16x16x32_bf16 v[48:51], v[174:177], v[182:185], v[48:51]
	v_mfma_f32_16x16x32_bf16 v[28:31], v[174:177], v[190:193], v[28:31]
	v_mfma_f32_16x16x32_bf16 v[36:39], v[166:169], v[190:193], v[36:39]
	v_mfma_f32_16x16x32_bf16 v[20:23], v[166:169], v[202:205], v[20:23]
	v_mfma_f32_16x16x32_bf16 v[12:15], v[174:177], v[202:205], v[12:15]
	v_mfma_f32_16x16x32_bf16 v[0:3], v[174:177], v[210:213], v[0:3]
	v_mfma_f32_16x16x32_bf16 v[4:7], v[166:169], v[210:213], v[4:7]
	v_mfma_f32_16x16x32_bf16 v[52:55], v[170:173], v[186:189], v[52:55]
	v_mfma_f32_16x16x32_bf16 v[48:51], v[178:181], v[186:189], v[48:51]
	v_mfma_f32_16x16x32_bf16 v[28:31], v[178:181], v[194:197], v[28:31]
	v_mfma_f32_16x16x32_bf16 v[36:39], v[170:173], v[194:197], v[36:39]
	v_mfma_f32_16x16x32_bf16 v[20:23], v[170:173], v[206:209], v[20:23]
	v_mfma_f32_16x16x32_bf16 v[12:15], v[178:181], v[206:209], v[12:15]
	v_mfma_f32_16x16x32_bf16 v[0:3], v[178:181], v[214:217], v[0:3]
	v_mfma_f32_16x16x32_bf16 v[4:7], v[170:173], v[214:217], v[4:7]
	s_setprio 0
	s_barrier
	ds_read_b128 v[128:131], v160
	ds_read_b128 v[132:135], v160 offset:1024
	ds_read_b128 v[148:151], v160 offset:2048
	ds_read_b128 v[162:165], v160 offset:3072
	ds_read_b128 v[166:169], v161
	ds_read_b128 v[170:173], v161 offset:1024
	ds_read_b128 v[174:177], v161 offset:2048
	ds_read_b128 v[178:181], v161 offset:3072
	s_add_u32 s44, s44, 0xb0000
	s_addc_u32 s45, s45, 0
	s_mov_b32 m0, s31
	v_lshl_add_u64 v[222:223], s[44:45], 0, v[136:137]
	ds_read_b128 v[182:185], v158 offset:32768
	ds_read_b128 v[186:189], v158 offset:33792
	ds_read_b128 v[190:193], v158 offset:34816
	ds_read_b128 v[194:197], v158 offset:35840
	ds_read_b128 v[202:205], v158 offset:36864
	ds_read_b128 v[206:209], v158 offset:37888
	ds_read_b128 v[210:213], v158 offset:38912
	ds_read_b128 v[214:217], v158 offset:39936
	global_load_lds_dwordx4 v[222:223], off
	v_lshl_add_u64 v[222:223], s[44:45], 0, v[140:141]
	s_mov_b32 m0, s37
	s_nop 0
	global_load_lds_dwordx4 v[222:223], off
	s_waitcnt vmcnt(8)
	s_waitcnt lgkmcnt(0)
	s_barrier
	s_setprio 1
	s_waitcnt lgkmcnt(0)
	v_mfma_f32_16x16x32_bf16 v[124:127], v[128:131], v[182:185], v[124:127]
	v_mfma_f32_16x16x32_bf16 v[120:123], v[148:151], v[182:185], v[120:123]
	v_mfma_f32_16x16x32_bf16 v[104:107], v[148:151], v[190:193], v[104:107]
	v_mfma_f32_16x16x32_bf16 v[108:111], v[128:131], v[190:193], v[108:111]
	v_mfma_f32_16x16x32_bf16 v[92:95], v[128:131], v[202:205], v[92:95]
	v_mfma_f32_16x16x32_bf16 v[88:91], v[148:151], v[202:205], v[88:91]
	v_mfma_f32_16x16x32_bf16 v[72:75], v[148:151], v[210:213], v[72:75]
	v_mfma_f32_16x16x32_bf16 v[76:79], v[128:131], v[210:213], v[76:79]
	v_mfma_f32_16x16x32_bf16 v[124:127], v[132:135], v[186:189], v[124:127]
	v_mfma_f32_16x16x32_bf16 v[120:123], v[162:165], v[186:189], v[120:123]
	v_mfma_f32_16x16x32_bf16 v[104:107], v[162:165], v[194:197], v[104:107]
	v_mfma_f32_16x16x32_bf16 v[108:111], v[132:135], v[194:197], v[108:111]
	v_mfma_f32_16x16x32_bf16 v[92:95], v[132:135], v[206:209], v[92:95]
	v_mfma_f32_16x16x32_bf16 v[88:91], v[162:165], v[206:209], v[88:91]
	v_mfma_f32_16x16x32_bf16 v[72:75], v[162:165], v[214:217], v[72:75]
	v_mfma_f32_16x16x32_bf16 v[76:79], v[132:135], v[214:217], v[76:79]
	s_setprio 0
	s_setprio 1
	v_mfma_f32_16x16x32_bf16 v[116:119], v[166:169], v[182:185], v[116:119]
	v_mfma_f32_16x16x32_bf16 v[112:115], v[174:177], v[182:185], v[112:115]
	v_mfma_f32_16x16x32_bf16 v[96:99], v[174:177], v[190:193], v[96:99]
	v_mfma_f32_16x16x32_bf16 v[100:103], v[166:169], v[190:193], v[100:103]
	v_mfma_f32_16x16x32_bf16 v[84:87], v[166:169], v[202:205], v[84:87]
	v_mfma_f32_16x16x32_bf16 v[80:83], v[174:177], v[202:205], v[80:83]
	v_mfma_f32_16x16x32_bf16 v[64:67], v[174:177], v[210:213], v[64:67]
	v_mfma_f32_16x16x32_bf16 v[68:71], v[166:169], v[210:213], v[68:71]
	v_mfma_f32_16x16x32_bf16 v[116:119], v[170:173], v[186:189], v[116:119]
	v_mfma_f32_16x16x32_bf16 v[112:115], v[178:181], v[186:189], v[112:115]
	v_mfma_f32_16x16x32_bf16 v[96:99], v[178:181], v[194:197], v[96:99]
	v_mfma_f32_16x16x32_bf16 v[100:103], v[170:173], v[194:197], v[100:103]
	v_mfma_f32_16x16x32_bf16 v[84:87], v[170:173], v[206:209], v[84:87]
	v_mfma_f32_16x16x32_bf16 v[80:83], v[178:181], v[206:209], v[80:83]
	v_mfma_f32_16x16x32_bf16 v[64:67], v[178:181], v[214:217], v[64:67]
	v_mfma_f32_16x16x32_bf16 v[68:71], v[170:173], v[214:217], v[68:71]
	s_setprio 0
	s_barrier
; #define PG8_STAGE(bufoff, gbase, voff) do { _Pragma("unroll") for (int _i = 0; _i < 2; ++_i) \
;         __builtin_amdgcn_global_load_lds((const unsigned*)((const char*)(gbase) + (voff)[_i]), (PG8_LAS unsigned*)(lds + (bufoff) + ldsw + _i * 8192), 16, 0, 0); } while (0)
; #define PG8_LDA(dst, b, h) do { _Pragma("unroll") for (int m = 0; m < 4; ++m) _Pragma("unroll") for (int k = 0; k < 2; ++k) dst[m][k] = *(const PG8_LAS bf16x8*)(lds + PG8_SA(b, h) + aoff + m * 2048 + k * 1024); } while (0)
; #define PG8_MMA(ai, bj, At, Bt) do { __builtin_amdgcn_s_setprio(1); _Pragma("unroll") for (int m = 0; m < 4; ++m) _Pragma("unroll") for (int n = 0; n < 2; ++n) _Pragma("unroll") for (int k = 0; k < 2; ++k) \
;         acc[ai][bj][m][n] = __builtin_amdgcn_mfma_f32_16x16x32_bf16(Bt[n][k], At[m][k], acc[ai][bj][m][n], 0, 0, 0); __builtin_amdgcn_s_setprio(0); } while (0)
; #define PG8_WAIT_V(n) asm volatile("s_waitcnt vmcnt(" #n ")" ::: "memory")
; #define PG8_WAIT_L(n) asm volatile("s_waitcnt lgkmcnt(" #n ")" ::: "memory")
; #define PG8_BAR __builtin_amdgcn_s_barrier()
; #define PG8_SCHED __builtin_amdgcn_sched_barrier(0)
; template <class Epi, class Sched, bool ALIGN_EPI = false, bool SP2 = false>
; __device__ __forceinline__ void gemm_phase(PG8_LAS unsigned char* lds, const Gemm g, const Sched& S, const Epi& E) {
;     ...
;         for (int t = 0; t < nt; t += 2) {
;             const bool last = (t == nt - 2);
;             const char* a1 = cA + (size_t)(t + 1) * kstep;
;             const char* a2 = last ? nA : cA + (size_t)(t + 2) * kstep; const char* b2 = last ? nB : cB + (size_t)(t + 2) * kstep;
;     ...
;             PG8_LDA(At, 1, 1); PG8_STAGE(PG8_SB(1, 0), b3, voffB); PG8_STAGE(PG8_SB(1, 1), b3 + hstep, voffB); PG8_STAGE(PG8_SA(1, 0), a3, voffA);
;             PG8_WAIT_V(8); PG8_WAIT_L(0); PG8_BAR; PG8_MMA(1, 0, At, B0); PG8_MMA(1, 1, At, B1); PG8_BAR; PG8_SCHED;
	s_add_i32 s44, s64, s28
	v_lshl_add_u64 v[152:153], v[152:153], 0, s[12:13]
	s_mov_b32 m0, s44
	ds_read_b128 v[182:185], v158 offset:49152
	ds_read_b128 v[186:189], v158 offset:50176
	ds_read_b128 v[190:193], v158 offset:51200
	ds_read_b128 v[194:197], v158 offset:52224
	ds_read_b128 v[202:205], v158 offset:53248
	ds_read_b128 v[206:209], v158 offset:54272
	ds_read_b128 v[210:213], v158 offset:55296
	ds_read_b128 v[214:217], v158 offset:56320
	global_load_lds_dwordx4 v[152:153], off
	s_add_i32 m0, s44, 0x2000
	s_add_u32 s42, s42, 0xb0080
	v_lshl_add_u64 v[152:153], v[198:199], 0, s[12:13]
	s_addc_u32 s43, s43, 0
	s_add_i32 s44, s65, s28
	global_load_lds_dwordx4 v[152:153], off
	v_lshl_add_u64 v[152:153], s[42:43], 0, v[138:139]
	s_mov_b32 m0, s44
	s_nop 0
	global_load_lds_dwordx4 v[152:153], off
	v_lshl_add_u64 v[152:153], s[42:43], 0, v[142:143]
	s_add_i32 m0, s44, 0x2000
	s_nop 0
	global_load_lds_dwordx4 v[152:153], off
	v_lshl_add_u64 v[152:153], v[218:219], 0, s[12:13]
	s_mov_b32 m0, s47
	s_nop 0
	global_load_lds_dwordx4 v[152:153], off
	v_lshl_add_u64 v[152:153], v[220:221], 0, s[12:13]
	s_mov_b32 m0, s48
	s_nop 0
	global_load_lds_dwordx4 v[152:153], off
	s_waitcnt vmcnt(8)
	s_waitcnt lgkmcnt(0)
	s_barrier
	s_setprio 1
	s_waitcnt lgkmcnt(0)
	v_mfma_f32_16x16x32_bf16 v[60:63], v[128:131], v[182:185], v[60:63]
	v_mfma_f32_16x16x32_bf16 v[56:59], v[148:151], v[182:185], v[56:59]
	v_mfma_f32_16x16x32_bf16 v[40:43], v[148:151], v[190:193], v[40:43]
	v_mfma_f32_16x16x32_bf16 v[44:47], v[128:131], v[190:193], v[44:47]
	v_mfma_f32_16x16x32_bf16 v[32:35], v[128:131], v[202:205], v[32:35]
	v_mfma_f32_16x16x32_bf16 v[24:27], v[148:151], v[202:205], v[24:27]
	v_mfma_f32_16x16x32_bf16 v[8:11], v[148:151], v[210:213], v[8:11]
	v_mfma_f32_16x16x32_bf16 v[16:19], v[128:131], v[210:213], v[16:19]
	v_mfma_f32_16x16x32_bf16 v[60:63], v[132:135], v[186:189], v[60:63]
	v_mfma_f32_16x16x32_bf16 v[56:59], v[162:165], v[186:189], v[56:59]
	v_mfma_f32_16x16x32_bf16 v[40:43], v[162:165], v[194:197], v[40:43]
	v_mfma_f32_16x16x32_bf16 v[44:47], v[132:135], v[194:197], v[44:47]
	v_mfma_f32_16x16x32_bf16 v[32:35], v[132:135], v[206:209], v[32:35]
	v_mfma_f32_16x16x32_bf16 v[24:27], v[162:165], v[206:209], v[24:27]
	v_mfma_f32_16x16x32_bf16 v[8:11], v[162:165], v[214:217], v[8:11]
	v_mfma_f32_16x16x32_bf16 v[16:19], v[132:135], v[214:217], v[16:19]
	s_setprio 0
	s_setprio 1
	v_mfma_f32_16x16x32_bf16 v[52:55], v[166:169], v[182:185], v[52:55]
	v_mfma_f32_16x16x32_bf16 v[48:51], v[174:177], v[182:185], v[48:51]
	v_mfma_f32_16x16x32_bf16 v[28:31], v[174:177], v[190:193], v[28:31]
	v_mfma_f32_16x16x32_bf16 v[36:39], v[166:169], v[190:193], v[36:39]
	v_mfma_f32_16x16x32_bf16 v[20:23], v[166:169], v[202:205], v[20:23]
	v_mfma_f32_16x16x32_bf16 v[12:15], v[174:177], v[202:205], v[12:15]
	v_mfma_f32_16x16x32_bf16 v[0:3], v[174:177], v[210:213], v[0:3]
	v_mfma_f32_16x16x32_bf16 v[4:7], v[166:169], v[210:213], v[4:7]
	v_mfma_f32_16x16x32_bf16 v[52:55], v[170:173], v[186:189], v[52:55]
	v_mfma_f32_16x16x32_bf16 v[48:51], v[178:181], v[186:189], v[48:51]
	v_mfma_f32_16x16x32_bf16 v[28:31], v[178:181], v[194:197], v[28:31]
	v_mfma_f32_16x16x32_bf16 v[36:39], v[170:173], v[194:197], v[36:39]
	v_mfma_f32_16x16x32_bf16 v[20:23], v[170:173], v[206:209], v[20:23]
	v_mfma_f32_16x16x32_bf16 v[12:15], v[178:181], v[206:209], v[12:15]
	v_mfma_f32_16x16x32_bf16 v[0:3], v[178:181], v[214:217], v[0:3]
	v_mfma_f32_16x16x32_bf16 v[4:7], v[170:173], v[214:217], v[4:7]
	s_setprio 0
	s_barrier
	s_add_i32 s72, s72, 2
	s_add_u32 s26, s26, 0x100
	s_addc_u32 s27, s27, 0
	s_add_u32 s70, s70, 0x100
	s_addc_u32 s71, s71, 0
	s_cmp_gt_u32 s72, 41
	s_cbranch_scc0 .LBB0_1363
	s_and_b64 vcc, exec, s[14:15]
	s_cbranch_vccz .LBB0_1366
	s_barrier
